# regenerated stack with issue slots preserved for removed waits/loads + rg nb-loop m-block loads hoisted to iteration start
# speedup vs baseline: 1.0019x; 1.0019x over previous
.LBB0_62:
	v_and_b32_e32 v131, 64, v202
	v_xor_b32_e32 v130, 16, v202
	v_add_u32_e32 v131, 64, v131
	v_cmp_lt_i32_e32 vcc, v130, v131
	s_lshl_b32 s3, s6, 8
	s_add_i32 s3, s3, s29
	v_cndmask_b32_e32 v130, v202, v130, vcc
	v_lshlrev_b32_e32 v184, 2, v130
	v_xor_b32_e32 v130, 32, v202
	s_lshl_b32 s2, s36, 5
	v_or_b32_e32 v176, s3, v147
	s_lshl_b32 s3, s8, 8
	v_cmp_lt_i32_e32 vcc, v130, v131
	s_or_b32 s2, s3, s2
	v_ashrrev_i32_e32 v177, 31, v176
	v_cndmask_b32_e32 v130, v202, v130, vcc
	v_lshl_or_b32 v128, v139, 2, s2
	v_lshlrev_b32_e32 v144, 2, v130
	v_lshlrev_b64 v[130:131], 12, v[176:177]
	v_ashrrev_i32_e32 v129, 31, v128
	v_lshl_add_u64 v[130:131], s[66:67], 0, v[130:131]
	v_lshl_add_u64 v[178:179], v[128:129], 2, v[130:131]
	s_barrier
	s_nop 0
	v_mov_b32_e32 v238, v178
	v_mov_b32_e32 v239, v179
	global_load_dwordx4 v[226:229], v[238:239], off
	global_load_dwordx4 v[230:233], v[238:239], off offset:64
	global_load_dwordx4 v[234:237], v[238:239], off offset:512
	global_load_dwordx4 v[242:245], v[238:239], off offset:576
	s_mov_b64 s[100:101], 0x10000
	v_lshl_add_u64 v[238:239], v[238:239], 0, s[100:101]
	global_load_dwordx4 v[246:249], v[238:239], off
	s_lshl_b32 s2, s36, 3
	s_add_i32 s2, s2, 0
	v_cmp_eq_u32_e32 vcc, 0, v139
	v_lshl_add_u32 v185, v138, 5, s2
	s_nop 0
	s_waitcnt vmcnt(4)
	v_pk_fma_f32 v[182:183], v[228:229], s[52:53], v[126:127] op_sel_hi:[1,0,1]
	v_pk_fma_f32 v[180:181], v[226:227], s[52:53], v[124:125] op_sel_hi:[1,0,1]
	global_load_dwordx4 v[226:229], v[238:239], off offset:64
	s_nop 0
	v_add_f32_e32 v130, v180, v181
	v_add_f32_e32 v132, v182, v183
	v_mul_f32_e32 v141, v180, v180
	v_mul_f32_e32 v153, v181, v181
	v_mul_f32_e32 v165, v182, v182
	v_mul_f32_e32 v167, v183, v183
	s_nop 0
	s_waitcnt vmcnt(4)
	v_pk_fma_f32 v[174:175], v[232:233], s[52:53], v[122:123] op_sel_hi:[1,0,1]
	v_pk_fma_f32 v[172:173], v[230:231], s[52:53], v[120:121] op_sel_hi:[1,0,1]
	global_load_dwordx4 v[230:233], v[238:239], off offset:512
	v_mul_f32_e32 v120, v174, v174
	v_pk_fma_f32 v[124:125], v[174:175], v[174:175], v[120:121] op_sel_hi:[1,1,0]
	s_nop 0
	v_mul_f32_e32 v131, v172, v172
	v_mul_f32_e32 v133, v173, v173
	v_mov_b32_e32 v140, v172
	v_mov_b32_e32 v152, v173
	v_mov_b32_e32 v164, v174
	v_mov_b32_e32 v166, v175
	v_pk_add_f32 v[140:141], v[140:141], v[152:153]
	v_pk_add_f32 v[152:153], v[164:165], v[166:167]
	v_pk_add_f32 v[130:131], v[130:131], v[132:133]
	v_mov_b32_e32 v124, v145
	v_pk_add_f32 v[140:141], v[140:141], v[152:153]
	v_pk_add_f32 v[124:125], v[130:131], v[124:125]
	s_nop 0
	s_waitcnt vmcnt(4)
	v_pk_fma_f32 v[162:163], v[236:237], s[52:53], v[118:119] op_sel_hi:[1,0,1]
	v_pk_fma_f32 v[142:143], v[234:235], s[52:53], v[116:117] op_sel_hi:[1,0,1]
	global_load_dwordx4 v[234:237], v[238:239], off offset:576
	s_nop 0
	v_mul_f32_e32 v121, v142, v142
	v_mul_f32_e32 v123, v143, v143
	v_mul_f32_e32 v127, v162, v162
	v_mul_f32_e32 v169, v163, v163
	v_mov_b32_e32 v120, v142
	v_mov_b32_e32 v122, v143
	v_mov_b32_e32 v126, v162
	v_mov_b32_e32 v168, v163
	v_pk_add_f32 v[120:121], v[120:121], v[122:123]
	v_pk_add_f32 v[122:123], v[126:127], v[168:169]
	v_pk_add_f32 v[124:125], v[140:141], v[124:125]
	v_pk_add_f32 v[120:121], v[120:121], v[122:123]
	s_nop 0
	s_waitcnt vmcnt(4)
	v_pk_fma_f32 v[136:137], v[244:245], s[52:53], v[114:115] op_sel_hi:[1,0,1]
	v_pk_fma_f32 v[134:135], v[242:243], s[52:53], v[112:113] op_sel_hi:[1,0,1]
	s_mov_b64 s[100:101], 0x10000
	v_lshl_add_u64 v[238:239], v[238:239], 0, s[100:101]
	global_load_dwordx4 v[242:245], v[238:239], off
	v_mul_f32_e32 v117, v136, v136
	v_mul_f32_e32 v113, v134, v134
	v_mul_f32_e32 v115, v135, v135
	v_mul_f32_e32 v119, v137, v137
	v_mov_b32_e32 v112, v134
	v_mov_b32_e32 v114, v135
	v_mov_b32_e32 v116, v136
	v_mov_b32_e32 v118, v137
	v_pk_add_f32 v[112:113], v[112:113], v[114:115]
	v_pk_add_f32 v[114:115], v[116:117], v[118:119]
	v_pk_add_f32 v[120:121], v[124:125], v[120:121]
	v_pk_add_f32 v[112:113], v[112:113], v[114:115]
	s_nop 0
	v_pk_add_f32 v[112:113], v[120:121], v[112:113]
	ds_bpermute_b32 v114, v184, v112
	ds_bpermute_b32 v115, v184, v113
	s_waitcnt lgkmcnt(0)
	v_pk_add_f32 v[112:113], v[112:113], v[114:115]
	ds_bpermute_b32 v114, v144, v112
	ds_bpermute_b32 v115, v144, v113
	s_and_saveexec_b64 s[2:3], vcc
	v_readlane_b32 s16, v253, 6
	s_mov_b64 s[40:41], s[60:61]
	s_mov_b64 s[18:19], s[0:1]
	s_cbranch_execz .LBB0_64
	s_waitcnt lgkmcnt(0)
	v_pk_add_f32 v[112:113], v[112:113], v[114:115]
	ds_write_b64 v185, v[112:113]
.LBB0_64:
	s_or_b64 exec, exec, s[2:3]
	v_or_b32_e32 v170, 16, v176
	v_ashrrev_i32_e32 v171, 31, v170
	v_lshlrev_b64 v[112:113], 12, v[170:171]
	v_lshl_add_u64 v[112:113], s[66:67], 0, v[112:113]
	v_lshl_add_u64 v[164:165], v[128:129], 2, v[112:113]
	s_waitcnt lgkmcnt(0)
	s_nop 0
	s_nop 0
	s_waitcnt vmcnt(4)
	v_pk_fma_f32 v[168:169], v[248:249], s[52:53], v[110:111] op_sel_hi:[1,0,1]
	v_pk_fma_f32 v[166:167], v[246:247], s[52:53], v[108:109] op_sel_hi:[1,0,1]
	global_load_dwordx4 v[246:249], v[238:239], off offset:64
	s_nop 0
	v_add_f32_e32 v116, v166, v167
	v_add_f32_e32 v118, v168, v169
	v_mul_f32_e32 v125, v166, v166
	v_mul_f32_e32 v127, v167, v167
	v_mul_f32_e32 v131, v168, v168
	v_mul_f32_e32 v133, v169, v169
	s_nop 0
	s_waitcnt vmcnt(4)
	v_pk_fma_f32 v[140:141], v[228:229], s[52:53], v[106:107] op_sel_hi:[1,0,1]
	v_pk_fma_f32 v[138:139], v[226:227], s[52:53], v[104:105] op_sel_hi:[1,0,1]
	global_load_dwordx4 v[226:229], v[238:239], off offset:512
	v_mul_f32_e32 v104, v140, v140
	v_pk_fma_f32 v[108:109], v[140:141], v[140:141], v[104:105] op_sel_hi:[1,1,0]
	s_nop 0
	v_mul_f32_e32 v117, v138, v138
	v_mul_f32_e32 v119, v139, v139
	v_mov_b32_e32 v124, v138
	v_mov_b32_e32 v126, v139
	v_mov_b32_e32 v130, v140
	v_mov_b32_e32 v132, v141
	v_pk_add_f32 v[124:125], v[124:125], v[126:127]
	v_pk_add_f32 v[126:127], v[130:131], v[132:133]
	v_pk_add_f32 v[116:117], v[116:117], v[118:119]
	v_mov_b32_e32 v108, v145
	v_pk_add_f32 v[124:125], v[124:125], v[126:127]
	v_pk_add_f32 v[108:109], v[116:117], v[108:109]
	s_nop 0
	s_waitcnt vmcnt(4)
	v_pk_fma_f32 v[122:123], v[232:233], s[52:53], v[102:103] op_sel_hi:[1,0,1]
	v_pk_fma_f32 v[120:121], v[230:231], s[52:53], v[100:101] op_sel_hi:[1,0,1]
	global_load_dwordx4 v[230:233], v[238:239], off offset:576
	s_nop 0
	v_mul_f32_e32 v105, v120, v120
	v_mul_f32_e32 v107, v121, v121
	v_mul_f32_e32 v111, v122, v122
	v_mul_f32_e32 v153, v123, v123
	v_mov_b32_e32 v104, v120
	v_mov_b32_e32 v106, v121
	v_mov_b32_e32 v110, v122
	v_mov_b32_e32 v152, v123
	v_pk_add_f32 v[104:105], v[104:105], v[106:107]
	v_pk_add_f32 v[106:107], v[110:111], v[152:153]
	v_pk_add_f32 v[108:109], v[124:125], v[108:109]
	v_pk_add_f32 v[104:105], v[104:105], v[106:107]
	s_nop 0
	s_waitcnt vmcnt(4)
	v_pk_fma_f32 v[114:115], v[236:237], s[52:53], v[98:99] op_sel_hi:[1,0,1]
	v_pk_fma_f32 v[112:113], v[234:235], s[52:53], v[96:97] op_sel_hi:[1,0,1]
	s_mov_b64 s[100:101], 0x10000
	v_lshl_add_u64 v[238:239], v[238:239], 0, s[100:101]
	global_load_dwordx4 v[234:237], v[238:239], off
	v_mul_f32_e32 v101, v114, v114
	v_mul_f32_e32 v97, v112, v112
	v_mul_f32_e32 v99, v113, v113
	v_mul_f32_e32 v103, v115, v115
	v_mov_b32_e32 v96, v112
	v_mov_b32_e32 v98, v113
	v_mov_b32_e32 v100, v114
	v_mov_b32_e32 v102, v115
	v_pk_add_f32 v[96:97], v[96:97], v[98:99]
	v_pk_add_f32 v[98:99], v[100:101], v[102:103]
	v_pk_add_f32 v[104:105], v[108:109], v[104:105]
	v_pk_add_f32 v[96:97], v[96:97], v[98:99]
	s_nop 0
	v_pk_add_f32 v[96:97], v[104:105], v[96:97]
	ds_bpermute_b32 v98, v184, v96
	ds_bpermute_b32 v99, v184, v97
	s_waitcnt lgkmcnt(0)
	v_pk_add_f32 v[96:97], v[96:97], v[98:99]
	ds_bpermute_b32 v98, v144, v96
	ds_bpermute_b32 v99, v144, v97
	s_and_saveexec_b64 s[2:3], vcc
	v_readlane_b32 s60, v252, 44
	v_readlane_b32 s61, v252, 45
	s_cbranch_execz .LBB0_66
	s_waitcnt lgkmcnt(0)
	v_pk_add_f32 v[96:97], v[96:97], v[98:99]
	ds_write_b64 v185, v[96:97] offset:512
.LBB0_66:
	s_or_b64 exec, exec, s[2:3]
	v_or_b32_e32 v132, 32, v176
	v_ashrrev_i32_e32 v133, 31, v132
	v_lshlrev_b64 v[96:97], 12, v[132:133]
	v_lshl_add_u64 v[96:97], s[66:67], 0, v[96:97]
	v_lshl_add_u64 v[124:125], v[128:129], 2, v[96:97]
	s_waitcnt lgkmcnt(0)
	s_nop 0
	s_nop 0
	s_waitcnt vmcnt(4)
	v_pk_fma_f32 v[130:131], v[244:245], s[52:53], v[94:95] op_sel_hi:[1,0,1]
	v_pk_fma_f32 v[126:127], v[242:243], s[52:53], v[92:93] op_sel_hi:[1,0,1]
	global_load_dwordx4 v[242:245], v[238:239], off offset:64
	s_nop 0
	v_add_f32_e32 v96, v126, v127
	v_add_f32_e32 v98, v130, v131
	v_mul_f32_e32 v105, v126, v126
	v_mul_f32_e32 v107, v127, v127
	v_mul_f32_e32 v109, v130, v130
	v_mul_f32_e32 v111, v131, v131
	s_nop 0
	s_waitcnt vmcnt(4)
	v_pk_fma_f32 v[118:119], v[248:249], s[52:53], v[90:91] op_sel_hi:[1,0,1]
	v_pk_fma_f32 v[116:117], v[246:247], s[52:53], v[88:89] op_sel_hi:[1,0,1]
	global_load_dwordx4 v[246:249], v[238:239], off offset:512
	v_mul_f32_e32 v88, v118, v118
	v_pk_fma_f32 v[152:153], v[118:119], v[118:119], v[88:89] op_sel_hi:[1,1,0]
	s_nop 0
	v_mul_f32_e32 v97, v116, v116
	v_mul_f32_e32 v99, v117, v117
	v_mov_b32_e32 v104, v116
	v_mov_b32_e32 v106, v117
	v_mov_b32_e32 v108, v118
	v_mov_b32_e32 v110, v119
	v_pk_add_f32 v[104:105], v[104:105], v[106:107]
	v_pk_add_f32 v[106:107], v[108:109], v[110:111]
	v_pk_add_f32 v[96:97], v[96:97], v[98:99]
	v_mov_b32_e32 v152, v145
	v_pk_add_f32 v[104:105], v[104:105], v[106:107]
	v_pk_add_f32 v[96:97], v[96:97], v[152:153]
	s_nop 0
	s_waitcnt vmcnt(4)
	v_pk_fma_f32 v[102:103], v[228:229], s[52:53], v[86:87] op_sel_hi:[1,0,1]
	v_pk_fma_f32 v[100:101], v[226:227], s[52:53], v[84:85] op_sel_hi:[1,0,1]
	global_load_dwordx4 v[226:229], v[238:239], off offset:576
	s_nop 0
	v_mul_f32_e32 v89, v100, v100
	v_mul_f32_e32 v91, v101, v101
	v_mul_f32_e32 v187, v102, v102
	v_mul_f32_e32 v189, v103, v103
	v_mov_b32_e32 v88, v100
	v_mov_b32_e32 v90, v101
	v_mov_b32_e32 v186, v102
	v_mov_b32_e32 v188, v103
	v_pk_add_f32 v[88:89], v[88:89], v[90:91]
	v_pk_add_f32 v[90:91], v[186:187], v[188:189]
	v_pk_add_f32 v[96:97], v[104:105], v[96:97]
	v_pk_add_f32 v[88:89], v[88:89], v[90:91]
	s_nop 0
	s_waitcnt vmcnt(4)
	v_pk_fma_f32 v[94:95], v[232:233], s[52:53], v[82:83] op_sel_hi:[1,0,1]
	v_pk_fma_f32 v[92:93], v[230:231], s[52:53], v[80:81] op_sel_hi:[1,0,1]
	s_mov_b64 s[100:101], 0x50000
	v_lshl_add_u64 v[238:239], v[238:239], 0, s[100:101]
	global_load_dwordx4 v[230:233], v[238:239], off
	v_mul_f32_e32 v85, v94, v94
	v_mul_f32_e32 v81, v92, v92
	v_mul_f32_e32 v83, v93, v93
	v_mul_f32_e32 v87, v95, v95
	v_mov_b32_e32 v80, v92
	v_mov_b32_e32 v82, v93
	v_mov_b32_e32 v84, v94
	v_mov_b32_e32 v86, v95
	v_pk_add_f32 v[80:81], v[80:81], v[82:83]
	v_pk_add_f32 v[82:83], v[84:85], v[86:87]
	v_pk_add_f32 v[88:89], v[96:97], v[88:89]
	v_pk_add_f32 v[80:81], v[80:81], v[82:83]
	s_nop 0
	v_pk_add_f32 v[80:81], v[88:89], v[80:81]
	ds_bpermute_b32 v82, v184, v80
	ds_bpermute_b32 v83, v184, v81
	s_waitcnt lgkmcnt(0)
	v_pk_add_f32 v[80:81], v[80:81], v[82:83]
	ds_bpermute_b32 v82, v144, v80
	ds_bpermute_b32 v83, v144, v81
	s_and_saveexec_b64 s[2:3], vcc
	s_cbranch_execz .LBB0_68
	s_waitcnt lgkmcnt(0)
	v_pk_add_f32 v[80:81], v[80:81], v[82:83]
	ds_write_b64 v185, v[80:81] offset:1024
.LBB0_68:
	s_or_b64 exec, exec, s[2:3]
	v_or_b32_e32 v110, 48, v176
	v_ashrrev_i32_e32 v111, 31, v110
	v_lshlrev_b64 v[80:81], 12, v[110:111]
	v_lshl_add_u64 v[80:81], s[66:67], 0, v[80:81]
	v_lshl_add_u64 v[104:105], v[128:129], 2, v[80:81]
	s_waitcnt lgkmcnt(0)
	s_nop 0
	s_nop 0
	s_waitcnt vmcnt(4)
	v_pk_fma_f32 v[108:109], v[236:237], s[52:53], v[78:79] op_sel_hi:[1,0,1]
	v_pk_fma_f32 v[106:107], v[234:235], s[52:53], v[76:77] op_sel_hi:[1,0,1]
	global_load_dwordx4 v[234:237], v[238:239], off offset:64
	s_nop 0
	v_add_f32_e32 v84, v106, v107
	v_add_f32_e32 v86, v108, v109
	v_mul_f32_e32 v89, v106, v106
	v_mul_f32_e32 v91, v107, v107
	v_mul_f32_e32 v153, v108, v108
	v_mul_f32_e32 v187, v109, v109
	s_nop 0
	s_waitcnt vmcnt(4)
	v_pk_fma_f32 v[98:99], v[244:245], s[52:53], v[74:75] op_sel_hi:[1,0,1]
	v_pk_fma_f32 v[96:97], v[242:243], s[52:53], v[72:73] op_sel_hi:[1,0,1]
	global_load_dwordx4 v[242:245], v[238:239], off offset:512
	v_mul_f32_e32 v72, v98, v98
	v_pk_fma_f32 v[76:77], v[98:99], v[98:99], v[72:73] op_sel_hi:[1,1,0]
	s_nop 0
	v_mul_f32_e32 v85, v96, v96
	v_mul_f32_e32 v87, v97, v97
	v_mov_b32_e32 v88, v96
	v_mov_b32_e32 v90, v97
	v_mov_b32_e32 v152, v98
	v_mov_b32_e32 v186, v99
	v_pk_add_f32 v[88:89], v[88:89], v[90:91]
	v_pk_add_f32 v[90:91], v[152:153], v[186:187]
	v_pk_add_f32 v[84:85], v[84:85], v[86:87]
	v_mov_b32_e32 v76, v145
	v_pk_add_f32 v[88:89], v[88:89], v[90:91]
	v_pk_add_f32 v[76:77], v[84:85], v[76:77]
	s_nop 0
	s_waitcnt vmcnt(4)
	v_pk_fma_f32 v[82:83], v[248:249], s[52:53], v[70:71] op_sel_hi:[1,0,1]
	v_pk_fma_f32 v[80:81], v[246:247], s[52:53], v[68:69] op_sel_hi:[1,0,1]
	global_load_dwordx4 v[246:249], v[238:239], off offset:576
	s_nop 0
	v_mul_f32_e32 v79, v80, v80
	v_mul_f32_e32 v189, v81, v81
	v_mul_f32_e32 v191, v82, v82
	v_mul_f32_e32 v193, v83, v83
	v_mov_b32_e32 v78, v80
	v_mov_b32_e32 v188, v81
	v_mov_b32_e32 v190, v82
	v_mov_b32_e32 v192, v83
	v_pk_add_f32 v[78:79], v[78:79], v[188:189]
	v_pk_add_f32 v[84:85], v[190:191], v[192:193]
	v_pk_add_f32 v[76:77], v[88:89], v[76:77]
	v_pk_add_f32 v[78:79], v[78:79], v[84:85]
	s_nop 0
	s_waitcnt vmcnt(4)
	v_pk_fma_f32 v[74:75], v[228:229], s[52:53], v[66:67] op_sel_hi:[1,0,1]
	v_pk_fma_f32 v[72:73], v[226:227], s[52:53], v[64:65] op_sel_hi:[1,0,1]
	s_mov_b64 s[100:101], 0x10000
	v_lshl_add_u64 v[238:239], v[238:239], 0, s[100:101]
	global_load_dwordx4 v[226:229], v[238:239], off
	v_mul_f32_e32 v69, v74, v74
	v_mul_f32_e32 v65, v72, v72
	v_mul_f32_e32 v67, v73, v73
	v_mul_f32_e32 v71, v75, v75
	v_mov_b32_e32 v64, v72
	v_mov_b32_e32 v66, v73
	v_mov_b32_e32 v68, v74
	v_mov_b32_e32 v70, v75
	v_pk_add_f32 v[64:65], v[64:65], v[66:67]
	v_pk_add_f32 v[66:67], v[68:69], v[70:71]
	v_pk_add_f32 v[76:77], v[76:77], v[78:79]
	v_pk_add_f32 v[64:65], v[64:65], v[66:67]
	s_nop 0
	v_pk_add_f32 v[64:65], v[76:77], v[64:65]
	ds_bpermute_b32 v66, v184, v64
	ds_bpermute_b32 v67, v184, v65
	s_waitcnt lgkmcnt(0)
	v_pk_add_f32 v[64:65], v[64:65], v[66:67]
	ds_bpermute_b32 v66, v144, v64
	ds_bpermute_b32 v67, v144, v65
	s_and_saveexec_b64 s[2:3], vcc
	s_cbranch_execz .LBB0_70
	s_waitcnt lgkmcnt(0)
	v_pk_add_f32 v[64:65], v[64:65], v[66:67]
	ds_write_b64 v185, v[64:65] offset:1536
.LBB0_70:
	s_or_b64 exec, exec, s[2:3]
	v_add_u32_e32 v90, 0x80, v176
	v_ashrrev_i32_e32 v91, 31, v90
	v_lshlrev_b64 v[64:65], 12, v[90:91]
	v_lshl_add_u64 v[64:65], s[66:67], 0, v[64:65]
	v_lshl_add_u64 v[84:85], v[128:129], 2, v[64:65]
	s_waitcnt lgkmcnt(0)
	s_nop 0
	s_nop 0
	s_waitcnt vmcnt(4)
	v_pk_fma_f32 v[88:89], v[232:233], s[52:53], v[62:63] op_sel_hi:[1,0,1]
	v_pk_fma_f32 v[86:87], v[230:231], s[52:53], v[60:61] op_sel_hi:[1,0,1]
	global_load_dwordx4 v[230:233], v[238:239], off offset:64
	s_nop 0
	v_add_f32_e32 v64, v86, v87
	v_add_f32_e32 v66, v88, v89
	v_mul_f32_e32 v69, v86, v86
	v_mul_f32_e32 v71, v87, v87
	v_mul_f32_e32 v153, v88, v88
	v_mul_f32_e32 v187, v89, v89
	s_nop 0
	s_waitcnt vmcnt(4)
	v_pk_fma_f32 v[78:79], v[236:237], s[52:53], v[58:59] op_sel_hi:[1,0,1]
	v_pk_fma_f32 v[76:77], v[234:235], s[52:53], v[56:57] op_sel_hi:[1,0,1]
	global_load_dwordx4 v[234:237], v[238:239], off offset:512
	v_mul_f32_e32 v56, v78, v78
	v_pk_fma_f32 v[188:189], v[78:79], v[78:79], v[56:57] op_sel_hi:[1,1,0]
	s_nop 0
	v_mul_f32_e32 v65, v76, v76
	v_mul_f32_e32 v67, v77, v77
	v_mov_b32_e32 v68, v76
	v_mov_b32_e32 v70, v77
	v_mov_b32_e32 v152, v78
	v_mov_b32_e32 v186, v79
	v_pk_add_f32 v[68:69], v[68:69], v[70:71]
	v_pk_add_f32 v[70:71], v[152:153], v[186:187]
	v_pk_add_f32 v[64:65], v[64:65], v[66:67]
	v_mov_b32_e32 v188, v145
	v_pk_add_f32 v[68:69], v[68:69], v[70:71]
	v_pk_add_f32 v[64:65], v[64:65], v[188:189]
	s_nop 0
	s_waitcnt vmcnt(4)
	v_pk_fma_f32 v[62:63], v[244:245], s[52:53], v[54:55] op_sel_hi:[1,0,1]
	v_pk_fma_f32 v[60:61], v[242:243], s[52:53], v[52:53] op_sel_hi:[1,0,1]
	global_load_dwordx4 v[242:245], v[238:239], off offset:576
	s_nop 0
	v_mul_f32_e32 v57, v60, v60
	v_mul_f32_e32 v59, v61, v61
	v_mul_f32_e32 v191, v62, v62
	v_mul_f32_e32 v193, v63, v63
	v_mov_b32_e32 v56, v60
	v_mov_b32_e32 v58, v61
	v_mov_b32_e32 v190, v62
	v_mov_b32_e32 v192, v63
	v_pk_add_f32 v[56:57], v[56:57], v[58:59]
	v_pk_add_f32 v[58:59], v[190:191], v[192:193]
	v_pk_add_f32 v[64:65], v[68:69], v[64:65]
	v_pk_add_f32 v[56:57], v[56:57], v[58:59]
	s_nop 0
	s_waitcnt vmcnt(4)
	v_pk_fma_f32 v[54:55], v[248:249], s[52:53], v[50:51] op_sel_hi:[1,0,1]
	v_pk_fma_f32 v[52:53], v[246:247], s[52:53], v[48:49] op_sel_hi:[1,0,1]
	s_mov_b64 s[100:101], 0x10000
	v_lshl_add_u64 v[238:239], v[238:239], 0, s[100:101]
	global_load_dwordx4 v[246:249], v[238:239], off
	v_mul_f32_e32 v195, v54, v54
	v_mul_f32_e32 v49, v52, v52
	v_mul_f32_e32 v51, v53, v53
	v_mul_f32_e32 v213, v55, v55
	v_mov_b32_e32 v48, v52
	v_mov_b32_e32 v50, v53
	v_mov_b32_e32 v194, v54
	v_mov_b32_e32 v212, v55
	v_pk_add_f32 v[48:49], v[48:49], v[50:51]
	v_pk_add_f32 v[50:51], v[194:195], v[212:213]
	v_pk_add_f32 v[56:57], v[64:65], v[56:57]
	v_pk_add_f32 v[48:49], v[48:49], v[50:51]
	s_nop 0
	v_pk_add_f32 v[48:49], v[56:57], v[48:49]
	ds_bpermute_b32 v50, v184, v48
	ds_bpermute_b32 v51, v184, v49
	s_waitcnt lgkmcnt(0)
	v_pk_add_f32 v[48:49], v[48:49], v[50:51]
	ds_bpermute_b32 v50, v144, v48
	ds_bpermute_b32 v51, v144, v49
	s_and_saveexec_b64 s[2:3], vcc
	s_cbranch_execz .LBB0_72
	s_waitcnt lgkmcnt(0)
	v_pk_add_f32 v[48:49], v[48:49], v[50:51]
	ds_write_b64 v185, v[48:49] offset:4096
.LBB0_72:
	s_or_b64 exec, exec, s[2:3]
	v_add_u32_e32 v70, 0x90, v176
	v_ashrrev_i32_e32 v71, 31, v70
	v_lshlrev_b64 v[48:49], 12, v[70:71]
	v_lshl_add_u64 v[48:49], s[66:67], 0, v[48:49]
	v_lshl_add_u64 v[64:65], v[128:129], 2, v[48:49]
	s_waitcnt lgkmcnt(0)
	s_nop 0
	s_nop 0
	s_waitcnt vmcnt(4)
	v_pk_fma_f32 v[68:69], v[228:229], s[52:53], v[46:47] op_sel_hi:[1,0,1]
	v_pk_fma_f32 v[66:67], v[226:227], s[52:53], v[44:45] op_sel_hi:[1,0,1]
	global_load_dwordx4 v[226:229], v[238:239], off offset:64
	s_nop 0
	v_add_f32_e32 v48, v66, v67
	v_add_f32_e32 v50, v68, v69
	v_mul_f32_e32 v153, v66, v66
	v_mul_f32_e32 v187, v67, v67
	v_mul_f32_e32 v189, v68, v68
	v_mul_f32_e32 v191, v69, v69
	s_nop 0
	s_waitcnt vmcnt(4)
	v_pk_fma_f32 v[58:59], v[232:233], s[52:53], v[42:43] op_sel_hi:[1,0,1]
	v_pk_fma_f32 v[56:57], v[230:231], s[52:53], v[40:41] op_sel_hi:[1,0,1]
	global_load_dwordx4 v[230:233], v[238:239], off offset:512
	v_mul_f32_e32 v40, v58, v58
	v_pk_fma_f32 v[44:45], v[58:59], v[58:59], v[40:41] op_sel_hi:[1,1,0]
	s_nop 0
	v_mul_f32_e32 v49, v56, v56
	v_mul_f32_e32 v51, v57, v57
	v_mov_b32_e32 v152, v56
	v_mov_b32_e32 v186, v57
	v_mov_b32_e32 v188, v58
	v_mov_b32_e32 v190, v59
	v_pk_add_f32 v[152:153], v[152:153], v[186:187]
	v_pk_add_f32 v[186:187], v[188:189], v[190:191]
	v_pk_add_f32 v[48:49], v[48:49], v[50:51]
	v_mov_b32_e32 v44, v145
	v_pk_add_f32 v[152:153], v[152:153], v[186:187]
	v_pk_add_f32 v[44:45], v[48:49], v[44:45]
	s_nop 0
	s_waitcnt vmcnt(4)
	v_pk_fma_f32 v[38:39], v[236:237], s[52:53], v[38:39] op_sel_hi:[1,0,1]
	v_pk_fma_f32 v[36:37], v[234:235], s[52:53], v[36:37] op_sel_hi:[1,0,1]
	global_load_dwordx4 v[234:237], v[238:239], off offset:576
	s_nop 0
	v_mul_f32_e32 v47, v36, v36
	v_mul_f32_e32 v193, v37, v37
	v_mul_f32_e32 v195, v38, v38
	v_mul_f32_e32 v213, v39, v39
	v_mov_b32_e32 v46, v36
	v_mov_b32_e32 v192, v37
	v_mov_b32_e32 v194, v38
	v_mov_b32_e32 v212, v39
	v_pk_add_f32 v[46:47], v[46:47], v[192:193]
	v_pk_add_f32 v[48:49], v[194:195], v[212:213]
	v_pk_add_f32 v[44:45], v[152:153], v[44:45]
	v_pk_add_f32 v[46:47], v[46:47], v[48:49]
	s_nop 0
	s_waitcnt vmcnt(4)
	v_pk_fma_f32 v[34:35], v[244:245], s[52:53], v[34:35] op_sel_hi:[1,0,1]
	v_pk_fma_f32 v[32:33], v[242:243], s[52:53], v[32:33] op_sel_hi:[1,0,1]
	s_mov_b64 s[100:101], 0x10000
	v_lshl_add_u64 v[238:239], v[238:239], 0, s[100:101]
	global_load_dwordx4 v[242:245], v[238:239], off
	v_mul_f32_e32 v215, v34, v34
	v_mul_f32_e32 v41, v32, v32
	v_mul_f32_e32 v43, v33, v33
	v_mul_f32_e32 v217, v35, v35
	v_mov_b32_e32 v40, v32
	v_mov_b32_e32 v42, v33
	v_mov_b32_e32 v214, v34
	v_mov_b32_e32 v216, v35
	v_pk_add_f32 v[40:41], v[40:41], v[42:43]
	v_pk_add_f32 v[42:43], v[214:215], v[216:217]
	v_pk_add_f32 v[44:45], v[44:45], v[46:47]
	v_pk_add_f32 v[40:41], v[40:41], v[42:43]
	s_nop 0
	v_pk_add_f32 v[40:41], v[44:45], v[40:41]
	ds_bpermute_b32 v42, v184, v40
	ds_bpermute_b32 v43, v184, v41
	s_waitcnt lgkmcnt(0)
	v_pk_add_f32 v[40:41], v[40:41], v[42:43]
	ds_bpermute_b32 v42, v144, v40
	ds_bpermute_b32 v43, v144, v41
	s_and_saveexec_b64 s[2:3], vcc
	s_cbranch_execz .LBB0_74
	s_waitcnt lgkmcnt(0)
	v_pk_add_f32 v[40:41], v[40:41], v[42:43]
	ds_write_b64 v185, v[40:41] offset:4608
.LBB0_74:
	s_or_b64 exec, exec, s[2:3]
	v_add_u32_e32 v46, 0xa0, v176
	v_ashrrev_i32_e32 v47, 31, v46
	v_lshlrev_b64 v[40:41], 12, v[46:47]
	v_lshl_add_u64 v[40:41], s[66:67], 0, v[40:41]
	v_lshl_add_u64 v[40:41], v[128:129], 2, v[40:41]
	s_waitcnt lgkmcnt(0)
	s_nop 0
	s_nop 0
	s_waitcnt vmcnt(4)
	v_pk_fma_f32 v[44:45], v[248:249], s[52:53], v[30:31] op_sel_hi:[1,0,1]
	v_pk_fma_f32 v[42:43], v[246:247], s[52:53], v[28:29] op_sel_hi:[1,0,1]
	global_load_dwordx4 v[246:249], v[238:239], off offset:64
	s_nop 0
	v_add_f32_e32 v48, v42, v43
	v_add_f32_e32 v50, v44, v45
	v_mul_f32_e32 v153, v42, v42
	v_mul_f32_e32 v187, v43, v43
	v_mul_f32_e32 v189, v44, v44
	v_mul_f32_e32 v191, v45, v45
	s_nop 0
	s_waitcnt vmcnt(4)
	v_pk_fma_f32 v[30:31], v[228:229], s[52:53], v[26:27] op_sel_hi:[1,0,1]
	v_pk_fma_f32 v[28:29], v[226:227], s[52:53], v[24:25] op_sel_hi:[1,0,1]
	global_load_dwordx4 v[226:229], v[238:239], off offset:512
	v_mul_f32_e32 v24, v30, v30
	v_pk_fma_f32 v[192:193], v[30:31], v[30:31], v[24:25] op_sel_hi:[1,1,0]
	s_nop 0
	v_mul_f32_e32 v49, v28, v28
	v_mul_f32_e32 v51, v29, v29
	v_mov_b32_e32 v152, v28
	v_mov_b32_e32 v186, v29
	v_mov_b32_e32 v188, v30
	v_mov_b32_e32 v190, v31
	v_pk_add_f32 v[152:153], v[152:153], v[186:187]
	v_pk_add_f32 v[186:187], v[188:189], v[190:191]
	v_pk_add_f32 v[48:49], v[48:49], v[50:51]
	v_mov_b32_e32 v192, v145
	v_pk_add_f32 v[152:153], v[152:153], v[186:187]
	v_pk_add_f32 v[48:49], v[48:49], v[192:193]
	s_nop 0
	s_waitcnt vmcnt(4)
	v_pk_fma_f32 v[22:23], v[232:233], s[52:53], v[22:23] op_sel_hi:[1,0,1]
	v_pk_fma_f32 v[20:21], v[230:231], s[52:53], v[20:21] op_sel_hi:[1,0,1]
	global_load_dwordx4 v[230:233], v[238:239], off offset:576
	s_nop 0
	v_mul_f32_e32 v195, v20, v20
	v_mul_f32_e32 v213, v21, v21
	v_mul_f32_e32 v215, v22, v22
	v_mul_f32_e32 v217, v23, v23
	v_mov_b32_e32 v194, v20
	v_mov_b32_e32 v212, v21
	v_mov_b32_e32 v214, v22
	v_mov_b32_e32 v216, v23
	v_pk_add_f32 v[48:49], v[152:153], v[48:49]
	v_pk_add_f32 v[50:51], v[194:195], v[212:213]
	v_pk_add_f32 v[152:153], v[214:215], v[216:217]
	s_nop 0
	s_waitcnt vmcnt(4)
	v_pk_fma_f32 v[18:19], v[236:237], s[52:53], v[18:19] op_sel_hi:[1,0,1]
	v_pk_fma_f32 v[16:17], v[234:235], s[52:53], v[16:17] op_sel_hi:[1,0,1]
	v_mul_f32_e32 v219, v18, v18
	v_mul_f32_e32 v25, v16, v16
	v_mul_f32_e32 v27, v17, v17
	v_mul_f32_e32 v221, v19, v19
	v_mov_b32_e32 v24, v16
	v_mov_b32_e32 v26, v17
	v_mov_b32_e32 v218, v18
	v_mov_b32_e32 v220, v19
	v_pk_add_f32 v[50:51], v[50:51], v[152:153]
	v_pk_add_f32 v[24:25], v[24:25], v[26:27]
	v_pk_add_f32 v[26:27], v[218:219], v[220:221]
	v_pk_add_f32 v[48:49], v[48:49], v[50:51]
	v_pk_add_f32 v[24:25], v[24:25], v[26:27]
	s_nop 0
	v_pk_add_f32 v[24:25], v[48:49], v[24:25]
	ds_bpermute_b32 v26, v184, v24
	ds_bpermute_b32 v27, v184, v25
	s_waitcnt lgkmcnt(0)
	v_pk_add_f32 v[24:25], v[24:25], v[26:27]
	ds_bpermute_b32 v26, v144, v24
	ds_bpermute_b32 v27, v144, v25
	s_and_saveexec_b64 s[2:3], vcc
	s_cbranch_execz .LBB0_76
	s_waitcnt lgkmcnt(0)
	v_pk_add_f32 v[24:25], v[24:25], v[26:27]
	ds_write_b64 v185, v[24:25] offset:5120
.LBB0_76:
	s_or_b64 exec, exec, s[2:3]
	s_waitcnt lgkmcnt(1)
	v_add_u32_e32 v26, 0xb0, v176
	s_waitcnt lgkmcnt(0)
	v_ashrrev_i32_e32 v27, 31, v26
	v_lshlrev_b64 v[24:25], 12, v[26:27]
	v_lshl_add_u64 v[24:25], s[66:67], 0, v[24:25]
	v_lshl_add_u64 v[24:25], v[128:129], 2, v[24:25]
	s_nop 0
	s_nop 0
	s_waitcnt vmcnt(3)
	v_pk_fma_f32 v[14:15], v[244:245], s[52:53], v[14:15] op_sel_hi:[1,0,1]
	v_pk_fma_f32 v[12:13], v[242:243], s[52:53], v[12:13] op_sel_hi:[1,0,1]
	s_nop 0
	v_add_f32_e32 v152, v12, v13
	v_add_f32_e32 v186, v14, v15
	v_mul_f32_e32 v189, v12, v12
	v_mul_f32_e32 v191, v13, v13
	v_mul_f32_e32 v193, v14, v14
	v_mul_f32_e32 v195, v15, v15
	s_nop 0
	s_waitcnt vmcnt(2)
	v_pk_fma_f32 v[10:11], v[248:249], s[52:53], v[10:11] op_sel_hi:[1,0,1]
	v_pk_fma_f32 v[8:9], v[246:247], s[52:53], v[8:9] op_sel_hi:[1,0,1]
	v_mul_f32_e32 v48, v10, v10
	v_pk_fma_f32 v[212:213], v[10:11], v[10:11], v[48:49] op_sel_hi:[1,1,0]
	s_nop 0
	v_mul_f32_e32 v153, v8, v8
	v_mul_f32_e32 v187, v9, v9
	v_mov_b32_e32 v188, v8
	v_mov_b32_e32 v190, v9
	v_mov_b32_e32 v192, v10
	v_mov_b32_e32 v194, v11
	v_pk_add_f32 v[188:189], v[188:189], v[190:191]
	v_pk_add_f32 v[190:191], v[192:193], v[194:195]
	v_pk_add_f32 v[152:153], v[152:153], v[186:187]
	v_mov_b32_e32 v212, v145
	v_pk_add_f32 v[188:189], v[188:189], v[190:191]
	v_pk_add_f32 v[152:153], v[152:153], v[212:213]
	s_nop 0
	s_waitcnt vmcnt(1)
	v_pk_fma_f32 v[6:7], v[228:229], s[52:53], v[6:7] op_sel_hi:[1,0,1]
	v_pk_fma_f32 v[4:5], v[226:227], s[52:53], v[4:5] op_sel_hi:[1,0,1]
	s_nop 0
	v_mul_f32_e32 v215, v4, v4
	v_mul_f32_e32 v217, v5, v5
	v_mul_f32_e32 v219, v6, v6
	v_mul_f32_e32 v221, v7, v7
	v_mov_b32_e32 v214, v4
	v_mov_b32_e32 v216, v5
	v_mov_b32_e32 v218, v6
	v_mov_b32_e32 v220, v7
	v_pk_add_f32 v[152:153], v[188:189], v[152:153]
	v_pk_add_f32 v[186:187], v[214:215], v[216:217]
	v_pk_add_f32 v[188:189], v[218:219], v[220:221]
	s_nop 0
	s_waitcnt vmcnt(0)
	v_pk_fma_f32 v[2:3], v[232:233], s[52:53], v[2:3] op_sel_hi:[1,0,1]
	v_pk_fma_f32 v[0:1], v[230:231], s[52:53], v[0:1] op_sel_hi:[1,0,1]
	v_mul_f32_e32 v223, v2, v2
	v_mul_f32_e32 v49, v0, v0
	v_mul_f32_e32 v51, v1, v1
	v_mul_f32_e32 v225, v3, v3
	v_mov_b32_e32 v48, v0
	v_mov_b32_e32 v50, v1
	v_mov_b32_e32 v222, v2
	v_mov_b32_e32 v224, v3
	v_pk_add_f32 v[186:187], v[186:187], v[188:189]
	v_pk_add_f32 v[48:49], v[48:49], v[50:51]
	v_pk_add_f32 v[50:51], v[222:223], v[224:225]
	v_pk_add_f32 v[152:153], v[152:153], v[186:187]
	v_pk_add_f32 v[48:49], v[48:49], v[50:51]
	s_nop 0
	v_pk_add_f32 v[48:49], v[152:153], v[48:49]
	ds_bpermute_b32 v50, v184, v48
	ds_bpermute_b32 v51, v184, v49
	s_waitcnt lgkmcnt(0)
	v_pk_add_f32 v[48:49], v[48:49], v[50:51]
	ds_bpermute_b32 v50, v144, v48
	ds_bpermute_b32 v51, v144, v49
	s_and_saveexec_b64 s[2:3], vcc
	s_cbranch_execz .LBB0_78
	s_waitcnt lgkmcnt(0)
	v_pk_add_f32 v[48:49], v[48:49], v[50:51]
	ds_write_b64 v185, v[48:49] offset:5632

.LBB0_87:
	s_or_b64 exec, exec, s[4:5]
	s_lshl_b32 s2, s29, 3
	s_add_i32 s2, s2, 0
	v_lshl_add_u32 v144, v147, 3, s2
	v_readlane_b32 s2, v253, 2
	v_lshlrev_b64 v[48:49], 10, v[176:177]
	v_lshlrev_b64 v[50:51], 2, v[128:129]
	v_readlane_b32 s3, v253, 3
	v_lshl_add_u64 v[176:177], v[48:49], 0, v[128:129]
	s_waitcnt lgkmcnt(0)
	v_lshl_add_u64 v[48:49], s[2:3], 0, v[50:51]
	v_readlane_b32 s2, v253, 4
	v_readlane_b32 s3, v253, 5
	s_barrier
	s_nop 0
	v_lshl_add_u64 v[50:51], s[2:3], 0, v[50:51]
	s_nop 0
	s_nop 0
	ds_read_b64 v[184:185], v144 offset:8192
	s_waitcnt lgkmcnt(0)
	v_sub_f32_e32 v153, v183, v184
	v_sub_f32_e32 v152, v182, v184
	v_sub_f32_e32 v181, v181, v184
	v_sub_f32_e32 v180, v180, v184
	v_pk_mul_f32 v[180:181], v[184:185], v[180:181] op_sel:[1,0]
	v_pk_mul_f32 v[152:153], v[184:185], v[152:153] op_sel:[1,0]
	v_sub_f32_e32 v173, v173, v184
	v_sub_f32_e32 v172, v172, v184
	v_pk_mul_f32 v[172:173], v[184:185], v[172:173] op_sel:[1,0]
	v_sub_f32_e32 v163, v163, v184
	v_sub_f32_e32 v162, v162, v184
	v_sub_f32_e32 v143, v143, v184
	v_sub_f32_e32 v142, v142, v184
	v_pk_mul_f32 v[142:143], v[184:185], v[142:143] op_sel:[1,0]
	v_pk_mul_f32 v[162:163], v[184:185], v[162:163] op_sel:[1,0]
	v_sub_f32_e32 v137, v137, v184
	v_sub_f32_e32 v136, v136, v184
	v_sub_f32_e32 v135, v135, v184
	v_sub_f32_e32 v134, v134, v184
	v_pk_mul_f32 v[134:135], v[184:185], v[134:135] op_sel:[1,0]
	v_pk_mul_f32 v[136:137], v[184:185], v[136:137] op_sel:[1,0]
	s_waitcnt vmcnt(0)
	v_pk_fma_f32 v[182:183], v[214:215], v[152:153], v[230:231]
	v_pk_fma_f32 v[180:181], v[212:213], v[180:181], v[228:229]
	global_store_dwordx4 v[178:179], v[180:183], off
	v_lshl_add_u64 v[178:179], v[176:177], 1, s[64:65]
	v_cvt_pk_bf16_f32 v152, v180, v181
	v_cvt_pk_bf16_f32 v153, v182, v183
	global_store_dwordx2 v[178:179], v[152:153], off
	s_nop 0
	s_nop 0
	v_sub_f32_e32 v153, v175, v184
	v_sub_f32_e32 v152, v174, v184
	v_pk_mul_f32 v[152:153], v[184:185], v[152:153] op_sel:[1,0]
	s_nop 0
	v_pk_fma_f32 v[172:173], v[172:173], v[216:217], v[232:233]
	v_pk_fma_f32 v[174:175], v[152:153], v[218:219], v[234:235]
	v_or_b32_e32 v152, 16, v176
	v_mov_b32_e32 v153, v177
	v_lshl_add_u64 v[178:179], v[152:153], 2, s[66:67]
	v_lshl_add_u64 v[152:153], v[152:153], 1, s[64:65]
	global_store_dwordx4 v[178:179], v[172:175], off
	s_nop 1
	s_nop 1
	v_cvt_pk_bf16_f32 v172, v172, v173
	v_cvt_pk_bf16_f32 v173, v174, v175
	global_store_dwordx2 v[152:153], v[172:173], off
	s_nop 0
	s_nop 0
	v_or_b32_e32 v152, 0x80, v176
	v_mov_b32_e32 v153, v177
	v_or_b32_e32 v176, 0x90, v176
	s_nop 0
	v_pk_fma_f32 v[174:175], v[162:163], v[222:223], v[244:245]
	v_pk_fma_f32 v[172:173], v[142:143], v[220:221], v[242:243]
	v_lshl_add_u64 v[142:143], v[152:153], 2, s[66:67]
	v_lshl_add_u64 v[152:153], v[152:153], 1, s[64:65]
	global_store_dwordx4 v[142:143], v[172:175], off
	v_cvt_pk_bf16_f32 v142, v172, v173
	v_cvt_pk_bf16_f32 v143, v174, v175
	global_store_dwordx2 v[152:153], v[142:143], off
	s_nop 0
	s_nop 0
	v_lshl_add_u64 v[142:143], v[176:177], 2, s[66:67]
	s_nop 0
	v_pk_fma_f32 v[136:137], v[136:137], v[226:227], v[248:249]
	v_pk_fma_f32 v[134:135], v[134:135], v[224:225], v[246:247]
	global_store_dwordx4 v[142:143], v[134:137], off
	s_nop 1
	s_nop 1
	v_cvt_pk_bf16_f32 v134, v134, v135
	v_cvt_pk_bf16_f32 v135, v136, v137
	v_lshl_add_u64 v[136:137], v[176:177], 1, s[64:65]
	global_store_dwordx2 v[136:137], v[134:135], off
	ds_read_b64 v[136:137], v144 offset:8320
	v_lshlrev_b64 v[134:135], 10, v[170:171]
	s_nop 0
	s_nop 0
	v_lshl_add_u64 v[134:135], v[134:135], 0, v[128:129]
	s_waitcnt lgkmcnt(0)
	v_sub_f32_e32 v143, v169, v136
	v_sub_f32_e32 v142, v168, v136
	v_sub_f32_e32 v153, v167, v136
	v_sub_f32_e32 v152, v166, v136
	v_pk_mul_f32 v[152:153], v[136:137], v[152:153] op_sel:[1,0]
	v_pk_mul_f32 v[142:143], v[136:137], v[142:143] op_sel:[1,0]
	v_sub_f32_e32 v141, v141, v136
	v_sub_f32_e32 v140, v140, v136
	v_sub_f32_e32 v139, v139, v136
	v_sub_f32_e32 v138, v138, v136
	v_pk_mul_f32 v[138:139], v[136:137], v[138:139] op_sel:[1,0]
	v_pk_mul_f32 v[140:141], v[136:137], v[140:141] op_sel:[1,0]
	v_sub_f32_e32 v123, v123, v136
	v_sub_f32_e32 v122, v122, v136
	v_sub_f32_e32 v121, v121, v136
	v_sub_f32_e32 v120, v120, v136
	v_pk_mul_f32 v[120:121], v[136:137], v[120:121] op_sel:[1,0]
	v_pk_mul_f32 v[122:123], v[136:137], v[122:123] op_sel:[1,0]
	v_sub_f32_e32 v115, v115, v136
	v_sub_f32_e32 v114, v114, v136
	v_sub_f32_e32 v113, v113, v136
	v_sub_f32_e32 v112, v112, v136
	v_pk_mul_f32 v[112:113], v[136:137], v[112:113] op_sel:[1,0]
	v_pk_mul_f32 v[114:115], v[136:137], v[114:115] op_sel:[1,0]
	s_nop 0
	v_pk_fma_f32 v[168:169], v[214:215], v[142:143], v[230:231]
	v_pk_fma_f32 v[166:167], v[212:213], v[152:153], v[228:229]
	v_lshl_add_u64 v[152:153], v[134:135], 1, s[64:65]
	global_store_dwordx4 v[164:165], v[166:169], off
	v_cvt_pk_bf16_f32 v142, v166, v167
	v_cvt_pk_bf16_f32 v143, v168, v169
	global_store_dwordx2 v[152:153], v[142:143], off
	s_nop 0
	s_nop 0
	v_or_b32_e32 v142, 16, v134
	v_mov_b32_e32 v143, v135
	v_lshl_add_u64 v[152:153], v[142:143], 2, s[66:67]
	s_nop 0
	v_pk_fma_f32 v[140:141], v[140:141], v[218:219], v[234:235]
	v_pk_fma_f32 v[138:139], v[138:139], v[216:217], v[232:233]
	global_store_dwordx4 v[152:153], v[138:141], off
	s_nop 1
	s_nop 1
	v_cvt_pk_bf16_f32 v138, v138, v139
	v_cvt_pk_bf16_f32 v139, v140, v141
	v_lshl_add_u64 v[140:141], v[142:143], 1, s[64:65]
	global_store_dwordx2 v[140:141], v[138:139], off
	s_nop 0
	s_nop 0
	v_or_b32_e32 v142, 0x80, v134
	v_or_b32_e32 v134, 0x90, v134
	s_nop 0
	v_pk_fma_f32 v[122:123], v[122:123], v[222:223], v[244:245]
	v_pk_fma_f32 v[120:121], v[120:121], v[220:221], v[242:243]
	v_lshl_add_u64 v[138:139], v[142:143], 2, s[66:67]
	global_store_dwordx4 v[138:139], v[120:123], off
	s_nop 1
	s_nop 1
	v_cvt_pk_bf16_f32 v120, v120, v121
	v_cvt_pk_bf16_f32 v121, v122, v123
	v_lshl_add_u64 v[122:123], v[142:143], 1, s[64:65]
	global_store_dwordx2 v[122:123], v[120:121], off
	s_nop 0
	s_nop 0
	s_nop 0
	v_pk_fma_f32 v[114:115], v[114:115], v[226:227], v[248:249]
	v_pk_fma_f32 v[112:113], v[112:113], v[224:225], v[246:247]
	v_lshl_add_u64 v[120:121], v[134:135], 2, s[66:67]
	global_store_dwordx4 v[120:121], v[112:115], off
	s_nop 1
	s_nop 1
	v_cvt_pk_bf16_f32 v112, v112, v113
	v_cvt_pk_bf16_f32 v113, v114, v115
	v_lshl_add_u64 v[114:115], v[134:135], 1, s[64:65]
	global_store_dwordx2 v[114:115], v[112:113], off
	ds_read_b64 v[114:115], v144 offset:8448
	v_lshlrev_b64 v[112:113], 10, v[132:133]
	s_nop 0
	s_nop 0
	v_lshl_add_u64 v[112:113], v[112:113], 0, v[128:129]
	s_waitcnt lgkmcnt(0)
	v_sub_f32_e32 v131, v131, v114
	v_sub_f32_e32 v130, v130, v114
	v_sub_f32_e32 v127, v127, v114
	v_sub_f32_e32 v126, v126, v114
	v_pk_mul_f32 v[126:127], v[114:115], v[126:127] op_sel:[1,0]
	v_pk_mul_f32 v[130:131], v[114:115], v[130:131] op_sel:[1,0]
	v_sub_f32_e32 v117, v117, v114
	v_sub_f32_e32 v116, v116, v114
	v_sub_f32_e32 v119, v119, v114
	v_sub_f32_e32 v118, v118, v114
	v_pk_mul_f32 v[116:117], v[114:115], v[116:117] op_sel:[1,0]
	v_pk_mul_f32 v[118:119], v[114:115], v[118:119] op_sel:[1,0]
	v_sub_f32_e32 v103, v103, v114
	v_sub_f32_e32 v102, v102, v114
	v_sub_f32_e32 v101, v101, v114
	v_sub_f32_e32 v100, v100, v114
	v_pk_mul_f32 v[100:101], v[114:115], v[100:101] op_sel:[1,0]
	v_pk_mul_f32 v[102:103], v[114:115], v[102:103] op_sel:[1,0]
	v_sub_f32_e32 v95, v95, v114
	v_sub_f32_e32 v94, v94, v114
	v_sub_f32_e32 v93, v93, v114
	v_sub_f32_e32 v92, v92, v114
	v_pk_mul_f32 v[92:93], v[114:115], v[92:93] op_sel:[1,0]
	v_pk_mul_f32 v[94:95], v[114:115], v[94:95] op_sel:[1,0]
	s_nop 0
	v_pk_fma_f32 v[122:123], v[214:215], v[130:131], v[230:231]
	v_pk_fma_f32 v[120:121], v[212:213], v[126:127], v[228:229]
	global_store_dwordx4 v[124:125], v[120:123], off
	s_nop 1
	s_nop 1
	v_cvt_pk_bf16_f32 v120, v120, v121
	v_cvt_pk_bf16_f32 v121, v122, v123
	v_lshl_add_u64 v[122:123], v[112:113], 1, s[64:65]
	global_store_dwordx2 v[122:123], v[120:121], off
	s_nop 0
	s_nop 0
	s_nop 0
	v_pk_fma_f32 v[116:117], v[116:117], v[216:217], v[232:233]
	v_or_b32_e32 v120, 16, v112
	v_mov_b32_e32 v121, v113
	v_pk_fma_f32 v[118:119], v[118:119], v[218:219], v[234:235]
	v_lshl_add_u64 v[122:123], v[120:121], 2, s[66:67]
	global_store_dwordx4 v[122:123], v[116:119], off
	v_or_b32_e32 v124, 0x80, v112
	v_mov_b32_e32 v125, v113
	v_cvt_pk_bf16_f32 v116, v116, v117
	v_cvt_pk_bf16_f32 v117, v118, v119
	v_lshl_add_u64 v[118:119], v[120:121], 1, s[64:65]
	global_store_dwordx2 v[118:119], v[116:117], off
	s_nop 0
	s_nop 0
	v_or_b32_e32 v112, 0x90, v112
	s_nop 0
	v_pk_fma_f32 v[102:103], v[102:103], v[222:223], v[244:245]
	v_pk_fma_f32 v[100:101], v[100:101], v[220:221], v[242:243]
	v_lshl_add_u64 v[116:117], v[124:125], 2, s[66:67]
	global_store_dwordx4 v[116:117], v[100:103], off
	s_nop 1
	s_nop 1
	v_cvt_pk_bf16_f32 v100, v100, v101
	v_cvt_pk_bf16_f32 v101, v102, v103
	v_lshl_add_u64 v[102:103], v[124:125], 1, s[64:65]
	global_store_dwordx2 v[102:103], v[100:101], off
	s_nop 0
	s_nop 0
	s_nop 0
	v_pk_fma_f32 v[94:95], v[94:95], v[226:227], v[248:249]
	v_pk_fma_f32 v[92:93], v[92:93], v[224:225], v[246:247]
	v_lshl_add_u64 v[100:101], v[112:113], 2, s[66:67]
	global_store_dwordx4 v[100:101], v[92:95], off
	s_nop 1
	s_nop 1
	v_cvt_pk_bf16_f32 v92, v92, v93
	v_cvt_pk_bf16_f32 v93, v94, v95
	v_lshl_add_u64 v[94:95], v[112:113], 1, s[64:65]
	global_store_dwordx2 v[94:95], v[92:93], off
	ds_read_b64 v[94:95], v144 offset:8576
	v_lshlrev_b64 v[92:93], 10, v[110:111]
	s_nop 0
	s_nop 0
	v_lshl_add_u64 v[92:93], v[92:93], 0, v[128:129]
	s_waitcnt lgkmcnt(0)
	v_sub_f32_e32 v109, v109, v94
	v_sub_f32_e32 v108, v108, v94
	v_sub_f32_e32 v107, v107, v94
	v_sub_f32_e32 v106, v106, v94
	v_pk_mul_f32 v[106:107], v[94:95], v[106:107] op_sel:[1,0]
	v_pk_mul_f32 v[108:109], v[94:95], v[108:109] op_sel:[1,0]
	v_sub_f32_e32 v97, v97, v94
	v_sub_f32_e32 v96, v96, v94
	v_sub_f32_e32 v99, v99, v94
	v_sub_f32_e32 v98, v98, v94
	v_pk_mul_f32 v[96:97], v[94:95], v[96:97] op_sel:[1,0]
	v_pk_mul_f32 v[98:99], v[94:95], v[98:99] op_sel:[1,0]
	v_sub_f32_e32 v83, v83, v94
	v_sub_f32_e32 v82, v82, v94
	v_sub_f32_e32 v81, v81, v94
	v_sub_f32_e32 v80, v80, v94
	v_pk_mul_f32 v[80:81], v[94:95], v[80:81] op_sel:[1,0]
	v_pk_mul_f32 v[82:83], v[94:95], v[82:83] op_sel:[1,0]
	v_sub_f32_e32 v75, v75, v94
	v_sub_f32_e32 v74, v74, v94
	v_sub_f32_e32 v73, v73, v94
	v_sub_f32_e32 v72, v72, v94
	v_pk_mul_f32 v[72:73], v[94:95], v[72:73] op_sel:[1,0]
	v_pk_mul_f32 v[74:75], v[94:95], v[74:75] op_sel:[1,0]
	s_nop 0
	v_pk_fma_f32 v[102:103], v[214:215], v[108:109], v[230:231]
	v_pk_fma_f32 v[100:101], v[212:213], v[106:107], v[228:229]
	global_store_dwordx4 v[104:105], v[100:103], off
	s_nop 1
	s_nop 1
	v_cvt_pk_bf16_f32 v100, v100, v101
	v_cvt_pk_bf16_f32 v101, v102, v103
	v_lshl_add_u64 v[102:103], v[92:93], 1, s[64:65]
	global_store_dwordx2 v[102:103], v[100:101], off
	s_nop 0
	s_nop 0
	s_nop 0
	v_pk_fma_f32 v[96:97], v[96:97], v[216:217], v[232:233]
	v_or_b32_e32 v100, 16, v92
	v_mov_b32_e32 v101, v93
	v_pk_fma_f32 v[98:99], v[98:99], v[218:219], v[234:235]
	v_lshl_add_u64 v[102:103], v[100:101], 2, s[66:67]
	global_store_dwordx4 v[102:103], v[96:99], off
	v_or_b32_e32 v104, 0x80, v92
	v_mov_b32_e32 v105, v93
	v_cvt_pk_bf16_f32 v96, v96, v97
	v_cvt_pk_bf16_f32 v97, v98, v99
	v_lshl_add_u64 v[98:99], v[100:101], 1, s[64:65]
	global_store_dwordx2 v[98:99], v[96:97], off
	s_nop 0
	s_nop 0
	v_or_b32_e32 v92, 0x90, v92
	s_nop 0
	v_pk_fma_f32 v[82:83], v[82:83], v[222:223], v[244:245]
	v_pk_fma_f32 v[80:81], v[80:81], v[220:221], v[242:243]
	v_lshl_add_u64 v[96:97], v[104:105], 2, s[66:67]
	global_store_dwordx4 v[96:97], v[80:83], off
	s_nop 1
	s_nop 1
	v_cvt_pk_bf16_f32 v80, v80, v81
	v_cvt_pk_bf16_f32 v81, v82, v83
	v_lshl_add_u64 v[82:83], v[104:105], 1, s[64:65]
	global_store_dwordx2 v[82:83], v[80:81], off
	s_nop 0
	s_nop 0
	s_nop 0
	v_pk_fma_f32 v[74:75], v[74:75], v[226:227], v[248:249]
	v_pk_fma_f32 v[72:73], v[72:73], v[224:225], v[246:247]
	v_lshl_add_u64 v[80:81], v[92:93], 2, s[66:67]
	global_store_dwordx4 v[80:81], v[72:75], off
	s_nop 1
	s_nop 1
	v_cvt_pk_bf16_f32 v72, v72, v73
	v_cvt_pk_bf16_f32 v73, v74, v75
	v_lshl_add_u64 v[74:75], v[92:93], 1, s[64:65]
	global_store_dwordx2 v[74:75], v[72:73], off
	ds_read_b64 v[74:75], v144 offset:9216
	v_lshlrev_b64 v[72:73], 10, v[90:91]
	s_nop 0
	s_nop 0
	v_lshl_add_u64 v[72:73], v[72:73], 0, v[128:129]
	s_waitcnt lgkmcnt(0)
	v_sub_f32_e32 v89, v89, v74
	v_sub_f32_e32 v88, v88, v74
	v_sub_f32_e32 v87, v87, v74
	v_sub_f32_e32 v86, v86, v74
	v_pk_mul_f32 v[86:87], v[74:75], v[86:87] op_sel:[1,0]
	v_pk_mul_f32 v[88:89], v[74:75], v[88:89] op_sel:[1,0]
	v_sub_f32_e32 v77, v77, v74
	v_sub_f32_e32 v76, v76, v74
	v_sub_f32_e32 v79, v79, v74
	v_sub_f32_e32 v78, v78, v74
	v_pk_mul_f32 v[76:77], v[74:75], v[76:77] op_sel:[1,0]
	v_pk_mul_f32 v[78:79], v[74:75], v[78:79] op_sel:[1,0]
	v_sub_f32_e32 v63, v63, v74
	v_sub_f32_e32 v62, v62, v74
	v_sub_f32_e32 v61, v61, v74
	v_sub_f32_e32 v60, v60, v74
	v_pk_mul_f32 v[60:61], v[74:75], v[60:61] op_sel:[1,0]
	v_pk_mul_f32 v[62:63], v[74:75], v[62:63] op_sel:[1,0]
	v_sub_f32_e32 v55, v55, v74
	v_sub_f32_e32 v54, v54, v74
	v_sub_f32_e32 v53, v53, v74
	v_sub_f32_e32 v52, v52, v74
	v_pk_mul_f32 v[52:53], v[74:75], v[52:53] op_sel:[1,0]
	v_pk_mul_f32 v[54:55], v[74:75], v[54:55] op_sel:[1,0]
	s_nop 0
	v_pk_fma_f32 v[82:83], v[214:215], v[88:89], v[230:231]
	v_pk_fma_f32 v[80:81], v[212:213], v[86:87], v[228:229]
	global_store_dwordx4 v[84:85], v[80:83], off
	s_nop 1
	s_nop 1
	v_cvt_pk_bf16_f32 v80, v80, v81
	v_cvt_pk_bf16_f32 v81, v82, v83
	v_lshl_add_u64 v[82:83], v[72:73], 1, s[64:65]
	global_store_dwordx2 v[82:83], v[80:81], off
	s_nop 0
	s_nop 0
	s_nop 0
	v_pk_fma_f32 v[76:77], v[76:77], v[216:217], v[232:233]
	v_or_b32_e32 v80, 16, v72
	v_mov_b32_e32 v81, v73
	v_pk_fma_f32 v[78:79], v[78:79], v[218:219], v[234:235]
	v_lshl_add_u64 v[82:83], v[80:81], 2, s[66:67]
	global_store_dwordx4 v[82:83], v[76:79], off
	v_or_b32_e32 v84, 0x80, v72
	v_mov_b32_e32 v85, v73
	v_cvt_pk_bf16_f32 v76, v76, v77
	v_cvt_pk_bf16_f32 v77, v78, v79
	v_lshl_add_u64 v[78:79], v[80:81], 1, s[64:65]
	global_store_dwordx2 v[78:79], v[76:77], off
	s_nop 0
	s_nop 0
	v_or_b32_e32 v72, 0x90, v72
	s_nop 0
	v_pk_fma_f32 v[62:63], v[62:63], v[222:223], v[244:245]
	v_pk_fma_f32 v[60:61], v[60:61], v[220:221], v[242:243]
	v_lshl_add_u64 v[76:77], v[84:85], 2, s[66:67]
	global_store_dwordx4 v[76:77], v[60:63], off
	s_nop 1
	s_nop 1
	v_cvt_pk_bf16_f32 v60, v60, v61
	v_cvt_pk_bf16_f32 v61, v62, v63
	v_lshl_add_u64 v[62:63], v[84:85], 1, s[64:65]
	global_store_dwordx2 v[62:63], v[60:61], off
	s_nop 0
	s_nop 0
	s_nop 0
	v_pk_fma_f32 v[54:55], v[54:55], v[226:227], v[248:249]
	v_pk_fma_f32 v[52:53], v[52:53], v[224:225], v[246:247]
	v_lshl_add_u64 v[60:61], v[72:73], 2, s[66:67]
	global_store_dwordx4 v[60:61], v[52:55], off
	s_nop 1
	s_nop 1
	v_cvt_pk_bf16_f32 v52, v52, v53
	v_cvt_pk_bf16_f32 v53, v54, v55
	v_lshl_add_u64 v[54:55], v[72:73], 1, s[64:65]
	global_store_dwordx2 v[54:55], v[52:53], off
	ds_read_b64 v[54:55], v144 offset:9344
	v_lshlrev_b64 v[52:53], 10, v[70:71]
	s_nop 0
	s_nop 0
	v_lshl_add_u64 v[52:53], v[52:53], 0, v[128:129]
	s_waitcnt lgkmcnt(0)
	v_sub_f32_e32 v69, v69, v54
	v_sub_f32_e32 v68, v68, v54
	v_sub_f32_e32 v67, v67, v54
	v_sub_f32_e32 v66, v66, v54
	v_pk_mul_f32 v[66:67], v[54:55], v[66:67] op_sel:[1,0]
	v_pk_mul_f32 v[68:69], v[54:55], v[68:69] op_sel:[1,0]
	v_sub_f32_e32 v57, v57, v54
	v_sub_f32_e32 v56, v56, v54
	v_sub_f32_e32 v59, v59, v54
	v_sub_f32_e32 v58, v58, v54
	v_pk_mul_f32 v[56:57], v[54:55], v[56:57] op_sel:[1,0]
	v_pk_mul_f32 v[58:59], v[54:55], v[58:59] op_sel:[1,0]
	v_sub_f32_e32 v39, v39, v54
	v_sub_f32_e32 v38, v38, v54
	v_sub_f32_e32 v37, v37, v54
	v_sub_f32_e32 v36, v36, v54
	v_pk_mul_f32 v[36:37], v[54:55], v[36:37] op_sel:[1,0]
	v_pk_mul_f32 v[38:39], v[54:55], v[38:39] op_sel:[1,0]
	v_sub_f32_e32 v35, v35, v54
	v_sub_f32_e32 v34, v34, v54
	v_sub_f32_e32 v33, v33, v54
	v_sub_f32_e32 v32, v32, v54
	v_pk_mul_f32 v[32:33], v[54:55], v[32:33] op_sel:[1,0]
	v_pk_mul_f32 v[34:35], v[54:55], v[34:35] op_sel:[1,0]
	s_nop 0
	v_pk_fma_f32 v[62:63], v[214:215], v[68:69], v[230:231]
	v_pk_fma_f32 v[60:61], v[212:213], v[66:67], v[228:229]
	global_store_dwordx4 v[64:65], v[60:63], off
	s_nop 1
	s_nop 1
	v_cvt_pk_bf16_f32 v60, v60, v61
	v_cvt_pk_bf16_f32 v61, v62, v63
	v_lshl_add_u64 v[62:63], v[52:53], 1, s[64:65]
	global_store_dwordx2 v[62:63], v[60:61], off
	s_nop 0
	s_nop 0
	s_nop 0
	v_pk_fma_f32 v[56:57], v[56:57], v[216:217], v[232:233]
	v_or_b32_e32 v60, 16, v52
	v_mov_b32_e32 v61, v53
	v_pk_fma_f32 v[58:59], v[58:59], v[218:219], v[234:235]
	v_lshl_add_u64 v[62:63], v[60:61], 2, s[66:67]
	global_store_dwordx4 v[62:63], v[56:59], off
	v_or_b32_e32 v64, 0x80, v52
	v_mov_b32_e32 v65, v53
	v_cvt_pk_bf16_f32 v56, v56, v57
	v_cvt_pk_bf16_f32 v57, v58, v59
	v_lshl_add_u64 v[58:59], v[60:61], 1, s[64:65]
	global_store_dwordx2 v[58:59], v[56:57], off
	s_nop 0
	s_nop 0
	v_or_b32_e32 v52, 0x90, v52
	s_nop 0
	v_pk_fma_f32 v[38:39], v[38:39], v[222:223], v[244:245]
	v_pk_fma_f32 v[36:37], v[36:37], v[220:221], v[242:243]
	v_lshl_add_u64 v[56:57], v[64:65], 2, s[66:67]
	global_store_dwordx4 v[56:57], v[36:39], off
	s_nop 1
	s_nop 1
	v_cvt_pk_bf16_f32 v36, v36, v37
	v_cvt_pk_bf16_f32 v37, v38, v39
	v_lshl_add_u64 v[38:39], v[64:65], 1, s[64:65]
	global_store_dwordx2 v[38:39], v[36:37], off
	s_nop 0
	s_nop 0
	s_nop 0
	v_pk_fma_f32 v[34:35], v[34:35], v[226:227], v[248:249]
	v_pk_fma_f32 v[32:33], v[32:33], v[224:225], v[246:247]
	v_lshl_add_u64 v[36:37], v[52:53], 2, s[66:67]
	global_store_dwordx4 v[36:37], v[32:35], off
	s_nop 1
	s_nop 1
	v_cvt_pk_bf16_f32 v32, v32, v33
	v_cvt_pk_bf16_f32 v33, v34, v35
	v_lshl_add_u64 v[34:35], v[52:53], 1, s[64:65]
	global_store_dwordx2 v[34:35], v[32:33], off
	ds_read_b64 v[34:35], v144 offset:9472
	s_nop 0
	s_nop 0
	v_lshlrev_b64 v[32:33], 10, v[46:47]
	v_lshl_add_u64 v[32:33], v[32:33], 0, v[128:129]
	s_waitcnt lgkmcnt(0)
	v_sub_f32_e32 v45, v45, v34
	v_sub_f32_e32 v44, v44, v34
	v_sub_f32_e32 v43, v43, v34
	v_sub_f32_e32 v42, v42, v34
	v_pk_mul_f32 v[42:43], v[34:35], v[42:43] op_sel:[1,0]
	v_pk_mul_f32 v[44:45], v[34:35], v[44:45] op_sel:[1,0]
	v_sub_f32_e32 v29, v29, v34
	v_sub_f32_e32 v28, v28, v34
	v_sub_f32_e32 v31, v31, v34
	v_sub_f32_e32 v30, v30, v34
	v_pk_mul_f32 v[28:29], v[34:35], v[28:29] op_sel:[1,0]
	v_pk_mul_f32 v[30:31], v[34:35], v[30:31] op_sel:[1,0]
	v_sub_f32_e32 v23, v23, v34
	v_sub_f32_e32 v22, v22, v34
	v_sub_f32_e32 v21, v21, v34
	v_sub_f32_e32 v20, v20, v34
	v_pk_mul_f32 v[20:21], v[34:35], v[20:21] op_sel:[1,0]
	v_pk_mul_f32 v[22:23], v[34:35], v[22:23] op_sel:[1,0]
	v_sub_f32_e32 v19, v19, v34
	v_sub_f32_e32 v18, v18, v34
	v_sub_f32_e32 v17, v17, v34
	v_sub_f32_e32 v16, v16, v34
	v_pk_mul_f32 v[16:17], v[34:35], v[16:17] op_sel:[1,0]
	v_pk_mul_f32 v[18:19], v[34:35], v[18:19] op_sel:[1,0]
	s_nop 0
	v_pk_fma_f32 v[38:39], v[214:215], v[44:45], v[230:231]
	v_pk_fma_f32 v[36:37], v[212:213], v[42:43], v[228:229]
	global_store_dwordx4 v[40:41], v[36:39], off
	s_nop 1
	s_nop 1
	v_cvt_pk_bf16_f32 v36, v36, v37
	v_cvt_pk_bf16_f32 v37, v38, v39
	v_lshl_add_u64 v[38:39], v[32:33], 1, s[64:65]
	global_store_dwordx2 v[38:39], v[36:37], off
	s_nop 0
	s_nop 0
	s_nop 0
	v_pk_fma_f32 v[28:29], v[28:29], v[216:217], v[232:233]
	v_or_b32_e32 v36, 16, v32
	v_mov_b32_e32 v37, v33
	v_pk_fma_f32 v[30:31], v[30:31], v[218:219], v[234:235]
	v_lshl_add_u64 v[38:39], v[36:37], 2, s[66:67]
	global_store_dwordx4 v[38:39], v[28:31], off
	v_or_b32_e32 v40, 0x80, v32
	v_mov_b32_e32 v41, v33
	v_cvt_pk_bf16_f32 v28, v28, v29
	v_cvt_pk_bf16_f32 v29, v30, v31
	v_lshl_add_u64 v[30:31], v[36:37], 1, s[64:65]
	global_store_dwordx2 v[30:31], v[28:29], off
	s_nop 0
	s_nop 0
	v_or_b32_e32 v32, 0x90, v32
	s_nop 0
	v_pk_fma_f32 v[22:23], v[22:23], v[222:223], v[244:245]
	v_pk_fma_f32 v[20:21], v[20:21], v[220:221], v[242:243]
	v_lshl_add_u64 v[28:29], v[40:41], 2, s[66:67]
	global_store_dwordx4 v[28:29], v[20:23], off
	s_nop 1
	s_nop 1
	v_cvt_pk_bf16_f32 v20, v20, v21
	v_cvt_pk_bf16_f32 v21, v22, v23
	v_lshl_add_u64 v[22:23], v[40:41], 1, s[64:65]
	global_store_dwordx2 v[22:23], v[20:21], off
	s_nop 0
	s_nop 0
	s_nop 0
	v_pk_fma_f32 v[18:19], v[18:19], v[226:227], v[248:249]
	v_pk_fma_f32 v[16:17], v[16:17], v[224:225], v[246:247]
	v_lshl_add_u64 v[20:21], v[32:33], 2, s[66:67]
	global_store_dwordx4 v[20:21], v[16:19], off
	s_nop 1
	s_nop 1
	v_cvt_pk_bf16_f32 v16, v16, v17
	v_cvt_pk_bf16_f32 v17, v18, v19
	v_lshl_add_u64 v[18:19], v[32:33], 1, s[64:65]
	global_store_dwordx2 v[18:19], v[16:17], off
	ds_read_b64 v[18:19], v144 offset:9600
	v_lshlrev_b64 v[16:17], 10, v[26:27]
	s_nop 0
	s_nop 0
	v_lshl_add_u64 v[16:17], v[16:17], 0, v[128:129]
	s_waitcnt lgkmcnt(0)
	v_sub_f32_e32 v15, v15, v18
	v_sub_f32_e32 v14, v14, v18
	v_sub_f32_e32 v13, v13, v18
	v_sub_f32_e32 v12, v12, v18
	v_pk_mul_f32 v[12:13], v[18:19], v[12:13] op_sel:[1,0]
	v_pk_mul_f32 v[14:15], v[18:19], v[14:15] op_sel:[1,0]
	v_sub_f32_e32 v9, v9, v18
	v_sub_f32_e32 v8, v8, v18
	v_sub_f32_e32 v11, v11, v18
	v_sub_f32_e32 v10, v10, v18
	v_pk_mul_f32 v[8:9], v[18:19], v[8:9] op_sel:[1,0]
	v_pk_mul_f32 v[10:11], v[18:19], v[10:11] op_sel:[1,0]
	v_sub_f32_e32 v7, v7, v18
	v_sub_f32_e32 v6, v6, v18
	v_sub_f32_e32 v5, v5, v18
	v_sub_f32_e32 v4, v4, v18
	v_pk_mul_f32 v[4:5], v[18:19], v[4:5] op_sel:[1,0]
	v_pk_mul_f32 v[6:7], v[18:19], v[6:7] op_sel:[1,0]
	v_sub_f32_e32 v3, v3, v18
	v_sub_f32_e32 v2, v2, v18
	v_sub_f32_e32 v1, v1, v18
	v_sub_f32_e32 v0, v0, v18
	v_pk_mul_f32 v[0:1], v[18:19], v[0:1] op_sel:[1,0]
	v_pk_mul_f32 v[2:3], v[18:19], v[2:3] op_sel:[1,0]
	s_nop 0
	v_pk_fma_f32 v[14:15], v[214:215], v[14:15], v[230:231]
	v_pk_fma_f32 v[12:13], v[212:213], v[12:13], v[228:229]
	global_store_dwordx4 v[24:25], v[12:15], off
	s_nop 1
	s_nop 1
	v_cvt_pk_bf16_f32 v12, v12, v13
	v_cvt_pk_bf16_f32 v13, v14, v15
	v_lshl_add_u64 v[14:15], v[16:17], 1, s[64:65]
	global_store_dwordx2 v[14:15], v[12:13], off
	s_nop 0
	s_nop 0
	s_nop 0
	v_pk_fma_f32 v[8:9], v[8:9], v[216:217], v[232:233]
	v_or_b32_e32 v12, 16, v16
	v_mov_b32_e32 v13, v17
	v_pk_fma_f32 v[10:11], v[10:11], v[218:219], v[234:235]
	v_lshl_add_u64 v[14:15], v[12:13], 2, s[66:67]
	global_store_dwordx4 v[14:15], v[8:11], off
	v_or_b32_e32 v20, 0x80, v16
	v_mov_b32_e32 v21, v17
	v_cvt_pk_bf16_f32 v8, v8, v9
	v_cvt_pk_bf16_f32 v9, v10, v11
	v_lshl_add_u64 v[10:11], v[12:13], 1, s[64:65]
	global_store_dwordx2 v[10:11], v[8:9], off
	s_nop 0
	s_nop 0
	v_or_b32_e32 v16, 0x90, v16
	s_nop 0
	v_pk_fma_f32 v[6:7], v[6:7], v[222:223], v[244:245]
	v_pk_fma_f32 v[4:5], v[4:5], v[220:221], v[242:243]
	v_lshl_add_u64 v[8:9], v[20:21], 2, s[66:67]
	global_store_dwordx4 v[8:9], v[4:7], off
	s_nop 1
	s_nop 1
	v_cvt_pk_bf16_f32 v4, v4, v5
	v_cvt_pk_bf16_f32 v5, v6, v7
	v_lshl_add_u64 v[6:7], v[20:21], 1, s[64:65]
	global_store_dwordx2 v[6:7], v[4:5], off
	s_nop 0
	s_nop 0
	s_nop 0
	v_pk_fma_f32 v[2:3], v[2:3], v[226:227], v[248:249]
	v_pk_fma_f32 v[0:1], v[0:1], v[224:225], v[246:247]
	v_lshl_add_u64 v[4:5], v[16:17], 2, s[66:67]
	global_store_dwordx4 v[4:5], v[0:3], off
	s_nop 1
	s_nop 1
	v_cvt_pk_bf16_f32 v0, v0, v1
	v_cvt_pk_bf16_f32 v1, v2, v3
	v_lshl_add_u64 v[2:3], v[16:17], 1, s[64:65]
	global_store_dwordx2 v[2:3], v[0:1], off

.LBB0_193:
	s_xor_b64 s[70:71], s[54:55], -1
	v_readlane_b32 s54, v254, 18
	s_or_b32 s80, s78, s54
	s_lshl_b32 s54, s80, 6
	s_ashr_i32 s55, s54, 31
	s_lshl_b64 s[78:79], s[54:55], 2
	v_readlane_b32 s82, v253, 13
	v_readlane_b32 s83, v253, 14
	s_add_u32 s84, s82, s78
	s_addc_u32 s85, s83, s79
	v_lshlrev_b32_e32 v144, 2, v88
	s_waitcnt lgkmcnt(0)
	v_lshl_add_u64 v[40:41], s[84:85], 0, v[144:145]
	s_movk_i32 s81, 0x1000
	v_add_co_u32_e32 v36, vcc, s81, v40
	s_mov_b64 s[82:83], 0x1000
	s_nop 0
	v_addc_co_u32_e32 v37, vcc, 0, v41, vcc
	v_add_co_u32_e32 v42, vcc, s33, v40
	v_lshl_add_u64 v[0:1], v[40:41], 0, s[82:83]
	s_nop 0
	v_addc_co_u32_e32 v43, vcc, 0, v41, vcc
	s_mov_b64 s[82:83], 0x2000
	global_load_dwordx4 v[8:11], v144, s[84:85] offset:16
	global_load_dwordx4 v[44:47], v144, s[84:85]
	global_load_dwordx4 v[28:31], v[42:43], off offset:-4096
	global_load_dwordx4 v[20:23], v[0:1], off offset:16
	v_lshl_add_u64 v[0:1], v[40:41], 0, s[82:83]
	s_mov_b64 s[82:83], 0x3000
	v_lshl_add_u64 v[12:13], v[40:41], 0, s[82:83]
	s_lshl_b64 s[82:83], s[54:55], 1
	v_add_co_u32_e32 v48, vcc, s87, v40
	v_lshl_add_u64 v[78:79], v[94:95], 0, s[82:83]
	s_nop 0
	v_addc_co_u32_e32 v49, vcc, 0, v41, vcc
	v_lshl_add_u64 v[50:51], v[96:97], 0, s[78:79]
	v_lshl_add_u64 v[38:39], v[78:79], 0, s[58:59]
	global_load_dwordx4 v[4:7], v[42:43], off
	s_nop 0
	global_load_dwordx4 v[0:3], v[0:1], off offset:16
	s_nop 0
	global_load_dwordx4 v[16:19], v[48:49], off
	s_nop 0
	global_load_dwordx4 v[12:15], v[12:13], off offset:16
	s_nop 0
	global_load_dwordx4 v[24:27], v[50:51], off offset:16
	global_load_dwordx4 v[32:35], v[50:51], off
	s_nop 0
	v_lshl_add_u64 v[38:39], v[78:79], 0, s[60:61]
	v_lshl_add_u64 v[74:75], v[78:79], 0, s[56:57]
	s_mov_b32 s100, 0xffff3a00
	s_mov_b32 s101, -1
	v_lshl_add_u64 v[242:243], v[74:75], 0, s[100:101]
	global_load_dwordx4 v[132:135], v[242:243], off
	s_mov_b32 s100, 0xffff7c00
	s_mov_b32 s101, -1
	v_lshl_add_u64 v[242:243], v[74:75], 0, s[100:101]
	global_load_dwordx4 v[136:139], v[242:243], off
	s_mov_b32 s100, 0xffffbe00
	s_mov_b32 s101, -1
	v_lshl_add_u64 v[242:243], v[74:75], 0, s[100:101]
	global_load_dwordx4 v[140:143], v[242:243], off
	s_mov_b32 s100, 0x0
	s_mov_b32 s101, 0
	v_lshl_add_u64 v[242:243], v[74:75], 0, s[100:101]
	global_load_dwordx4 v[162:165], v[242:243], off
	s_mov_b32 s100, 0x35a00
	s_mov_b32 s101, 0
	v_lshl_add_u64 v[242:243], v[74:75], 0, s[100:101]
	global_load_dwordx4 v[166:169], v[242:243], off
	s_mov_b32 s100, 0x39c00
	s_mov_b32 s101, 0
	v_lshl_add_u64 v[242:243], v[74:75], 0, s[100:101]
	global_load_dwordx4 v[172:175], v[242:243], off
	s_mov_b32 s100, 0x3de00
	s_mov_b32 s101, 0
	v_lshl_add_u64 v[242:243], v[74:75], 0, s[100:101]
	global_load_dwordx4 v[176:179], v[242:243], off
	s_mov_b32 s100, 0x42000
	s_mov_b32 s101, 0
	v_lshl_add_u64 v[242:243], v[74:75], 0, s[100:101]
	global_load_dwordx4 v[180:183], v[242:243], off
	s_mov_b32 s100, 0x77a00
	s_mov_b32 s101, 0
	v_lshl_add_u64 v[242:243], v[74:75], 0, s[100:101]
	global_load_dwordx4 v[184:187], v[242:243], off
	s_mov_b32 s100, 0x7fe00
	s_mov_b32 s101, 0
	v_lshl_add_u64 v[242:243], v[74:75], 0, s[100:101]
	global_load_dwordx4 v[192:195], v[242:243], off
	s_mov_b32 s100, 0x7bc00
	s_mov_b32 s101, 0
	v_lshl_add_u64 v[242:243], v[74:75], 0, s[100:101]
	global_load_dwordx4 v[212:215], v[242:243], off
	s_mov_b32 s100, 0x84000
	s_mov_b32 s101, 0
	v_lshl_add_u64 v[242:243], v[74:75], 0, s[100:101]
	global_load_dwordx4 v[216:219], v[242:243], off
	s_mov_b32 s100, 0xb9a00
	s_mov_b32 s101, 0
	v_lshl_add_u64 v[242:243], v[74:75], 0, s[100:101]
	global_load_dwordx4 v[220:223], v[242:243], off
	s_mov_b32 s100, 0xbdc00
	s_mov_b32 s101, 0
	v_lshl_add_u64 v[242:243], v[74:75], 0, s[100:101]
	global_load_dwordx4 v[224:227], v[242:243], off
	s_mov_b32 s100, 0xc1e00
	s_mov_b32 s101, 0
	v_lshl_add_u64 v[242:243], v[74:75], 0, s[100:101]
	global_load_dwordx4 v[228:231], v[242:243], off
	s_mov_b32 s100, 0xc6000
	s_mov_b32 s101, 0
	v_lshl_add_u64 v[242:243], v[74:75], 0, s[100:101]
	global_load_dwordx4 v[232:235], v[242:243], off
	s_mov_b32 s100, 0xffff3a40
	s_mov_b32 s101, -1
	v_lshl_add_u64 v[242:243], v[74:75], 0, s[100:101]
	global_load_dwordx4 v[236:239], v[242:243], off
	s_mov_b32 s100, 0xffff7c40
	s_mov_b32 s101, -1
	v_lshl_add_u64 v[242:243], v[74:75], 0, s[100:101]
	global_load_dwordx4 v[246:249], v[242:243], off
	s_nop 0
	s_waitcnt vmcnt(23)
	v_mov_b32_e32 v86, v4
	s_nop 0
	s_waitcnt vmcnt(21)
	v_mov_b32_e32 v87, v16
	v_mov_b32_e32 v16, v5
	v_mov_b32_e32 v84, v6
	s_nop 0
	s_waitcnt vmcnt(17)
	v_cndmask_b32_e64 v62, 0, v135, s[2:3]
	v_cndmask_b32_e64 v56, 0, v134, s[2:3]
	v_cndmask_b32_e64 v57, 0, v133, s[2:3]
	v_cndmask_b32_e64 v58, 0, v132, s[2:3]
	s_mov_b32 s100, 0xffffbe40
	s_mov_b32 s101, -1
	v_lshl_add_u64 v[242:243], v[74:75], 0, s[100:101]
	global_load_dwordx4 v[132:135], v[242:243], off
	s_nop 0
	v_mov_b32_e32 v38, v44
	v_mov_b32_e32 v39, v28
	v_mov_b32_e32 v85, v18
	v_mov_b32_e32 v18, v7
	v_mov_b32_e32 v80, v0
	v_mov_b32_e32 v81, v12
	v_mov_b32_e32 v12, v1
	v_mov_b32_e32 v82, v2
	v_mov_b32_e32 v83, v14
	v_mov_b32_e32 v14, v3
	s_nop 0
	s_waitcnt vmcnt(17)
	v_cndmask_b32_e64 v59, 0, v136, s[4:5]
	v_cndmask_b32_e64 v63, 0, v139, s[4:5]
	v_cndmask_b32_e64 v55, 0, v137, s[4:5]
	v_lshlrev_b32_e32 v53, 16, v59
	v_lshlrev_b32_e32 v52, 16, v58
	v_pk_mul_f32 v[52:53], v[38:39], v[52:53]
	v_cndmask_b32_e64 v138, 0, v138, s[4:5]
	v_add_f32_e32 v28, v32, v52
	v_add_f32_e32 v61, v28, v53
	v_and_b32_e32 v53, 0xffff0000, v59
	v_and_b32_e32 v52, 0xffff0000, v58
	v_mov_b32_e32 v28, v45
	v_pk_mul_f32 v[44:45], v[28:29], v[52:53]
	v_lshlrev_b32_e32 v53, 16, v55
	v_add_f32_e32 v44, v33, v44
	v_add_f32_e32 v60, v44, v45
	v_lshlrev_b32_e32 v52, 16, v57
	v_mov_b32_e32 v44, v46
	v_mov_b32_e32 v45, v30
	v_pk_mul_f32 v[52:53], v[44:45], v[52:53]
	s_nop 0
	v_add_f32_e32 v30, v34, v52
	v_add_f32_e32 v59, v30, v53
	v_and_b32_e32 v53, 0xffff0000, v55
	v_and_b32_e32 v52, 0xffff0000, v57
	v_mov_b32_e32 v30, v47
	v_pk_mul_f32 v[46:47], v[30:31], v[52:53]
	v_lshlrev_b32_e32 v53, 16, v138
	v_add_f32_e32 v46, v35, v46
	v_add_f32_e32 v58, v46, v47
	v_lshlrev_b32_e32 v52, 16, v56
	v_mov_b32_e32 v46, v8
	v_mov_b32_e32 v47, v20
	v_pk_mul_f32 v[52:53], v[46:47], v[52:53]
	v_mov_b32_e32 v20, v9
	v_add_f32_e32 v8, v24, v52
	v_add_f32_e32 v55, v8, v53
	v_and_b32_e32 v53, 0xffff0000, v138
	s_mov_b32 s100, 0x40
	s_mov_b32 s101, 0
	v_lshl_add_u64 v[242:243], v[74:75], 0, s[100:101]
	global_load_dwordx4 v[136:139], v[242:243], off
	v_and_b32_e32 v52, 0xffff0000, v56
	v_pk_mul_f32 v[8:9], v[20:21], v[52:53]
	v_mov_b32_e32 v56, v10
	v_add_f32_e32 v8, v25, v8
	v_add_f32_e32 v54, v8, v9
	v_lshlrev_b32_e32 v9, 16, v63
	v_lshlrev_b32_e32 v8, 16, v62
	v_mov_b32_e32 v57, v22
	v_pk_mul_f32 v[8:9], v[56:57], v[8:9]
	v_mov_b32_e32 v22, v11
	v_add_f32_e32 v8, v26, v8
	v_add_f32_e32 v53, v8, v9
	v_and_b32_e32 v9, 0xffff0000, v63
	v_and_b32_e32 v8, 0xffff0000, v62
	v_pk_mul_f32 v[8:9], v[22:23], v[8:9]
	s_nop 0
	v_add_f32_e32 v8, v27, v8
	v_add_f32_e32 v52, v8, v9
	v_lshl_add_u64 v[8:9], v[78:79], 0, s[62:63]
	s_nop 0
	s_nop 0
	s_waitcnt vmcnt(17)
	v_cndmask_b32_e64 v62, 0, v143, s[8:9]
	v_cndmask_b32_e64 v63, 0, v142, s[8:9]
	v_cndmask_b32_e64 v64, 0, v141, s[8:9]
	v_cndmask_b32_e64 v65, 0, v140, s[8:9]
	s_mov_b32 s100, 0x35a40
	s_mov_b32 s101, 0
	v_lshl_add_u64 v[242:243], v[74:75], 0, s[100:101]
	global_load_dwordx4 v[140:143], v[242:243], off
	s_nop 0
	s_nop 0
	s_waitcnt vmcnt(17)
	v_cndmask_b32_e64 v67, 0, v162, s[10:11]
	v_cndmask_b32_e64 v66, 0, v163, s[10:11]
	v_lshlrev_b32_e32 v9, 16, v67
	v_lshlrev_b32_e32 v8, 16, v65
	v_pk_mul_f32 v[8:9], v[86:87], v[8:9]
	v_cndmask_b32_e64 v164, 0, v164, s[10:11]
	v_add_f32_e32 v4, v61, v8
	v_add_f32_e32 v61, v4, v9
	v_and_b32_e32 v9, 0xffff0000, v67
	v_and_b32_e32 v8, 0xffff0000, v65
	v_pk_mul_f32 v[4:5], v[16:17], v[8:9]
	v_cndmask_b32_e64 v165, 0, v165, s[10:11]
	v_add_f32_e32 v4, v60, v4
	v_add_f32_e32 v8, v4, v5
	v_lshlrev_b32_e32 v5, 16, v66
	v_lshlrev_b32_e32 v4, 16, v64
	v_pk_mul_f32 v[4:5], v[84:85], v[4:5]
	s_nop 0
	v_add_f32_e32 v4, v59, v4
	v_add_f32_e32 v6, v4, v5
	v_and_b32_e32 v5, 0xffff0000, v66
	v_and_b32_e32 v4, 0xffff0000, v64
	v_pk_mul_f32 v[4:5], v[18:19], v[4:5]
	s_nop 0
	v_add_f32_e32 v4, v58, v4
	v_add_f32_e32 v7, v4, v5
	v_lshlrev_b32_e32 v5, 16, v164
	v_lshlrev_b32_e32 v4, 16, v63
	v_pk_mul_f32 v[4:5], v[80:81], v[4:5]
	s_nop 0
	v_add_f32_e32 v0, v55, v4
	v_add_f32_e32 v9, v0, v5
	v_and_b32_e32 v5, 0xffff0000, v164
	v_and_b32_e32 v4, 0xffff0000, v63
	v_pk_mul_f32 v[0:1], v[12:13], v[4:5]
	s_nop 0
	v_add_f32_e32 v0, v54, v0
	v_add_f32_e32 v4, v0, v1
	v_lshlrev_b32_e32 v1, 16, v165
	v_lshlrev_b32_e32 v0, 16, v62
	v_pk_mul_f32 v[0:1], v[82:83], v[0:1]
	v_cvt_pk_bf16_f32 v2, v9, v4
	s_nop 0
	v_add_f32_e32 v0, v53, v0
	v_add_f32_e32 v5, v0, v1
	v_and_b32_e32 v1, 0xffff0000, v165
	s_mov_b32 s100, 0x39c40
	s_mov_b32 s101, 0
	v_lshl_add_u64 v[242:243], v[74:75], 0, s[100:101]
	global_load_dwordx4 v[162:165], v[242:243], off
	v_and_b32_e32 v0, 0xffff0000, v62
	v_pk_mul_f32 v[0:1], v[14:15], v[0:1]
	s_nop 0
	v_add_f32_e32 v0, v52, v0
	v_add_f32_e32 v3, v0, v1
	v_cvt_pk_bf16_f32 v0, v61, v8
	v_cvt_pk_bf16_f32 v1, v6, v7
	v_cvt_pk_bf16_f32 v3, v5, v3
	s_mov_b32 s81, 0x35000
	v_add_co_u32_e32 v68, vcc, s81, v74
	s_mov_b32 s81, 0x39000
	s_nop 0
	v_addc_co_u32_e32 v69, vcc, 0, v75, vcc
	s_nop 0
	v_add_co_u32_e32 v70, vcc, s81, v74
	s_mov_b32 s81, 0x3d000
	s_nop 0
	v_addc_co_u32_e32 v71, vcc, 0, v75, vcc
	v_add_co_u32_e32 v72, vcc, s81, v74
	s_mov_b32 s81, 0x42000
	s_nop 0
	v_addc_co_u32_e32 v73, vcc, 0, v75, vcc
	v_add_co_u32_e32 v76, vcc, s81, v74
	s_nop 0
	s_waitcnt vmcnt(17)
	v_cndmask_b32_e64 v10, 0, v169, s[12:13]
	v_cndmask_b32_e64 v11, 0, v168, s[12:13]
	v_cndmask_b32_e64 v8, 0, v167, s[12:13]
	v_cndmask_b32_e64 v9, 0, v166, s[12:13]
	s_mov_b32 s100, 0x3de40
	s_mov_b32 s101, 0
	v_lshl_add_u64 v[242:243], v[74:75], 0, s[100:101]
	global_load_dwordx4 v[166:169], v[242:243], off
	s_nop 0
	v_addc_co_u32_e32 v77, vcc, 0, v75, vcc
	s_nop 0
	s_waitcnt vmcnt(17)
	v_cndmask_b32_e64 v53, 0, v172, s[14:15]
	v_cndmask_b32_e64 v52, 0, v175, s[14:15]
	v_cndmask_b32_e64 v7, 0, v173, s[14:15]
	v_lshlrev_b32_e32 v5, 16, v53
	v_lshlrev_b32_e32 v4, 16, v9
	v_pk_mul_f32 v[4:5], v[38:39], v[4:5]
	v_cndmask_b32_e64 v174, 0, v174, s[14:15]
	v_add_f32_e32 v4, v32, v4
	v_add_f32_e32 v58, v4, v5
	v_and_b32_e32 v5, 0xffff0000, v53
	v_and_b32_e32 v4, 0xffff0000, v9
	v_pk_mul_f32 v[4:5], v[28:29], v[4:5]
	s_nop 0
	v_add_f32_e32 v4, v33, v4
	v_add_f32_e32 v59, v4, v5
	v_lshlrev_b32_e32 v5, 16, v7
	v_lshlrev_b32_e32 v4, 16, v8
	v_pk_mul_f32 v[4:5], v[44:45], v[4:5]
	s_nop 0
	v_add_f32_e32 v4, v34, v4
	v_add_f32_e32 v9, v4, v5
	v_and_b32_e32 v5, 0xffff0000, v7
	v_and_b32_e32 v4, 0xffff0000, v8
	v_pk_mul_f32 v[4:5], v[30:31], v[4:5]
	s_nop 0
	v_add_f32_e32 v4, v35, v4
	v_add_f32_e32 v8, v4, v5
	v_lshlrev_b32_e32 v5, 16, v174
	v_lshlrev_b32_e32 v4, 16, v11
	v_pk_mul_f32 v[4:5], v[46:47], v[4:5]
	s_nop 0
	v_add_f32_e32 v4, v24, v4
	v_add_f32_e32 v7, v4, v5
	v_and_b32_e32 v5, 0xffff0000, v174
	s_mov_b32 s100, 0x42040
	s_mov_b32 s101, 0
	v_lshl_add_u64 v[242:243], v[74:75], 0, s[100:101]
	global_load_dwordx4 v[172:175], v[242:243], off
	v_and_b32_e32 v4, 0xffff0000, v11
	v_pk_mul_f32 v[4:5], v[20:21], v[4:5]
	v_and_b32_e32 v11, 0xffff0000, v52
	v_add_f32_e32 v4, v25, v4
	v_add_f32_e32 v6, v4, v5
	v_lshlrev_b32_e32 v5, 16, v52
	s_nop 0
	v_lshlrev_b32_e32 v4, 16, v10
	v_pk_mul_f32 v[4:5], v[56:57], v[4:5]
	v_and_b32_e32 v10, 0xffff0000, v10
	v_add_f32_e32 v4, v26, v4
	v_pk_mul_f32 v[10:11], v[22:23], v[10:11]
	v_add_f32_e32 v5, v4, v5
	v_add_f32_e32 v4, v27, v10
	v_add_f32_e32 v4, v4, v11
	s_nop 0
	s_waitcnt vmcnt(17)
	v_cndmask_b32_e64 v60, 0, v179, s[16:17]
	v_cndmask_b32_e64 v61, 0, v178, s[16:17]
	v_cndmask_b32_e64 v62, 0, v177, s[16:17]
	v_cndmask_b32_e64 v63, 0, v176, s[16:17]
	s_mov_b32 s100, 0x77a40
	s_mov_b32 s101, 0
	v_lshl_add_u64 v[242:243], v[74:75], 0, s[100:101]
	global_load_dwordx4 v[176:179], v[242:243], off
	s_nop 0
	v_lshlrev_b32_e32 v10, 16, v63
	s_nop 0
	s_waitcnt vmcnt(17)
	v_cndmask_b32_e64 v180, 0, v180, s[10:11]
	v_lshlrev_b32_e32 v11, 16, v180
	v_pk_mul_f32 v[10:11], v[86:87], v[10:11]
	v_cndmask_b32_e64 v181, 0, v181, s[10:11]
	v_add_f32_e32 v10, v58, v10
	v_add_f32_e32 v58, v10, v11
	v_and_b32_e32 v11, 0xffff0000, v180
	v_and_b32_e32 v10, 0xffff0000, v63
	v_pk_mul_f32 v[10:11], v[16:17], v[10:11]
	v_cndmask_b32_e64 v182, 0, v182, s[10:11]
	v_add_f32_e32 v10, v59, v10
	v_add_f32_e32 v52, v10, v11
	v_lshlrev_b32_e32 v11, 16, v181
	v_lshlrev_b32_e32 v10, 16, v62
	v_pk_mul_f32 v[10:11], v[84:85], v[10:11]
	v_cndmask_b32_e64 v183, 0, v183, s[10:11]
	v_add_f32_e32 v9, v9, v10
	v_add_f32_e32 v59, v9, v11
	v_and_b32_e32 v11, 0xffff0000, v181
	v_and_b32_e32 v10, 0xffff0000, v62
	v_pk_mul_f32 v[10:11], v[18:19], v[10:11]
	v_lshlrev_b32_e32 v9, 16, v182
	v_add_f32_e32 v8, v8, v10
	v_add_f32_e32 v10, v8, v11
	v_lshlrev_b32_e32 v8, 16, v61
	v_pk_mul_f32 v[8:9], v[80:81], v[8:9]
	s_nop 0
	v_add_f32_e32 v7, v7, v8
	v_add_f32_e32 v11, v7, v9
	v_and_b32_e32 v9, 0xffff0000, v182
	v_and_b32_e32 v8, 0xffff0000, v61
	v_pk_mul_f32 v[8:9], v[12:13], v[8:9]
	v_lshlrev_b32_e32 v7, 16, v183
	v_add_f32_e32 v6, v6, v8
	v_add_f32_e32 v8, v6, v9
	v_lshlrev_b32_e32 v6, 16, v60
	v_pk_mul_f32 v[6:7], v[82:83], v[6:7]
	s_nop 0
	v_add_f32_e32 v5, v5, v6
	v_add_f32_e32 v9, v5, v7
	v_and_b32_e32 v7, 0xffff0000, v183
	s_mov_b32 s100, 0x7bc40
	s_mov_b32 s101, 0
	v_lshl_add_u64 v[242:243], v[74:75], 0, s[100:101]
	global_load_dwordx4 v[180:183], v[242:243], off
	v_and_b32_e32 v6, 0xffff0000, v60
	v_pk_mul_f32 v[6:7], v[14:15], v[6:7]
	v_cvt_pk_bf16_f32 v5, v59, v10
	s_nop 0
	v_add_f32_e32 v4, v4, v6
	v_add_f32_e32 v7, v4, v7
	v_cvt_pk_bf16_f32 v4, v58, v52
	v_cvt_pk_bf16_f32 v6, v11, v8
	v_cvt_pk_bf16_f32 v7, v9, v7
	s_mov_b32 s81, 0x77000
	v_add_co_u32_e32 v60, vcc, s81, v74
	s_mov_b32 s81, 0x7b000
	s_nop 0
	v_addc_co_u32_e32 v61, vcc, 0, v75, vcc
	s_nop 0
	v_add_co_u32_e32 v62, vcc, s81, v74
	s_mov_b32 s81, 0x7f000
	s_nop 0
	v_addc_co_u32_e32 v63, vcc, 0, v75, vcc
	v_add_co_u32_e32 v64, vcc, s81, v74
	s_mov_b32 s81, 0x84000
	s_nop 0
	v_addc_co_u32_e32 v65, vcc, 0, v75, vcc
	s_nop 0
	v_add_co_u32_e32 v66, vcc, s81, v74
	s_nop 0
	s_waitcnt vmcnt(17)
	v_cndmask_b32_e64 v54, 0, v187, s[18:19]
	v_cndmask_b32_e64 v55, 0, v186, s[18:19]
	v_cndmask_b32_e64 v52, 0, v185, s[18:19]
	v_cndmask_b32_e64 v53, 0, v184, s[18:19]
	s_mov_b32 s100, 0x7fe40
	s_mov_b32 s101, 0
	v_lshl_add_u64 v[242:243], v[74:75], 0, s[100:101]
	global_load_dwordx4 v[184:187], v[242:243], off
	s_nop 0
	v_addc_co_u32_e32 v67, vcc, 0, v75, vcc
	s_nop 0
	s_waitcnt vmcnt(17)
	v_cndmask_b32_e64 v123, 0, v194, s[22:23]
	v_cndmask_b32_e64 v124, 0, v193, s[22:23]
	v_cndmask_b32_e64 v125, 0, v192, s[22:23]
	s_nop 0
	s_waitcnt vmcnt(16)
	v_cndmask_b32_e64 v59, 0, v212, s[20:21]
	v_cndmask_b32_e64 v58, 0, v215, s[20:21]
	v_cndmask_b32_e64 v11, 0, v213, s[20:21]
	v_lshlrev_b32_e32 v9, 16, v59
	v_lshlrev_b32_e32 v8, 16, v53
	v_pk_mul_f32 v[8:9], v[38:39], v[8:9]
	v_cndmask_b32_e64 v214, 0, v214, s[20:21]
	v_add_f32_e32 v8, v32, v8
	v_add_f32_e32 v122, v8, v9
	v_and_b32_e32 v9, 0xffff0000, v59
	v_and_b32_e32 v8, 0xffff0000, v53
	v_pk_mul_f32 v[8:9], v[28:29], v[8:9]
	s_nop 0
	v_add_f32_e32 v8, v33, v8
	v_add_f32_e32 v59, v8, v9
	v_lshlrev_b32_e32 v9, 16, v11
	v_lshlrev_b32_e32 v8, 16, v52
	v_pk_mul_f32 v[8:9], v[44:45], v[8:9]
	s_nop 0
	v_add_f32_e32 v8, v34, v8
	v_add_f32_e32 v53, v8, v9
	v_and_b32_e32 v9, 0xffff0000, v11
	v_and_b32_e32 v8, 0xffff0000, v52
	v_pk_mul_f32 v[8:9], v[30:31], v[8:9]
	s_nop 0
	v_add_f32_e32 v8, v35, v8
	v_add_f32_e32 v52, v8, v9
	v_lshlrev_b32_e32 v9, 16, v214
	v_lshlrev_b32_e32 v8, 16, v55
	v_pk_mul_f32 v[8:9], v[46:47], v[8:9]
	s_nop 0
	v_add_f32_e32 v8, v24, v8
	v_add_f32_e32 v11, v8, v9
	v_and_b32_e32 v9, 0xffff0000, v214
	v_and_b32_e32 v8, 0xffff0000, v55
	v_pk_mul_f32 v[8:9], v[20:21], v[8:9]
	v_and_b32_e32 v55, 0xffff0000, v58
	v_add_f32_e32 v8, v25, v8
	v_add_f32_e32 v10, v8, v9
	v_lshlrev_b32_e32 v9, 16, v58
	v_cndmask_b32_e64 v58, 0, v195, s[22:23]
	s_mov_b32 s100, 0x84040
	s_mov_b32 s101, 0
	v_lshl_add_u64 v[242:243], v[74:75], 0, s[100:101]
	global_load_dwordx4 v[192:195], v[242:243], off
	s_mov_b32 s100, 0xb9a40
	s_mov_b32 s101, 0
	v_lshl_add_u64 v[242:243], v[74:75], 0, s[100:101]
	global_load_dwordx4 v[212:215], v[242:243], off
	s_nop 0
	v_lshlrev_b32_e32 v8, 16, v54
	v_pk_mul_f32 v[8:9], v[56:57], v[8:9]
	v_and_b32_e32 v54, 0xffff0000, v54
	v_add_f32_e32 v8, v26, v8
	v_pk_mul_f32 v[54:55], v[22:23], v[54:55]
	v_add_f32_e32 v9, v8, v9
	v_add_f32_e32 v8, v27, v54
	v_add_f32_e32 v8, v8, v55
	v_lshlrev_b32_e32 v54, 16, v125
	s_nop 0
	s_waitcnt vmcnt(17)
	v_cndmask_b32_e64 v216, 0, v216, s[10:11]
	v_lshlrev_b32_e32 v55, 16, v216
	v_pk_mul_f32 v[54:55], v[86:87], v[54:55]
	v_cndmask_b32_e64 v217, 0, v217, s[10:11]
	v_add_f32_e32 v54, v122, v54
	v_add_f32_e32 v122, v54, v55
	v_and_b32_e32 v55, 0xffff0000, v216
	v_and_b32_e32 v54, 0xffff0000, v125
	v_pk_mul_f32 v[54:55], v[16:17], v[54:55]
	v_cndmask_b32_e64 v218, 0, v218, s[10:11]
	v_add_f32_e32 v54, v59, v54
	v_add_f32_e32 v59, v54, v55
	v_lshlrev_b32_e32 v55, 16, v217
	v_lshlrev_b32_e32 v54, 16, v124
	v_pk_mul_f32 v[54:55], v[84:85], v[54:55]
	v_cndmask_b32_e64 v219, 0, v219, s[10:11]
	v_add_f32_e32 v53, v53, v54
	v_add_f32_e32 v118, v53, v55
	v_and_b32_e32 v55, 0xffff0000, v217
	v_and_b32_e32 v54, 0xffff0000, v124
	v_pk_mul_f32 v[54:55], v[18:19], v[54:55]
	v_lshlrev_b32_e32 v53, 16, v218
	v_add_f32_e32 v52, v52, v54
	v_add_f32_e32 v54, v52, v55
	v_lshlrev_b32_e32 v52, 16, v123
	v_pk_mul_f32 v[52:53], v[80:81], v[52:53]
	s_nop 0
	v_add_f32_e32 v11, v11, v52
	v_add_f32_e32 v55, v11, v53
	v_and_b32_e32 v53, 0xffff0000, v218
	v_and_b32_e32 v52, 0xffff0000, v123
	v_pk_mul_f32 v[52:53], v[12:13], v[52:53]
	v_lshlrev_b32_e32 v11, 16, v219
	v_add_f32_e32 v10, v10, v52
	v_add_f32_e32 v52, v10, v53
	v_lshlrev_b32_e32 v10, 16, v58
	v_pk_mul_f32 v[10:11], v[82:83], v[10:11]
	s_nop 0
	v_add_f32_e32 v9, v9, v10
	v_add_f32_e32 v53, v9, v11
	v_and_b32_e32 v11, 0xffff0000, v219
	s_mov_b32 s100, 0xbdc40
	s_mov_b32 s101, 0
	v_lshl_add_u64 v[242:243], v[74:75], 0, s[100:101]
	global_load_dwordx4 v[216:219], v[242:243], off
	v_and_b32_e32 v10, 0xffff0000, v58
	v_pk_mul_f32 v[10:11], v[14:15], v[10:11]
	v_cvt_pk_bf16_f32 v9, v118, v54
	s_nop 0
	v_add_f32_e32 v8, v8, v10
	v_add_f32_e32 v11, v8, v11
	v_cvt_pk_bf16_f32 v8, v122, v59
	v_cvt_pk_bf16_f32 v10, v55, v52
	v_cvt_pk_bf16_f32 v11, v53, v11
	s_mov_b32 s81, 0xb9000
	v_add_co_u32_e32 v52, vcc, s81, v74
	s_mov_b32 s81, 0xbd000
	s_nop 0
	v_addc_co_u32_e32 v53, vcc, 0, v75, vcc
	s_nop 0
	v_add_co_u32_e32 v54, vcc, s81, v74
	s_mov_b32 s81, 0xc1000
	s_nop 0
	v_addc_co_u32_e32 v55, vcc, 0, v75, vcc
	s_nop 0
	s_waitcnt vmcnt(17)
	v_cndmask_b32_e64 v122, 0, v223, s[0:1]
	v_cndmask_b32_e64 v123, 0, v222, s[0:1]
	v_cndmask_b32_e64 v124, 0, v221, s[0:1]
	v_cndmask_b32_e64 v125, 0, v220, s[0:1]
	s_mov_b32 s100, 0xc1e40
	s_mov_b32 s101, 0
	v_lshl_add_u64 v[242:243], v[74:75], 0, s[100:101]
	global_load_dwordx4 v[220:223], v[242:243], off
	s_nop 0
	v_lshlrev_b32_e32 v58, 16, v125
	s_nop 0
	s_waitcnt vmcnt(17)
	v_cndmask_b32_e64 v224, 0, v224, s[24:25]
	v_lshlrev_b32_e32 v59, 16, v224
	v_pk_mul_f32 v[38:39], v[38:39], v[58:59]
	v_cndmask_b32_e64 v225, 0, v225, s[24:25]
	v_add_f32_e32 v32, v32, v38
	v_add_f32_e32 v126, v32, v39
	v_and_b32_e32 v39, 0xffff0000, v224
	v_and_b32_e32 v38, 0xffff0000, v125
	v_pk_mul_f32 v[28:29], v[28:29], v[38:39]
	v_cndmask_b32_e64 v226, 0, v226, s[24:25]
	v_add_f32_e32 v28, v33, v28
	v_add_f32_e32 v33, v28, v29
	v_lshlrev_b32_e32 v29, 16, v225
	v_lshlrev_b32_e32 v28, 16, v124
	v_pk_mul_f32 v[28:29], v[44:45], v[28:29]
	v_cndmask_b32_e64 v227, 0, v227, s[24:25]
	v_add_f32_e32 v28, v34, v28
	v_add_f32_e32 v32, v28, v29
	v_and_b32_e32 v29, 0xffff0000, v225
	v_and_b32_e32 v28, 0xffff0000, v124
	v_pk_mul_f32 v[28:29], v[30:31], v[28:29]
	v_lshlrev_b32_e32 v31, 16, v226
	v_lshlrev_b32_e32 v30, 16, v123
	v_pk_mul_f32 v[30:31], v[46:47], v[30:31]
	v_add_f32_e32 v28, v35, v28
	v_add_f32_e32 v24, v24, v30
	v_add_f32_e32 v29, v28, v29
	v_add_f32_e32 v28, v24, v31
	v_and_b32_e32 v31, 0xffff0000, v226
	v_and_b32_e32 v30, 0xffff0000, v123
	v_pk_mul_f32 v[20:21], v[20:21], v[30:31]
	v_and_b32_e32 v31, 0xffff0000, v227
	v_add_f32_e32 v20, v25, v20
	v_add_f32_e32 v24, v20, v21
	v_lshlrev_b32_e32 v21, 16, v227
	s_mov_b32 s100, 0xc6040
	s_mov_b32 s101, 0
	v_lshl_add_u64 v[242:243], v[74:75], 0, s[100:101]
	global_load_dwordx4 v[224:227], v[242:243], off
	v_lshlrev_b32_e32 v20, 16, v122
	v_pk_mul_f32 v[20:21], v[56:57], v[20:21]
	v_add_co_u32_e32 v56, vcc, s81, v74
	s_mov_b32 s81, 0xc6000
	s_nop 0
	v_addc_co_u32_e32 v57, vcc, 0, v75, vcc
	s_nop 0
	v_and_b32_e32 v30, 0xffff0000, v122
	v_add_co_u32_e32 v58, vcc, s81, v74
	v_add_f32_e32 v20, v26, v20
	v_pk_mul_f32 v[22:23], v[22:23], v[30:31]
	v_addc_co_u32_e32 v59, vcc, 0, v75, vcc
	v_add_f32_e32 v21, v20, v21
	v_add_f32_e32 v20, v27, v22
	v_add_f32_e32 v20, v20, v23
	s_nop 0
	s_waitcnt vmcnt(17)
	v_cndmask_b32_e64 v25, 0, v231, s[26:27]
	v_cndmask_b32_e64 v26, 0, v230, s[26:27]
	v_cndmask_b32_e64 v27, 0, v229, s[26:27]
	v_cndmask_b32_e64 v30, 0, v228, s[26:27]
	s_nop 0
	v_lshlrev_b32_e32 v22, 16, v30
	s_nop 0
	s_waitcnt vmcnt(16)
	v_cndmask_b32_e64 v38, 0, v232, s[10:11]
	v_lshlrev_b32_e32 v23, 16, v38
	v_pk_mul_f32 v[22:23], v[86:87], v[22:23]
	v_cndmask_b32_e64 v35, 0, v233, s[10:11]
	v_add_f32_e32 v22, v126, v22
	v_add_f32_e32 v39, v22, v23
	v_and_b32_e32 v23, 0xffff0000, v38
	v_and_b32_e32 v22, 0xffff0000, v30
	v_pk_mul_f32 v[16:17], v[16:17], v[22:23]
	v_cndmask_b32_e64 v34, 0, v234, s[10:11]
	v_add_f32_e32 v16, v33, v16
	v_add_f32_e32 v22, v16, v17
	v_lshlrev_b32_e32 v17, 16, v35
	v_lshlrev_b32_e32 v16, 16, v27
	v_pk_mul_f32 v[16:17], v[84:85], v[16:17]
	v_cndmask_b32_e64 v31, 0, v235, s[10:11]
	v_add_f32_e32 v16, v32, v16
	v_add_f32_e32 v23, v16, v17
	v_and_b32_e32 v17, 0xffff0000, v35
	v_and_b32_e32 v16, 0xffff0000, v27
	v_pk_mul_f32 v[16:17], v[18:19], v[16:17]
	s_nop 0
	v_add_f32_e32 v16, v29, v16
	v_add_f32_e32 v18, v16, v17
	v_lshlrev_b32_e32 v17, 16, v34
	v_lshlrev_b32_e32 v16, 16, v26
	v_pk_mul_f32 v[16:17], v[80:81], v[16:17]
	s_nop 0
	v_add_f32_e32 v16, v28, v16
	v_add_f32_e32 v19, v16, v17
	v_and_b32_e32 v17, 0xffff0000, v34
	v_and_b32_e32 v16, 0xffff0000, v26
	v_pk_mul_f32 v[12:13], v[12:13], v[16:17]
	s_nop 0
	v_add_f32_e32 v12, v24, v12
	v_add_f32_e32 v16, v12, v13
	v_lshlrev_b32_e32 v13, 16, v31
	v_lshlrev_b32_e32 v12, 16, v25
	v_pk_mul_f32 v[12:13], v[82:83], v[12:13]
	s_nop 0
	v_add_f32_e32 v12, v21, v12
	v_add_f32_e32 v17, v12, v13
	v_and_b32_e32 v13, 0xffff0000, v31
	v_and_b32_e32 v12, 0xffff0000, v25
	v_pk_mul_f32 v[12:13], v[14:15], v[12:13]
	v_cvt_pk_bf16_f32 v14, v19, v16
	s_nop 0
	v_add_f32_e32 v12, v20, v12
	v_add_f32_e32 v15, v12, v13
	v_cvt_pk_bf16_f32 v12, v39, v22
	v_cvt_pk_bf16_f32 v13, v23, v18
	v_cvt_pk_bf16_f32 v15, v17, v15
	global_load_dwordx4 v[24:27], v144, s[84:85] offset:144
	global_load_dwordx4 v[80:83], v144, s[84:85] offset:128
	s_mov_b64 s[84:85], 0x1080
	v_lshl_add_u64 v[16:17], v[40:41], 0, s[84:85]
	s_mov_b64 s[84:85], 0x2080
	global_load_dwordx4 v[44:47], v[36:37], off offset:128
	s_nop 0
	global_load_dwordx4 v[36:39], v[16:17], off offset:16
	v_lshl_add_u64 v[16:17], v[40:41], 0, s[84:85]
	s_mov_b64 s[84:85], 0x3080
	v_lshl_add_u64 v[120:121], v[78:79], 0, 64
	v_lshl_add_u64 v[28:29], v[40:41], 0, s[84:85]
	v_lshl_add_u64 v[78:79], v[120:121], 0, s[58:59]
	global_load_dwordx4 v[20:23], v[42:43], off offset:128
	s_nop 0
	global_load_dwordx4 v[16:19], v[16:17], off offset:16
	s_nop 0
	global_load_dwordx4 v[32:35], v[48:49], off offset:128
	s_nop 0
	global_load_dwordx4 v[28:31], v[28:29], off offset:16
	s_nop 0
	global_load_dwordx4 v[40:43], v[50:51], off offset:144
	s_nop 0
	global_load_dwordx4 v[48:51], v[50:51], off offset:128
	s_ashr_i32 s81, s80, 31
	s_nop 0
	v_lshl_add_u64 v[78:79], v[120:121], 0, s[60:61]
	s_nop 0
	s_waitcnt vmcnt(25)
	v_cndmask_b32_e64 v122, 0, v239, s[2:3]
	v_cndmask_b32_e64 v123, 0, v238, s[2:3]
	v_cndmask_b32_e64 v124, 0, v237, s[2:3]
	v_cndmask_b32_e64 v118, 0, v236, s[2:3]
	s_nop 0
	s_waitcnt vmcnt(8)
	v_mov_b32_e32 v78, v80
	s_waitcnt vmcnt(7)
	v_mov_b32_e32 v79, v44
	s_nop 0
	v_cndmask_b32_e64 v126, 0, v249, s[4:5]
	v_cndmask_b32_e64 v87, 0, v246, s[4:5]
	v_cndmask_b32_e64 v127, 0, v248, s[4:5]
	v_cndmask_b32_e64 v86, 0, v247, s[4:5]
	v_lshlrev_b32_e32 v85, 16, v87
	v_lshlrev_b32_e32 v84, 16, v118
	v_pk_mul_f32 v[84:85], v[78:79], v[84:85]
	s_nop 0
	s_waitcnt vmcnt(0)
	v_add_f32_e32 v44, v48, v84
	v_add_f32_e32 v119, v44, v85
	v_and_b32_e32 v85, 0xffff0000, v87
	v_and_b32_e32 v84, 0xffff0000, v118
	v_mov_b32_e32 v44, v81
	v_pk_mul_f32 v[80:81], v[44:45], v[84:85]
	v_lshlrev_b32_e32 v85, 16, v86
	v_add_f32_e32 v80, v49, v80
	v_add_f32_e32 v118, v80, v81
	v_lshlrev_b32_e32 v84, 16, v124
	v_mov_b32_e32 v80, v82
	v_mov_b32_e32 v81, v46
	v_pk_mul_f32 v[84:85], v[80:81], v[84:85]
	s_nop 0
	v_add_f32_e32 v46, v50, v84
	v_add_f32_e32 v87, v46, v85
	v_and_b32_e32 v85, 0xffff0000, v86
	v_and_b32_e32 v84, 0xffff0000, v124
	v_mov_b32_e32 v46, v83
	v_pk_mul_f32 v[82:83], v[46:47], v[84:85]
	v_lshlrev_b32_e32 v85, 16, v127
	v_add_f32_e32 v82, v51, v82
	v_add_f32_e32 v86, v82, v83
	v_lshlrev_b32_e32 v84, 16, v123
	v_mov_b32_e32 v82, v24
	v_mov_b32_e32 v83, v36
	v_pk_mul_f32 v[84:85], v[82:83], v[84:85]
	v_mov_b32_e32 v36, v25
	v_add_f32_e32 v24, v40, v84
	v_add_f32_e32 v125, v24, v85
	v_and_b32_e32 v85, 0xffff0000, v127
	v_and_b32_e32 v84, 0xffff0000, v123
	v_pk_mul_f32 v[24:25], v[36:37], v[84:85]
	v_mov_b32_e32 v84, v26
	v_add_f32_e32 v24, v41, v24
	v_add_f32_e32 v124, v24, v25
	v_lshlrev_b32_e32 v25, 16, v126
	v_lshlrev_b32_e32 v24, 16, v122
	v_mov_b32_e32 v85, v38
	v_pk_mul_f32 v[24:25], v[84:85], v[24:25]
	v_mov_b32_e32 v38, v27
	v_add_f32_e32 v24, v42, v24
	v_add_f32_e32 v123, v24, v25
	v_and_b32_e32 v25, 0xffff0000, v126
	v_and_b32_e32 v24, 0xffff0000, v122
	v_pk_mul_f32 v[24:25], v[38:39], v[24:25]
	s_nop 0
	v_add_f32_e32 v24, v43, v24
	v_add_f32_e32 v122, v24, v25
	v_lshl_add_u64 v[24:25], v[120:121], 0, s[62:63]
	s_nop 0
	v_mov_b32_e32 v120, v20
	v_mov_b32_e32 v121, v32
	v_mov_b32_e32 v32, v21
	s_nop 0
	v_cndmask_b32_e64 v126, 0, v135, s[8:9]
	v_cndmask_b32_e64 v127, 0, v134, s[8:9]
	v_cndmask_b32_e64 v128, 0, v133, s[8:9]
	v_cndmask_b32_e64 v129, 0, v132, s[8:9]
	s_nop 0
	s_nop 0
	v_cndmask_b32_e64 v75, 0, v136, s[10:11]
	v_cndmask_b32_e64 v74, 0, v137, s[10:11]
	v_lshlrev_b32_e32 v25, 16, v75
	v_lshlrev_b32_e32 v24, 16, v129
	v_pk_mul_f32 v[24:25], v[120:121], v[24:25]
	v_cndmask_b32_e64 v138, 0, v138, s[10:11]
	v_add_f32_e32 v20, v119, v24
	v_add_f32_e32 v130, v20, v25
	v_and_b32_e32 v25, 0xffff0000, v75
	v_and_b32_e32 v24, 0xffff0000, v129
	v_pk_mul_f32 v[20:21], v[32:33], v[24:25]
	v_mov_b32_e32 v119, v34
	v_add_f32_e32 v20, v118, v20
	v_add_f32_e32 v24, v20, v21
	v_lshlrev_b32_e32 v21, 16, v74
	v_lshlrev_b32_e32 v20, 16, v128
	v_mov_b32_e32 v118, v22
	v_pk_mul_f32 v[20:21], v[118:119], v[20:21]
	v_mov_b32_e32 v34, v23
	v_add_f32_e32 v20, v87, v20
	v_add_f32_e32 v22, v20, v21
	v_and_b32_e32 v21, 0xffff0000, v74
	v_and_b32_e32 v20, 0xffff0000, v128
	v_pk_mul_f32 v[20:21], v[34:35], v[20:21]
	v_mov_b32_e32 v87, v28
	v_add_f32_e32 v20, v86, v20
	v_add_f32_e32 v23, v20, v21
	v_lshlrev_b32_e32 v21, 16, v138
	v_lshlrev_b32_e32 v20, 16, v127
	v_mov_b32_e32 v86, v16
	v_pk_mul_f32 v[20:21], v[86:87], v[20:21]
	v_mov_b32_e32 v28, v17
	v_add_f32_e32 v16, v125, v20
	v_add_f32_e32 v25, v16, v21
	v_and_b32_e32 v21, 0xffff0000, v138
	v_and_b32_e32 v20, 0xffff0000, v127
	v_pk_mul_f32 v[16:17], v[28:29], v[20:21]
	v_cndmask_b32_e64 v139, 0, v139, s[10:11]
	v_add_f32_e32 v16, v124, v16
	v_add_f32_e32 v20, v16, v17
	v_lshlrev_b32_e32 v17, 16, v139
	v_lshlrev_b32_e32 v16, 16, v126
	v_mov_b32_e32 v74, v18
	v_mov_b32_e32 v75, v30
	v_pk_mul_f32 v[16:17], v[74:75], v[16:17]
	v_mov_b32_e32 v30, v19
	v_add_f32_e32 v16, v123, v16
	v_add_f32_e32 v21, v16, v17
	v_and_b32_e32 v17, 0xffff0000, v139
	v_and_b32_e32 v16, 0xffff0000, v126
	v_pk_mul_f32 v[16:17], v[30:31], v[16:17]
	v_cvt_pk_bf16_f32 v18, v25, v20
	s_nop 0
	v_add_f32_e32 v16, v122, v16
	v_add_f32_e32 v19, v16, v17
	v_cvt_pk_bf16_f32 v16, v130, v24
	v_cvt_pk_bf16_f32 v17, v22, v23
	v_cvt_pk_bf16_f32 v19, v21, v19
	s_nop 0
	s_nop 0
	v_cndmask_b32_e64 v24, 0, v143, s[12:13]
	v_cndmask_b32_e64 v25, 0, v142, s[12:13]
	v_cndmask_b32_e64 v26, 0, v141, s[12:13]
	v_cndmask_b32_e64 v27, 0, v140, s[12:13]
	s_nop 0
	s_nop 0
	v_cndmask_b32_e64 v69, 0, v162, s[14:15]
	v_cndmask_b32_e64 v68, 0, v163, s[14:15]
	v_lshlrev_b32_e32 v21, 16, v69
	v_lshlrev_b32_e32 v20, 16, v27
	v_pk_mul_f32 v[20:21], v[78:79], v[20:21]
	v_cndmask_b32_e64 v164, 0, v164, s[14:15]
	v_add_f32_e32 v20, v48, v20
	v_add_f32_e32 v70, v20, v21
	v_and_b32_e32 v21, 0xffff0000, v69
	v_and_b32_e32 v20, 0xffff0000, v27
	v_pk_mul_f32 v[20:21], v[44:45], v[20:21]
	v_cndmask_b32_e64 v165, 0, v165, s[14:15]
	v_add_f32_e32 v20, v49, v20
	v_add_f32_e32 v69, v20, v21
	v_lshlrev_b32_e32 v21, 16, v68
	v_lshlrev_b32_e32 v20, 16, v26
	v_pk_mul_f32 v[20:21], v[80:81], v[20:21]
	s_nop 0
	v_add_f32_e32 v20, v50, v20
	v_add_f32_e32 v71, v20, v21
	v_and_b32_e32 v21, 0xffff0000, v68
	v_and_b32_e32 v20, 0xffff0000, v26
	v_pk_mul_f32 v[20:21], v[46:47], v[20:21]
	s_nop 0
	v_add_f32_e32 v20, v51, v20
	v_add_f32_e32 v68, v20, v21
	v_lshlrev_b32_e32 v21, 16, v164
	v_lshlrev_b32_e32 v20, 16, v25
	v_pk_mul_f32 v[20:21], v[82:83], v[20:21]
	s_nop 0
	v_add_f32_e32 v20, v40, v20
	v_add_f32_e32 v122, v20, v21
	v_and_b32_e32 v21, 0xffff0000, v164
	v_and_b32_e32 v20, 0xffff0000, v25
	v_pk_mul_f32 v[20:21], v[36:37], v[20:21]
	v_and_b32_e32 v25, 0xffff0000, v165
	v_add_f32_e32 v20, v41, v20
	v_add_f32_e32 v22, v20, v21
	v_lshlrev_b32_e32 v21, 16, v165
	v_lshlrev_b32_e32 v20, 16, v24
	v_pk_mul_f32 v[20:21], v[84:85], v[20:21]
	v_and_b32_e32 v24, 0xffff0000, v24
	v_add_f32_e32 v20, v42, v20
	v_pk_mul_f32 v[24:25], v[38:39], v[24:25]
	v_add_f32_e32 v21, v20, v21
	v_add_f32_e32 v20, v43, v24
	v_add_f32_e32 v20, v20, v25
	s_nop 0
	s_nop 0
	v_cndmask_b32_e64 v72, 0, v169, s[16:17]
	v_cndmask_b32_e64 v23, 0, v168, s[16:17]
	v_cndmask_b32_e64 v73, 0, v167, s[16:17]
	v_cndmask_b32_e64 v123, 0, v166, s[16:17]
	s_nop 0
	s_nop 0
	v_cndmask_b32_e64 v77, 0, v172, s[10:11]
	v_cndmask_b32_e64 v76, 0, v173, s[10:11]
	v_lshlrev_b32_e32 v25, 16, v77
	v_lshlrev_b32_e32 v24, 16, v123
	v_pk_mul_f32 v[24:25], v[120:121], v[24:25]
	v_cndmask_b32_e64 v174, 0, v174, s[10:11]
	v_add_f32_e32 v24, v70, v24
	v_add_f32_e32 v70, v24, v25
	v_and_b32_e32 v25, 0xffff0000, v77
	v_and_b32_e32 v24, 0xffff0000, v123
	v_pk_mul_f32 v[24:25], v[32:33], v[24:25]
	v_cndmask_b32_e64 v175, 0, v175, s[10:11]
	v_add_f32_e32 v24, v69, v24
	v_add_f32_e32 v69, v24, v25
	v_lshlrev_b32_e32 v25, 16, v76
	v_lshlrev_b32_e32 v24, 16, v73
	v_pk_mul_f32 v[24:25], v[118:119], v[24:25]
	s_nop 0
	v_add_f32_e32 v24, v71, v24
	v_add_f32_e32 v71, v24, v25
	v_and_b32_e32 v25, 0xffff0000, v76
	v_and_b32_e32 v24, 0xffff0000, v73
	v_pk_mul_f32 v[24:25], v[34:35], v[24:25]
	s_nop 0
	v_add_f32_e32 v24, v68, v24
	v_add_f32_e32 v68, v24, v25
	v_lshlrev_b32_e32 v25, 16, v174
	v_lshlrev_b32_e32 v24, 16, v23
	v_pk_mul_f32 v[24:25], v[86:87], v[24:25]
	s_nop 0
	v_add_f32_e32 v24, v122, v24
	v_add_f32_e32 v73, v24, v25
	v_and_b32_e32 v25, 0xffff0000, v174
	v_and_b32_e32 v24, 0xffff0000, v23
	v_pk_mul_f32 v[24:25], v[28:29], v[24:25]
	v_lshlrev_b32_e32 v23, 16, v175
	v_add_f32_e32 v22, v22, v24
	v_add_f32_e32 v24, v22, v25
	v_lshlrev_b32_e32 v22, 16, v72
	v_pk_mul_f32 v[22:23], v[74:75], v[22:23]
	s_nop 0
	v_add_f32_e32 v21, v21, v22
	v_add_f32_e32 v25, v21, v23
	v_and_b32_e32 v23, 0xffff0000, v175
	v_and_b32_e32 v22, 0xffff0000, v72
	v_pk_mul_f32 v[22:23], v[30:31], v[22:23]
	v_cvt_pk_bf16_f32 v21, v71, v68
	s_nop 0
	v_add_f32_e32 v20, v20, v22
	v_add_f32_e32 v23, v20, v23
	v_cvt_pk_bf16_f32 v20, v70, v69
	v_cvt_pk_bf16_f32 v22, v73, v24
	v_cvt_pk_bf16_f32 v23, v25, v23
	s_nop 0
	s_nop 0
	v_cndmask_b32_e64 v60, 0, v179, s[18:19]
	v_cndmask_b32_e64 v61, 0, v178, s[18:19]
	v_cndmask_b32_e64 v68, 0, v177, s[18:19]
	v_cndmask_b32_e64 v69, 0, v176, s[18:19]
	s_nop 0
	s_nop 0
	v_cndmask_b32_e64 v63, 0, v180, s[20:21]
	v_cndmask_b32_e64 v62, 0, v181, s[20:21]
	v_lshlrev_b32_e32 v25, 16, v63
	v_lshlrev_b32_e32 v24, 16, v69
	v_pk_mul_f32 v[24:25], v[78:79], v[24:25]
	v_cndmask_b32_e64 v182, 0, v182, s[20:21]
	v_add_f32_e32 v24, v48, v24
	v_add_f32_e32 v70, v24, v25
	v_and_b32_e32 v25, 0xffff0000, v63
	v_and_b32_e32 v24, 0xffff0000, v69
	v_pk_mul_f32 v[24:25], v[44:45], v[24:25]
	v_cndmask_b32_e64 v183, 0, v183, s[20:21]
	v_add_f32_e32 v24, v49, v24
	v_add_f32_e32 v69, v24, v25
	v_lshlrev_b32_e32 v25, 16, v62
	v_lshlrev_b32_e32 v24, 16, v68
	v_pk_mul_f32 v[24:25], v[80:81], v[24:25]
	s_nop 0
	v_add_f32_e32 v24, v50, v24
	v_add_f32_e32 v71, v24, v25
	v_and_b32_e32 v25, 0xffff0000, v62
	v_and_b32_e32 v24, 0xffff0000, v68
	v_pk_mul_f32 v[24:25], v[46:47], v[24:25]
	s_nop 0
	v_add_f32_e32 v24, v51, v24
	v_add_f32_e32 v68, v24, v25
	v_lshlrev_b32_e32 v25, 16, v182
	v_lshlrev_b32_e32 v24, 16, v61
	v_pk_mul_f32 v[24:25], v[82:83], v[24:25]
	s_nop 0
	v_add_f32_e32 v24, v40, v24
	v_add_f32_e32 v72, v24, v25
	v_and_b32_e32 v25, 0xffff0000, v182
	v_and_b32_e32 v24, 0xffff0000, v61
	v_pk_mul_f32 v[24:25], v[36:37], v[24:25]
	v_and_b32_e32 v61, 0xffff0000, v183
	v_add_f32_e32 v24, v41, v24
	v_add_f32_e32 v26, v24, v25
	v_lshlrev_b32_e32 v25, 16, v183
	v_lshlrev_b32_e32 v24, 16, v60
	v_pk_mul_f32 v[24:25], v[84:85], v[24:25]
	v_and_b32_e32 v60, 0xffff0000, v60
	v_add_f32_e32 v24, v42, v24
	v_pk_mul_f32 v[60:61], v[38:39], v[60:61]
	v_add_f32_e32 v25, v24, v25
	v_add_f32_e32 v24, v43, v60
	v_add_f32_e32 v24, v24, v61
	s_nop 0
	s_nop 0
	v_cndmask_b32_e64 v64, 0, v187, s[22:23]
	v_cndmask_b32_e64 v27, 0, v186, s[22:23]
	v_cndmask_b32_e64 v65, 0, v185, s[22:23]
	v_cndmask_b32_e64 v73, 0, v184, s[22:23]
	s_nop 0
	s_nop 0
	v_cndmask_b32_e64 v67, 0, v192, s[10:11]
	v_cndmask_b32_e64 v66, 0, v193, s[10:11]
	v_lshlrev_b32_e32 v61, 16, v67
	v_lshlrev_b32_e32 v60, 16, v73
	v_pk_mul_f32 v[60:61], v[120:121], v[60:61]
	v_cndmask_b32_e64 v194, 0, v194, s[10:11]
	v_add_f32_e32 v60, v70, v60
	v_add_f32_e32 v70, v60, v61
	v_and_b32_e32 v61, 0xffff0000, v67
	v_and_b32_e32 v60, 0xffff0000, v73
	v_pk_mul_f32 v[60:61], v[32:33], v[60:61]
	v_cndmask_b32_e64 v195, 0, v195, s[10:11]
	v_add_f32_e32 v60, v69, v60
	v_add_f32_e32 v67, v60, v61
	v_lshlrev_b32_e32 v61, 16, v66
	v_lshlrev_b32_e32 v60, 16, v65
	v_pk_mul_f32 v[60:61], v[118:119], v[60:61]
	s_nop 0
	v_add_f32_e32 v60, v71, v60
	v_add_f32_e32 v69, v60, v61
	v_and_b32_e32 v61, 0xffff0000, v66
	v_and_b32_e32 v60, 0xffff0000, v65
	v_pk_mul_f32 v[60:61], v[34:35], v[60:61]
	s_nop 0
	v_add_f32_e32 v60, v68, v60
	v_add_f32_e32 v65, v60, v61
	v_lshlrev_b32_e32 v61, 16, v194
	v_lshlrev_b32_e32 v60, 16, v27
	v_pk_mul_f32 v[60:61], v[86:87], v[60:61]
	s_nop 0
	v_add_f32_e32 v60, v72, v60
	v_add_f32_e32 v66, v60, v61
	v_and_b32_e32 v61, 0xffff0000, v194
	v_and_b32_e32 v60, 0xffff0000, v27
	v_pk_mul_f32 v[60:61], v[28:29], v[60:61]
	v_lshlrev_b32_e32 v27, 16, v195
	v_add_f32_e32 v26, v26, v60
	v_add_f32_e32 v60, v26, v61
	v_lshlrev_b32_e32 v26, 16, v64
	v_pk_mul_f32 v[26:27], v[74:75], v[26:27]
	s_nop 0
	v_add_f32_e32 v25, v25, v26
	v_add_f32_e32 v61, v25, v27
	v_and_b32_e32 v27, 0xffff0000, v195
	v_and_b32_e32 v26, 0xffff0000, v64
	v_pk_mul_f32 v[26:27], v[30:31], v[26:27]
	v_cvt_pk_bf16_f32 v25, v69, v65
	s_nop 0
	v_add_f32_e32 v24, v24, v26
	v_add_f32_e32 v27, v24, v27
	v_cvt_pk_bf16_f32 v24, v70, v67
	v_cvt_pk_bf16_f32 v26, v66, v60
	v_cvt_pk_bf16_f32 v27, v61, v27
	s_nop 0
	s_nop 0
	v_cndmask_b32_e64 v212, 0, v212, s[0:1]
	s_nop 0
	v_cndmask_b32_e64 v213, 0, v213, s[0:1]
	v_cndmask_b32_e64 v214, 0, v214, s[0:1]
	v_cndmask_b32_e64 v215, 0, v215, s[0:1]
	s_nop 0
	v_cndmask_b32_e64 v65, 0, v216, s[24:25]
	v_cndmask_b32_e64 v64, 0, v217, s[24:25]
	v_lshlrev_b32_e32 v53, 16, v65
	v_lshlrev_b32_e32 v52, 16, v212
	v_pk_mul_f32 v[52:53], v[78:79], v[52:53]
	v_cndmask_b32_e64 v218, 0, v218, s[24:25]
	v_add_f32_e32 v48, v48, v52
	v_add_f32_e32 v48, v48, v53
	v_and_b32_e32 v53, 0xffff0000, v65
	v_and_b32_e32 v52, 0xffff0000, v212
	v_pk_mul_f32 v[44:45], v[44:45], v[52:53]
	v_cndmask_b32_e64 v219, 0, v219, s[24:25]
	v_add_f32_e32 v44, v49, v44
	v_add_f32_e32 v49, v44, v45
	v_lshlrev_b32_e32 v45, 16, v64
	v_lshlrev_b32_e32 v44, 16, v213
	v_pk_mul_f32 v[44:45], v[80:81], v[44:45]
	s_nop 0
	v_add_f32_e32 v44, v50, v44
	v_add_f32_e32 v50, v44, v45
	v_and_b32_e32 v45, 0xffff0000, v64
	v_and_b32_e32 v44, 0xffff0000, v213
	v_pk_mul_f32 v[44:45], v[46:47], v[44:45]
	s_nop 0
	v_add_f32_e32 v44, v51, v44
	v_add_f32_e32 v46, v44, v45
	v_lshlrev_b32_e32 v45, 16, v218
	v_lshlrev_b32_e32 v44, 16, v214
	v_pk_mul_f32 v[44:45], v[82:83], v[44:45]
	s_nop 0
	v_add_f32_e32 v40, v40, v44
	v_add_f32_e32 v47, v40, v45
	v_and_b32_e32 v45, 0xffff0000, v218
	v_and_b32_e32 v44, 0xffff0000, v214
	v_pk_mul_f32 v[36:37], v[36:37], v[44:45]
	v_and_b32_e32 v45, 0xffff0000, v219
	v_add_f32_e32 v36, v41, v36
	v_add_f32_e32 v40, v36, v37
	v_lshlrev_b32_e32 v37, 16, v219
	v_lshlrev_b32_e32 v36, 16, v215
	v_pk_mul_f32 v[36:37], v[84:85], v[36:37]
	v_and_b32_e32 v44, 0xffff0000, v215
	v_add_f32_e32 v36, v42, v36
	v_pk_mul_f32 v[38:39], v[38:39], v[44:45]
	v_add_f32_e32 v37, v36, v37
	v_add_f32_e32 v36, v43, v38
	s_nop 0
	v_add_f32_e32 v36, v36, v39
	s_nop 0
	v_cndmask_b32_e64 v41, 0, v223, s[26:27]
	v_cndmask_b32_e64 v51, 0, v222, s[26:27]
	v_cndmask_b32_e64 v52, 0, v221, s[26:27]
	v_cndmask_b32_e64 v53, 0, v220, s[26:27]
	s_nop 0
	v_lshlrev_b32_e32 v38, 16, v53
	s_nop 0
	v_cndmask_b32_e64 v224, 0, v224, s[10:11]
	v_lshlrev_b32_e32 v39, 16, v224
	v_pk_mul_f32 v[38:39], v[120:121], v[38:39]
	v_cndmask_b32_e64 v225, 0, v225, s[10:11]
	v_add_f32_e32 v38, v48, v38
	v_add_f32_e32 v48, v38, v39
	v_and_b32_e32 v39, 0xffff0000, v224
	v_and_b32_e32 v38, 0xffff0000, v53
	v_pk_mul_f32 v[32:33], v[32:33], v[38:39]
	v_cndmask_b32_e64 v226, 0, v226, s[10:11]
	v_add_f32_e32 v32, v49, v32
	v_add_f32_e32 v38, v32, v33
	v_lshlrev_b32_e32 v33, 16, v225
	v_lshlrev_b32_e32 v32, 16, v52
	v_pk_mul_f32 v[32:33], v[118:119], v[32:33]
	v_cndmask_b32_e64 v227, 0, v227, s[10:11]
	v_add_f32_e32 v32, v50, v32
	v_add_f32_e32 v39, v32, v33
	v_and_b32_e32 v33, 0xffff0000, v225
	v_and_b32_e32 v32, 0xffff0000, v52
	v_pk_mul_f32 v[32:33], v[34:35], v[32:33]
	s_nop 0
	v_add_f32_e32 v32, v46, v32
	v_add_f32_e32 v34, v32, v33
	v_lshlrev_b32_e32 v33, 16, v226
	v_lshlrev_b32_e32 v32, 16, v51
	v_pk_mul_f32 v[32:33], v[86:87], v[32:33]
	s_nop 0
	v_add_f32_e32 v32, v47, v32
	v_add_f32_e32 v35, v32, v33
	v_and_b32_e32 v33, 0xffff0000, v226
	v_and_b32_e32 v32, 0xffff0000, v51
	v_pk_mul_f32 v[28:29], v[28:29], v[32:33]
	s_nop 0
	v_add_f32_e32 v28, v40, v28
	v_add_f32_e32 v32, v28, v29
	v_lshlrev_b32_e32 v29, 16, v227
	v_lshlrev_b32_e32 v28, 16, v41
	v_pk_mul_f32 v[28:29], v[74:75], v[28:29]
	s_nop 0
	v_add_f32_e32 v28, v37, v28
	v_add_f32_e32 v33, v28, v29
	v_and_b32_e32 v29, 0xffff0000, v227
	v_and_b32_e32 v28, 0xffff0000, v41
	v_pk_mul_f32 v[28:29], v[30:31], v[28:29]
	v_cvt_pk_bf16_f32 v30, v35, v32
	s_nop 0
	v_add_f32_e32 v28, v36, v28
	v_add_f32_e32 v31, v28, v29
	v_cvt_pk_bf16_f32 v28, v48, v38
	v_cvt_pk_bf16_f32 v29, v39, v34
	v_cvt_pk_bf16_f32 v31, v33, v31
	s_lshl_b64 s[80:81], s[80:81], 14
	v_lshl_add_u64 v[120:121], v[100:101], 0, s[78:79]
	v_lshl_add_u64 v[122:123], v[102:103], 0, s[78:79]
	v_lshl_add_u64 v[124:125], v[104:105], 0, s[78:79]
	v_lshl_add_u64 v[126:127], v[106:107], 0, s[78:79]
	v_lshl_add_u64 v[128:129], v[108:109], 0, s[78:79]
	v_readlane_b32 s78, v255, 2
	s_add_u32 s78, s78, s54
	v_readlane_b32 s79, v255, 4
	v_and_or_b32 v32, v202, 64, v92
	s_addc_u32 s79, s79, s55
	v_lshl_or_b32 v184, v32, 2, 60
	v_lshl_add_u64 v[32:33], v[110:111], 0, s[54:55]
	s_add_u32 s54, s68, s54
	s_addc_u32 s55, s69, s55
	v_lshl_add_u64 v[118:119], v[116:117], 0, s[82:83]
	v_lshl_add_u64 v[130:131], s[78:79], 2, v[90:91]
	v_lshl_add_u64 v[132:133], v[32:33], 1, s[66:67]
	v_lshl_add_u64 v[134:135], s[54:55], 1, v[112:113]
	v_lshl_add_u64 v[136:137], v[114:115], 0, s[80:81]
	s_mov_b64 s[78:79], 0
	s_branch .LBB0_195

.LBB0_209:
	s_andn2_saveexec_b64 s[54:55], s[80:81]
	v_fma_f32 v82, v81, s92, 0.5
	v_fma_f32 v82, -v81, v82, 1.0
	v_mul_f32_e32 v170, v81, v82
	s_or_b64 exec, exec, s[54:55]
	v_lshl_add_u64 v[138:139], s[74:75], 0, v[118:119]
	v_add_co_u32_e32 v84, vcc, 0x13094000, v138
	v_max_f32_e64 v76, -v76, -v76
	s_nop 0
	v_addc_co_u32_e32 v85, vcc, 0, v139, vcc
	global_load_dwordx2 v[168:169], v[84:85], off offset:2560
	v_add_co_u32_e32 v84, vcc, 0x13098000, v138
	v_max_f32_e32 v76, 0, v76
	s_nop 0
	v_addc_co_u32_e32 v85, vcc, 0, v139, vcc
	global_load_dwordx2 v[164:165], v[84:85], off offset:3072
	v_add_co_u32_e32 v84, vcc, 0x1309c000, v138
	v_add_f32_e32 v185, v76, v80
	s_nop 0
	v_addc_co_u32_e32 v85, vcc, 0, v139, vcc
	v_add_co_u32_e32 v140, vcc, 0x130a1000, v138
	global_load_dwordx2 v[162:163], v[84:85], off offset:3584
	s_nop 0
	v_addc_co_u32_e32 v141, vcc, 0, v139, vcc
	global_load_dwordx2 v[166:167], v[140:141], off
	global_load_dwordx2 v[142:143], v[140:141], off offset:2048
	v_add_co_u32_e32 v140, vcc, s97, v138
	v_mfma_f32_16x16x32_bf16 v[84:87], v[72:75], v[0:3], 0
	s_nop 0
	v_addc_co_u32_e32 v141, vcc, 0, v139, vcc
	global_load_dwordx2 v[140:141], v[140:141], off
	s_mov_b32 s100, 0x130d6a00
	s_mov_b32 s101, 0
	v_lshl_add_u64 v[248:249], v[138:139], 0, s[100:101]
	global_load_dwordx2 v[194:195], v[248:249], off
	s_mov_b32 s100, 0x130dac00
	s_mov_b32 s101, 0
	v_lshl_add_u64 v[248:249], v[138:139], 0, s[100:101]
	global_load_dwordx2 v[212:213], v[248:249], off
	s_mov_b32 s100, 0x130dee00
	s_mov_b32 s101, 0
	v_lshl_add_u64 v[248:249], v[138:139], 0, s[100:101]
	global_load_dwordx2 v[214:215], v[248:249], off
	s_mov_b32 s100, 0x130e3000
	s_mov_b32 s101, 0
	v_lshl_add_u64 v[248:249], v[138:139], 0, s[100:101]
	global_load_dwordx2 v[216:217], v[248:249], off
	s_mov_b32 s100, 0x130e3800
	s_mov_b32 s101, 0
	v_lshl_add_u64 v[248:249], v[138:139], 0, s[100:101]
	global_load_dwordx2 v[218:219], v[248:249], off
	s_mov_b32 s100, 0x130e6000
	s_mov_b32 s101, 0
	v_lshl_add_u64 v[248:249], v[138:139], 0, s[100:101]
	global_load_dwordx2 v[220:221], v[248:249], off
	s_mov_b32 s100, 0x13118a00
	s_mov_b32 s101, 0
	v_lshl_add_u64 v[248:249], v[138:139], 0, s[100:101]
	global_load_dwordx2 v[222:223], v[248:249], off
	s_mov_b32 s100, 0x1311cc00
	s_mov_b32 s101, 0
	v_lshl_add_u64 v[248:249], v[138:139], 0, s[100:101]
	global_load_dwordx2 v[224:225], v[248:249], off
	s_mov_b32 s100, 0x13120e00
	s_mov_b32 s101, 0
	v_lshl_add_u64 v[248:249], v[138:139], 0, s[100:101]
	global_load_dwordx2 v[226:227], v[248:249], off
	s_mov_b32 s100, 0x13125000
	s_mov_b32 s101, 0
	v_lshl_add_u64 v[248:249], v[138:139], 0, s[100:101]
	global_load_dwordx2 v[228:229], v[248:249], off
	s_mov_b32 s100, 0x13125800
	s_mov_b32 s101, 0
	v_lshl_add_u64 v[248:249], v[138:139], 0, s[100:101]
	global_load_dwordx2 v[230:231], v[248:249], off
	s_mov_b32 s100, 0x13128000
	s_mov_b32 s101, 0
	v_lshl_add_u64 v[248:249], v[138:139], 0, s[100:101]
	global_load_dwordx2 v[232:233], v[248:249], off
	s_mov_b32 s100, 0x1315aa00
	s_mov_b32 s101, 0
	v_lshl_add_u64 v[248:249], v[138:139], 0, s[100:101]
	global_load_dwordx2 v[234:235], v[248:249], off
	s_mov_b32 s100, 0x1315ec00
	s_mov_b32 s101, 0
	v_lshl_add_u64 v[248:249], v[138:139], 0, s[100:101]
	global_load_dwordx2 v[236:237], v[248:249], off
	s_mov_b32 s100, 0x13162e00
	s_mov_b32 s101, 0
	v_lshl_add_u64 v[248:249], v[138:139], 0, s[100:101]
	global_load_dwordx2 v[238:239], v[248:249], off
	s_mov_b32 s100, 0x13167000
	s_mov_b32 s101, 0
	v_lshl_add_u64 v[248:249], v[138:139], 0, s[100:101]
	global_load_dwordx2 v[242:243], v[248:249], off
	s_mov_b32 s100, 0x13167800
	s_mov_b32 s101, 0
	v_lshl_add_u64 v[248:249], v[138:139], 0, s[100:101]
	global_load_dwordx2 v[244:245], v[248:249], off
	s_mov_b32 s100, 0x1316a000
	s_mov_b32 s101, 0
	v_lshl_add_u64 v[248:249], v[138:139], 0, s[100:101]
	global_load_dwordx2 v[246:247], v[248:249], off
	v_mfma_f32_16x16x32_bf16 v[84:87], v[60:63], v[16:19], v[84:87]
	v_mfma_f32_16x16x32_bf16 v[80:83], v[68:71], v[0:3], 0
	v_mfma_f32_16x16x32_bf16 v[80:83], v[64:67], v[16:19], v[80:83]
	s_nop 0
	s_nop 4
	s_waitcnt vmcnt(25)
	v_add_f32_e32 v76, v56, v84
	v_mul_f32_e32 v76, 0xbfb8aa3b, v76
	v_exp_f32_e32 v76, v76
	s_nop 0
	v_add_f32_e32 v76, 1.0, v76
	v_rcp_f32_e32 v76, v76
	s_nop 0
	v_mul_f32_e32 v76, 0xc1000000, v76
	v_mul_f32_e32 v76, v185, v76
	v_add_f32_e32 v171, v76, v76
	v_cmp_nlt_f32_e32 vcc, s93, v171
	s_and_saveexec_b64 s[54:55], vcc
	s_xor_b64 s[54:55], exec, s[54:55]
	v_mul_f32_e32 v84, 0x3fb8aa3b, v171
	v_exp_f32_e32 v84, v84
	s_nop 0
	v_sub_f32_e32 v84, 1.0, v84
	s_andn2_saveexec_b64 s[54:55], s[54:55]
	v_fma_f32 v84, v171, s94, 0.5
	v_fma_f32 v84, v171, v84, 1.0
	v_mul_f32_e64 v84, v84, -v171
	s_or_b64 exec, exec, s[54:55]
	v_add_f32_e32 v85, v57, v85
	v_mul_f32_e32 v85, 0xbfb8aa3b, v85
	v_exp_f32_e32 v85, v85
	v_max_f32_e64 v77, -v77, -v77
	v_max_f32_e32 v77, 0, v77
	v_add_f32_e32 v186, v77, v144
	v_add_f32_e32 v85, 1.0, v85
	v_rcp_f32_e32 v85, v85
	s_nop 0
	v_mul_f32_e32 v77, 0xc1000000, v85
	v_mul_f32_e32 v77, v186, v77
	v_add_f32_e32 v144, v77, v77
	v_cmp_nlt_f32_e32 vcc, s93, v144
	s_and_saveexec_b64 s[54:55], vcc
	s_xor_b64 s[54:55], exec, s[54:55]
	v_mul_f32_e32 v85, 0x3fb8aa3b, v144
	v_exp_f32_e32 v85, v85
	s_nop 0
	v_sub_f32_e32 v85, 1.0, v85
	s_andn2_saveexec_b64 s[54:55], s[54:55]
	v_fma_f32 v85, v144, s94, 0.5
	v_fma_f32 v85, v144, v85, 1.0
	v_mul_f32_e64 v85, v85, -v144
	s_or_b64 exec, exec, s[54:55]
	v_add_f32_e32 v86, v58, v86
	v_mul_f32_e32 v86, 0xbfb8aa3b, v86
	v_exp_f32_e32 v86, v86
	v_max_f32_e64 v78, -v78, -v78
	v_max_f32_e32 v78, 0, v78
	v_add_f32_e32 v187, v78, v147
	v_add_f32_e32 v86, 1.0, v86
	v_rcp_f32_e32 v86, v86
	s_nop 0
	v_mul_f32_e32 v78, 0xc1000000, v86
	v_mul_f32_e32 v78, v187, v78
	v_add_f32_e32 v144, v78, v78
	v_cmp_nlt_f32_e32 vcc, s93, v144
	s_and_saveexec_b64 s[54:55], vcc
	s_xor_b64 s[54:55], exec, s[54:55]
	v_mul_f32_e32 v86, 0x3fb8aa3b, v144
	v_exp_f32_e32 v86, v86
	s_nop 0
	v_sub_f32_e32 v86, 1.0, v86
	s_andn2_saveexec_b64 s[54:55], s[54:55]
	v_fma_f32 v86, v144, s94, 0.5
	v_fma_f32 v86, v144, v86, 1.0
	v_mul_f32_e64 v86, v86, -v144
	s_or_b64 exec, exec, s[54:55]
	v_add_f32_e32 v87, v59, v87
	v_mul_f32_e32 v87, 0xbfb8aa3b, v87
	v_exp_f32_e32 v87, v87
	v_max_f32_e64 v79, -v79, -v79
	v_max_f32_e32 v79, 0, v79
	v_add_f32_e32 v188, v79, v170
	v_add_f32_e32 v87, 1.0, v87
	v_rcp_f32_e32 v87, v87
	s_nop 0
	v_mul_f32_e32 v79, 0xc1000000, v87
	v_mul_f32_e32 v87, v188, v79
	v_add_f32_e32 v144, v87, v87
	v_cmp_nlt_f32_e32 vcc, s93, v144
	s_and_saveexec_b64 s[54:55], vcc
	s_xor_b64 s[54:55], exec, s[54:55]
	v_mul_f32_e32 v79, 0x3fb8aa3b, v144
	v_exp_f32_e32 v79, v79
	s_nop 0
	v_sub_f32_e32 v79, 1.0, v79
	s_andn2_saveexec_b64 s[54:55], s[54:55]
	v_fma_f32 v79, v144, s94, 0.5
	v_fma_f32 v79, v144, v79, 1.0
	v_mul_f32_e64 v79, v79, -v144
	s_or_b64 exec, exec, s[54:55]
	s_nop 0
	s_waitcnt vmcnt(24)
	v_add_f32_e32 v82, v34, v82
	v_mul_f32_e32 v82, 0xbfb8aa3b, v82
	v_exp_f32_e32 v82, v82
	v_add_f32_e32 v81, v33, v81
	s_nop 0
	s_waitcnt vmcnt(23)
	v_cndmask_b32_e64 v144, v169, 0, s[28:29]
	v_cndmask_b32_e64 v147, v168, 0, s[28:29]
	v_add_f32_e32 v82, 1.0, v82
	v_add_f32_e32 v83, v35, v83
	v_mul_f32_e32 v81, 0xbfb8aa3b, v81
	v_lshlrev_b32_e32 v152, 16, v147
	v_and_b32_e32 v153, 0xffff0000, v147
	v_lshlrev_b32_e32 v168, 16, v144
	v_and_b32_e32 v169, 0xffff0000, v144
	s_nop 0
	s_waitcnt vmcnt(22)
	v_cndmask_b32_e64 v144, v165, 0, s[30:31]
	v_cndmask_b32_e64 v147, v164, 0, s[30:31]
	v_rcp_f32_e32 v82, v82
	v_sqrt_f32_e32 v86, v86
	v_mul_f32_e32 v83, 0xbfb8aa3b, v83
	v_exp_f32_e32 v81, v81
	v_pk_fma_f32 v[168:169], v[50:51], v[168:169], v[54:55]
	v_pk_fma_f32 v[152:153], v[48:49], v[152:153], v[52:53]
	v_lshlrev_b32_e32 v164, 16, v147
	v_and_b32_e32 v165, 0xffff0000, v147
	v_lshlrev_b32_e32 v170, 16, v144
	v_and_b32_e32 v171, 0xffff0000, v144
	s_nop 0
	s_waitcnt vmcnt(21)
	v_cndmask_b32_e64 v144, v163, 0, s[34:35]
	v_cndmask_b32_e64 v147, v162, 0, s[34:35]
	v_exp_f32_e32 v83, v83
	v_pk_fma_f32 v[152:153], v[44:45], v[164:165], v[152:153]
	v_pk_fma_f32 v[164:165], v[46:47], v[170:171], v[168:169]
	v_lshlrev_b32_e32 v162, 16, v147
	v_and_b32_e32 v163, 0xffff0000, v147
	v_lshlrev_b32_e32 v168, 16, v144
	v_and_b32_e32 v169, 0xffff0000, v144
	s_nop 0
	s_waitcnt vmcnt(20)
	v_cndmask_b32_e64 v144, v167, 0, s[64:65]
	v_cndmask_b32_e64 v147, v166, 0, s[64:65]
	v_add_f32_e32 v80, v32, v80
	v_pk_fma_f32 v[164:165], v[42:43], v[168:169], v[164:165]
	v_pk_fma_f32 v[152:153], v[40:41], v[162:163], v[152:153]
	v_lshlrev_b32_e32 v162, 16, v147
	v_and_b32_e32 v163, 0xffff0000, v147
	v_lshlrev_b32_e32 v166, 16, v144
	v_and_b32_e32 v167, 0xffff0000, v144
	v_mul_f32_e32 v80, 0xbfb8aa3b, v80
	v_pk_fma_f32 v[152:153], v[36:37], v[162:163], v[152:153]
	v_pk_fma_f32 v[162:163], v[38:39], v[166:167], v[164:165]
	v_mul_f32_e32 v82, v82, v86
	v_add_f32_e32 v81, 1.0, v81
	v_exp_f32_e32 v80, v80
	v_mul_f32_e32 v162, v162, v82
	v_add_f32_e32 v82, 1.0, v83
	v_rcp_f32_e32 v81, v81
	v_sqrt_f32_e32 v83, v85
	v_add_f32_e32 v80, 1.0, v80
	v_rcp_f32_e32 v80, v80
	v_mul_f32_e32 v76, 0x3fb8aa3b, v76
	v_mul_f32_e32 v81, v81, v83
	v_sqrt_f32_e32 v83, v84
	v_exp_f32_e32 v76, v76
	v_mul_f32_e32 v77, 0x3fb8aa3b, v77
	v_mul_f32_e32 v85, 0x3fb8aa3b, v87
	v_mul_f32_e32 v80, v80, v83
	v_mul_f32_e32 v87, v152, v80
	v_exp_f32_e32 v77, v77
	v_mov_b32_e32 v80, 0
	v_rcp_f32_e32 v82, v82
	v_mul_f32_e32 v78, 0x3fb8aa3b, v78
	v_sqrt_f32_e32 v79, v79
	v_mov_b32_dpp v80, v87 row_shr:1 row_mask:0xf bank_mask:0xf
	v_mul_f32_e32 v153, v153, v81
	v_exp_f32_e32 v78, v78
	v_fmac_f32_e32 v87, v76, v80
	v_mov_b32_e32 v80, 0
	v_exp_f32_e32 v85, v85
	v_mul_f32_e32 v79, v82, v79
	v_mov_b32_dpp v80, v153 row_shr:1 row_mask:0xf bank_mask:0xf
	v_fmac_f32_e32 v153, v77, v80
	v_mov_b32_e32 v80, 0
	v_mul_f32_e32 v152, v163, v79
	v_mov_b32_e32 v79, 1.0
	v_mov_b32_dpp v80, v162 row_shr:1 row_mask:0xf bank_mask:0xf
	v_fmac_f32_e32 v162, v78, v80
	v_mov_b32_e32 v80, 0
	v_mov_b32_dpp v79, v76 row_shr:1 row_mask:0xf bank_mask:0xf
	v_mul_f32_e32 v76, v76, v79
	v_mov_b32_dpp v80, v152 row_shr:1 row_mask:0xf bank_mask:0xf
	v_mov_b32_e32 v79, 1.0
	v_fmac_f32_e32 v152, v85, v80
	v_mov_b32_e32 v80, 1.0
	v_mov_b32_e32 v81, 0
	v_mov_b32_dpp v79, v77 row_shr:1 row_mask:0xf bank_mask:0xf
	v_mov_b32_dpp v80, v76 row_shr:2 row_mask:0xf bank_mask:0xf
	v_mov_b32_dpp v81, v87 row_shr:2 row_mask:0xf bank_mask:0xf
	v_mul_f32_e32 v77, v77, v79
	v_mov_b32_e32 v79, 1.0
	v_fmac_f32_e32 v87, v76, v81
	v_mul_f32_e32 v147, v76, v80
	v_mov_b32_e32 v76, 1.0
	v_mov_b32_dpp v79, v78 row_shr:1 row_mask:0xf bank_mask:0xf
	v_mul_f32_e32 v78, v78, v79
	v_mov_b32_dpp v76, v77 row_shr:2 row_mask:0xf bank_mask:0xf
	v_mov_b32_e32 v79, 1.0
	v_mul_f32_e32 v163, v77, v76
	v_mov_b32_e32 v76, 1.0
	v_mov_b32_dpp v79, v85 row_shr:1 row_mask:0xf bank_mask:0xf
	v_mul_f32_e32 v79, v85, v79
	v_mov_b32_dpp v76, v78 row_shr:2 row_mask:0xf bank_mask:0xf
	v_mul_f32_e32 v164, v78, v76
	v_mov_b32_e32 v76, 1.0
	v_mov_b32_e32 v80, 0
	s_nop 0
	s_waitcnt vmcnt(18)
	v_lshlrev_b32_e32 v84, 16, v140
	v_mov_b32_dpp v76, v79 row_shr:2 row_mask:0xf bank_mask:0xf
	v_mul_f32_e32 v165, v79, v76
	v_mov_b32_e32 v76, 0
	v_mov_b32_dpp v80, v153 row_shr:2 row_mask:0xf bank_mask:0xf
	v_fmac_f32_e32 v153, v77, v80
	v_mov_b32_dpp v76, v87 row_shr:4 row_mask:0xf bank_mask:0xf
	v_mov_b32_e32 v77, 0
	v_fmac_f32_e32 v87, v147, v76
	v_mov_b32_e32 v76, 0
	v_mov_b32_dpp v77, v162 row_shr:2 row_mask:0xf bank_mask:0xf
	v_fmac_f32_e32 v162, v78, v77
	v_mov_b32_dpp v76, v153 row_shr:4 row_mask:0xf bank_mask:0xf
	v_mov_b32_e32 v77, 0
	v_fmac_f32_e32 v153, v163, v76
	v_mov_b32_e32 v76, 0
	v_mov_b32_dpp v77, v152 row_shr:2 row_mask:0xf bank_mask:0xf
	v_fmac_f32_e32 v152, v79, v77
	v_mov_b32_dpp v76, v162 row_shr:4 row_mask:0xf bank_mask:0xf
	v_fmac_f32_e32 v162, v164, v76
	v_mov_b32_e32 v76, 0
	v_mov_b32_e32 v77, 1.0
	v_mul_f32_e32 v84, 0xbfb8aa3b, v84
	v_mov_b32_dpp v76, v152 row_shr:4 row_mask:0xf bank_mask:0xf
	v_mov_b32_dpp v77, v147 row_shr:4 row_mask:0xf bank_mask:0xf
	v_fmac_f32_e32 v152, v165, v76
	v_lshlrev_b32_e32 v76, 16, v142
	v_and_b32_e32 v78, 0xffff0000, v142
	v_and_b32_e32 v142, 0xffff0000, v140
	v_exp_f32_e32 v140, v84
	v_pk_mul_f32 v[84:85], v[146:147], v[76:77]
	v_mul_f32_e32 v77, 0x3d372713, v76
	v_mul_f32_e32 v77, v77, v76
	v_fmac_f32_e32 v76, v77, v76
	v_mul_f32_e32 v76, 0x3f4c422a, v76
	v_add_f32_e32 v76, v76, v76
	v_mul_f32_e32 v76, 0x3fb8aa3b, v76
	v_exp_f32_e32 v76, v76
	v_add_f32_e32 v77, 1.0, v140
	v_rcp_f32_e32 v144, v77
	v_mov_b32_e32 v77, 1.0
	v_add_f32_e32 v76, 1.0, v76
	v_rcp_f32_e32 v76, v76
	v_mov_b32_e32 v86, 0
	v_mov_b32_dpp v77, v85 row_shr:8 row_mask:0xf bank_mask:0xf
	v_mov_b32_e32 v79, 1.0
	v_fma_f32 v76, v76, -2.0, 1.0
	v_add_f32_e32 v76, 1.0, v76
	v_mov_b32_dpp v86, v87 row_shr:8 row_mask:0xf bank_mask:0xf
	v_pk_mul_f32 v[76:77], v[84:85], v[76:77]
	v_lshlrev_b32_e32 v169, 16, v141
	v_and_b32_e32 v170, 0xffff0000, v141
	v_fmac_f32_e32 v87, v85, v86
	v_pk_mul_f32 v[140:141], v[144:145], v[76:77]
	v_mov_b32_dpp v79, v163 row_shr:4 row_mask:0xf bank_mask:0xf
	v_add_f32_e32 v76, v141, v87
	v_mov_b32_e32 v147, v163
	v_lshlrev_b32_e32 v80, 16, v143
	v_and_b32_e32 v82, 0xffff0000, v143
	v_mul_f32_e32 v171, v140, v76
	v_mul_f32_e32 v76, 0xbfb8aa3b, v142
	v_pk_mul_f32 v[142:143], v[146:147], v[78:79]
	v_mul_f32_e32 v79, 0x3d372713, v78
	v_mul_f32_e32 v79, v79, v78
	v_fmac_f32_e32 v78, v79, v78
	v_mul_f32_e32 v78, 0x3f4c422a, v78
	v_add_f32_e32 v78, v78, v78
	v_exp_f32_e32 v76, v76
	v_mul_f32_e32 v78, 0x3fb8aa3b, v78
	v_exp_f32_e32 v78, v78
	ds_bpermute_b32 v86, v184, v77
	v_add_f32_e32 v76, 1.0, v76
	v_rcp_f32_e32 v144, v76
	v_add_f32_e32 v76, 1.0, v78
	v_rcp_f32_e32 v76, v76
	v_mul_f32_e32 v163, v140, v77
	v_mov_b32_e32 v77, 1.0
	v_mov_b32_e32 v166, 0
	v_fma_f32 v76, v76, -2.0, 1.0
	v_mov_b32_dpp v77, v143 row_shr:8 row_mask:0xf bank_mask:0xf
	v_add_f32_e32 v76, 1.0, v76
	v_mov_b32_dpp v166, v153 row_shr:8 row_mask:0xf bank_mask:0xf
	v_pk_mul_f32 v[76:77], v[142:143], v[76:77]
	v_fmac_f32_e32 v153, v143, v166
	v_pk_mul_f32 v[78:79], v[144:145], v[76:77]
	v_mov_b32_e32 v81, 1.0
	v_add_f32_e32 v76, v79, v153
	v_mul_f32_e32 v79, 0x3d372713, v80
	v_mov_b32_dpp v81, v164 row_shr:4 row_mask:0xf bank_mask:0xf
	v_mov_b32_e32 v147, v164
	v_mul_f32_e32 v79, v79, v80
	v_pk_mul_f32 v[140:141], v[146:147], v[80:81]
	v_fmac_f32_e32 v80, v79, v80
	v_mul_f32_e32 v79, 0x3f4c422a, v80
	ds_bpermute_b32 v85, v184, v153
	v_mul_f32_e32 v153, v78, v76
	v_mul_f32_e32 v76, 0xbfb8aa3b, v169
	v_add_f32_e32 v79, v79, v79
	v_exp_f32_e32 v76, v76
	v_mul_f32_e32 v79, 0x3fb8aa3b, v79
	v_exp_f32_e32 v79, v79
	ds_bpermute_b32 v84, v184, v87
	v_add_f32_e32 v76, 1.0, v76
	v_rcp_f32_e32 v144, v76
	v_add_f32_e32 v76, 1.0, v79
	v_rcp_f32_e32 v76, v76
	ds_bpermute_b32 v87, v184, v77
	v_mul_f32_e32 v164, v78, v77
	v_mov_b32_e32 v77, 1.0
	v_fma_f32 v76, v76, -2.0, 1.0
	v_mov_b32_e32 v167, 0
	v_mov_b32_dpp v77, v141 row_shr:8 row_mask:0xf bank_mask:0xf
	v_add_f32_e32 v76, 1.0, v76
	v_mov_b32_dpp v167, v162 row_shr:8 row_mask:0xf bank_mask:0xf
	v_pk_mul_f32 v[76:77], v[140:141], v[76:77]
	v_fmac_f32_e32 v162, v141, v167
	v_pk_mul_f32 v[78:79], v[144:145], v[76:77]
	v_mov_b32_e32 v83, 1.0
	v_add_f32_e32 v76, v79, v162
	v_mul_f32_e32 v79, 0x3d372713, v82
	v_mov_b32_dpp v83, v165 row_shr:4 row_mask:0xf bank_mask:0xf
	v_mov_b32_e32 v147, v165
	v_mul_f32_e32 v79, v79, v82
	v_pk_mul_f32 v[80:81], v[146:147], v[82:83]
	v_fmac_f32_e32 v82, v79, v82
	v_mul_f32_e32 v79, 0x3f4c422a, v82
	ds_bpermute_b32 v142, v184, v162
	v_mul_f32_e32 v162, v78, v76
	v_mul_f32_e32 v76, 0xbfb8aa3b, v170
	v_add_f32_e32 v79, v79, v79
	v_exp_f32_e32 v76, v76
	v_mul_f32_e32 v79, 0x3fb8aa3b, v79
	v_exp_f32_e32 v79, v79
	ds_bpermute_b32 v140, v184, v77
	v_add_f32_e32 v76, 1.0, v76
	v_rcp_f32_e32 v144, v76
	v_add_f32_e32 v76, 1.0, v79
	v_rcp_f32_e32 v76, v76
	v_mul_f32_e32 v82, v78, v77
	v_mov_b32_e32 v77, 1.0
	v_mov_b32_e32 v168, 0
	v_fma_f32 v76, v76, -2.0, 1.0
	v_mov_b32_dpp v77, v81 row_shr:8 row_mask:0xf bank_mask:0xf
	v_add_f32_e32 v76, 1.0, v76
	v_mov_b32_dpp v168, v152 row_shr:8 row_mask:0xf bank_mask:0xf
	v_pk_mul_f32 v[76:77], v[80:81], v[76:77]
	v_fmac_f32_e32 v152, v81, v168
	v_pk_mul_f32 v[78:79], v[144:145], v[76:77]
	ds_bpermute_b32 v141, v184, v77
	v_add_f32_e32 v76, v79, v152
	v_mul_f32_e32 v79, v78, v76
	ds_bpermute_b32 v143, v184, v152
	v_mul_f32_e32 v83, v78, v77
	v_cvt_pk_bf16_f32 v77, v162, v79
	v_lshl_add_u64 v[78:79], s[74:75], 0, v[134:135]
	v_add_co_u32_e32 v80, vcc, s95, v78
	v_cvt_pk_bf16_f32 v76, v171, v153
	s_nop 1
	v_addc_co_u32_e32 v81, vcc, 0, v79, vcc
	v_add_co_u32_e32 v78, vcc, s96, v78
	global_store_dwordx2 v[80:81], v[76:77], off
	s_nop 0
	v_addc_co_u32_e32 v79, vcc, 0, v79, vcc
	v_cvt_pk_bf16_f32 v76, v163, v164
	v_cvt_pk_bf16_f32 v77, v82, v83
	global_store_dwordx2 v[78:79], v[76:77], off
	s_mov_b32 s54, 0x130d6000
	v_add_co_u32_e32 v80, vcc, s54, v138
	s_mov_b32 s54, 0x130da000
	s_nop 0
	v_addc_co_u32_e32 v81, vcc, 0, v139, vcc
	s_nop 0
	v_add_co_u32_e32 v80, vcc, s54, v138
	s_mov_b32 s54, 0x130de000
	s_nop 0
	v_addc_co_u32_e32 v81, vcc, 0, v139, vcc
	s_nop 0
	v_add_co_u32_e32 v80, vcc, s54, v138
	s_mov_b32 s54, 0x130e3000
	s_nop 0
	v_addc_co_u32_e32 v81, vcc, 0, v139, vcc
	v_add_co_u32_e32 v152, vcc, s54, v138
	s_nop 0
	s_nop 0
	v_addc_co_u32_e32 v153, vcc, 0, v139, vcc
	s_nop 0
	s_nop 0
	v_add_co_u32_e32 v152, vcc, 0x130e6000, v138
	v_mfma_f32_16x16x32_bf16 v[80:83], v[72:75], v[4:7], 0
	s_nop 0
	v_addc_co_u32_e32 v153, vcc, 0, v139, vcc
	s_nop 0
	v_mfma_f32_16x16x32_bf16 v[80:83], v[60:63], v[20:23], v[80:83]
	v_mfma_f32_16x16x32_bf16 v[76:79], v[68:71], v[4:7], 0
	v_mfma_f32_16x16x32_bf16 v[76:79], v[64:67], v[20:23], v[76:79]
	s_nop 5
	v_add_f32_e32 v80, v56, v80
	v_mul_f32_e32 v80, 0xbfb8aa3b, v80
	v_exp_f32_e32 v80, v80
	s_nop 0
	v_add_f32_e32 v80, 1.0, v80
	v_rcp_f32_e32 v80, v80
	s_nop 0
	v_mul_f32_e32 v80, 0xc1000000, v80
	v_mul_f32_e32 v80, v185, v80
	v_add_f32_e32 v147, v80, v80
	v_cmp_nlt_f32_e32 vcc, s93, v147
	s_and_saveexec_b64 s[54:55], vcc
	s_xor_b64 s[54:55], exec, s[54:55]
	v_mul_f32_e32 v144, 0x3fb8aa3b, v147
	v_exp_f32_e32 v144, v144
	s_nop 0
	v_sub_f32_e32 v144, 1.0, v144
	s_andn2_saveexec_b64 s[54:55], s[54:55]
	v_fma_f32 v144, v147, s94, 0.5
	v_fma_f32 v144, v147, v144, 1.0
	v_mul_f32_e64 v144, v144, -v147
	s_or_b64 exec, exec, s[54:55]
	v_add_f32_e32 v81, v57, v81
	v_mul_f32_e32 v81, 0xbfb8aa3b, v81
	v_exp_f32_e32 v81, v81
	s_nop 0
	v_add_f32_e32 v81, 1.0, v81
	v_rcp_f32_e32 v81, v81
	s_nop 0
	v_mul_f32_e32 v81, 0xc1000000, v81
	v_mul_f32_e32 v81, v186, v81
	v_add_f32_e32 v174, v81, v81
	v_cmp_nlt_f32_e32 vcc, s93, v174
	s_and_saveexec_b64 s[54:55], vcc
	s_xor_b64 s[54:55], exec, s[54:55]
	v_mul_f32_e32 v147, 0x3fb8aa3b, v174
	v_exp_f32_e32 v147, v147
	s_nop 0
	v_sub_f32_e32 v147, 1.0, v147
	s_andn2_saveexec_b64 s[54:55], s[54:55]
	v_fma_f32 v147, v174, s94, 0.5
	v_fma_f32 v147, v174, v147, 1.0
	v_mul_f32_e64 v147, v147, -v174
	s_or_b64 exec, exec, s[54:55]
	v_add_f32_e32 v82, v58, v82
	v_mul_f32_e32 v82, 0xbfb8aa3b, v82
	v_exp_f32_e32 v82, v82
	s_nop 0
	v_add_f32_e32 v82, 1.0, v82
	v_rcp_f32_e32 v82, v82
	s_nop 0
	v_mul_f32_e32 v82, 0xc1000000, v82
	v_mul_f32_e32 v82, v187, v82
	v_add_f32_e32 v175, v82, v82
	v_cmp_nlt_f32_e32 vcc, s93, v175
	s_and_saveexec_b64 s[54:55], vcc
	s_xor_b64 s[54:55], exec, s[54:55]
	v_mul_f32_e32 v152, 0x3fb8aa3b, v175
	v_exp_f32_e32 v152, v152
	s_nop 0
	v_sub_f32_e32 v174, 1.0, v152
	s_andn2_saveexec_b64 s[54:55], s[54:55]
	v_fma_f32 v152, v175, s94, 0.5
	v_fma_f32 v152, v175, v152, 1.0
	v_mul_f32_e64 v174, v152, -v175
	s_or_b64 exec, exec, s[54:55]
	v_add_f32_e32 v83, v59, v83
	v_mul_f32_e32 v83, 0xbfb8aa3b, v83
	v_exp_f32_e32 v83, v83
	s_nop 0
	v_add_f32_e32 v83, 1.0, v83
	v_rcp_f32_e32 v83, v83
	s_nop 0
	v_mul_f32_e32 v83, 0xc1000000, v83
	v_mul_f32_e32 v175, v188, v83
	v_add_f32_e32 v176, v175, v175
	v_cmp_nlt_f32_e32 vcc, s93, v176
	s_and_saveexec_b64 s[54:55], vcc
	s_xor_b64 s[54:55], exec, s[54:55]
	v_mul_f32_e32 v83, 0x3fb8aa3b, v176
	v_exp_f32_e32 v83, v83
	s_nop 0
	v_sub_f32_e32 v83, 1.0, v83
	s_andn2_saveexec_b64 s[54:55], s[54:55]
	v_fma_f32 v83, v176, s94, 0.5
	v_fma_f32 v83, v176, v83, 1.0
	v_mul_f32_e64 v83, v83, -v176
	s_or_b64 exec, exec, s[54:55]
	v_add_f32_e32 v78, v34, v78
	v_mul_f32_e32 v78, 0xbfb8aa3b, v78
	s_nop 0
	s_waitcnt vmcnt(19)
	v_cndmask_b32_e64 v171, v195, 0, s[36:37]
	v_cndmask_b32_e64 v153, v194, 0, s[36:37]
	v_exp_f32_e32 v78, v78
	v_lshlrev_b32_e32 v152, 16, v153
	v_and_b32_e32 v153, 0xffff0000, v153
	v_lshlrev_b32_e32 v170, 16, v171
	v_and_b32_e32 v171, 0xffff0000, v171
	s_nop 0
	s_waitcnt vmcnt(18)
	v_cndmask_b32_e64 v177, v213, 0, s[38:39]
	v_cndmask_b32_e64 v163, v212, 0, s[38:39]
	v_pk_fma_f32 v[170:171], v[50:51], v[170:171], v[54:55]
	v_pk_fma_f32 v[152:153], v[48:49], v[152:153], v[52:53]
	v_lshlrev_b32_e32 v162, 16, v163
	v_and_b32_e32 v163, 0xffff0000, v163
	v_lshlrev_b32_e32 v176, 16, v177
	v_and_b32_e32 v177, 0xffff0000, v177
	v_pk_fma_f32 v[152:153], v[44:45], v[162:163], v[152:153]
	v_pk_fma_f32 v[162:163], v[46:47], v[176:177], v[170:171]
	s_nop 0
	s_waitcnt vmcnt(17)
	v_cndmask_b32_e64 v171, v215, 0, s[40:41]
	v_cndmask_b32_e64 v169, v214, 0, s[40:41]
	v_add_f32_e32 v77, v33, v77
	v_lshlrev_b32_e32 v168, 16, v169
	v_and_b32_e32 v169, 0xffff0000, v169
	v_add_f32_e32 v78, 1.0, v78
	v_add_f32_e32 v79, v35, v79
	v_mul_f32_e32 v77, 0xbfb8aa3b, v77
	v_pk_fma_f32 v[152:153], v[40:41], v[168:169], v[152:153]
	s_nop 0
	s_waitcnt vmcnt(16)
	v_cndmask_b32_e64 v169, v216, 0, s[64:65]
	v_rcp_f32_e32 v78, v78
	v_sqrt_f32_e32 v172, v174
	v_mul_f32_e32 v79, 0xbfb8aa3b, v79
	v_exp_f32_e32 v77, v77
	v_lshlrev_b32_e32 v170, 16, v171
	v_and_b32_e32 v171, 0xffff0000, v171
	v_exp_f32_e32 v79, v79
	v_pk_fma_f32 v[162:163], v[42:43], v[170:171], v[162:163]
	v_cndmask_b32_e64 v171, v217, 0, s[64:65]
	v_add_f32_e32 v76, v32, v76
	v_lshlrev_b32_e32 v168, 16, v169
	v_and_b32_e32 v169, 0xffff0000, v169
	v_lshlrev_b32_e32 v170, 16, v171
	v_and_b32_e32 v171, 0xffff0000, v171
	v_mul_f32_e32 v76, 0xbfb8aa3b, v76
	v_pk_fma_f32 v[152:153], v[36:37], v[168:169], v[152:153]
	v_pk_fma_f32 v[168:169], v[38:39], v[170:171], v[162:163]
	v_mul_f32_e32 v78, v78, v172
	v_add_f32_e32 v77, 1.0, v77
	v_exp_f32_e32 v76, v76
	v_mul_f32_e32 v171, v168, v78
	v_add_f32_e32 v78, 1.0, v79
	v_rcp_f32_e32 v77, v77
	v_sqrt_f32_e32 v79, v147
	v_add_f32_e32 v76, 1.0, v76
	v_rcp_f32_e32 v76, v76
	v_rcp_f32_e32 v78, v78
	v_mul_f32_e32 v77, v77, v79
	v_sqrt_f32_e32 v79, v144
	v_mul_f32_e32 v80, 0x3fb8aa3b, v80
	v_exp_f32_e32 v80, v80
	v_mul_f32_e32 v144, v153, v77
	v_mul_f32_e32 v76, v76, v79
	v_sqrt_f32_e32 v79, v83
	v_mul_f32_e32 v168, v152, v76
	v_mul_f32_e32 v76, 0x3fb8aa3b, v81
	v_exp_f32_e32 v76, v76
	v_mul_f32_e32 v78, v78, v79
	v_mul_f32_e32 v172, v169, v78
	v_mov_b32_e32 v78, 1.0
	v_mov_b32_e32 v79, v145
	v_mul_f32_e32 v77, 0x3fb8aa3b, v82
	v_mov_b32_dpp v78, v80 row_shr:1 row_mask:0xf bank_mask:0xf
	v_mov_b32_dpp v79, v168 row_shr:1 row_mask:0xf bank_mask:0xf
	v_exp_f32_e32 v77, v77
	v_fmac_f32_e32 v168, v80, v79
	v_mul_f32_e32 v78, v80, v78
	v_mov_b32_e32 v80, v145
	v_mul_f32_e32 v147, 0x3fb8aa3b, v175
	v_exp_f32_e32 v147, v147
	v_mov_b32_dpp v80, v144 row_shr:1 row_mask:0xf bank_mask:0xf
	v_mov_b32_e32 v79, 1.0
	v_fmac_f32_e32 v144, v76, v80
	v_mov_b32_e32 v80, v145
	v_mov_b32_dpp v79, v76 row_shr:1 row_mask:0xf bank_mask:0xf
	v_mul_f32_e32 v76, v76, v79
	v_mov_b32_dpp v80, v171 row_shr:1 row_mask:0xf bank_mask:0xf
	v_mov_b32_e32 v79, 1.0
	v_fmac_f32_e32 v171, v77, v80
	v_mov_b32_e32 v80, v145
	v_mov_b32_dpp v79, v77 row_shr:1 row_mask:0xf bank_mask:0xf
	v_mul_f32_e32 v77, v77, v79
	v_mov_b32_dpp v80, v172 row_shr:1 row_mask:0xf bank_mask:0xf
	v_mov_b32_e32 v79, 1.0
	v_fmac_f32_e32 v172, v147, v80
	v_mov_b32_e32 v80, 1.0
	v_mov_b32_e32 v81, v145
	v_mov_b32_dpp v79, v147 row_shr:1 row_mask:0xf bank_mask:0xf
	v_mov_b32_dpp v80, v78 row_shr:2 row_mask:0xf bank_mask:0xf
	v_mov_b32_dpp v81, v168 row_shr:2 row_mask:0xf bank_mask:0xf
	v_mul_f32_e32 v79, v147, v79
	v_fmac_f32_e32 v168, v78, v81
	v_mul_f32_e32 v147, v78, v80
	v_mov_b32_e32 v78, 1.0
	v_mov_b32_e32 v80, v145
	s_waitcnt lgkmcnt(4)
	v_pk_fma_f32 v[162:163], v[86:87], 0, v[84:85] op_sel_hi:[1,0,1]
	v_mov_b32_dpp v78, v76 row_shr:2 row_mask:0xf bank_mask:0xf
	v_mov_b32_dpp v80, v144 row_shr:2 row_mask:0xf bank_mask:0xf
	v_fmac_f32_e32 v144, v76, v80
	v_mul_f32_e32 v169, v76, v78
	v_mov_b32_e32 v76, 1.0
	v_mov_b32_e32 v78, v145
	s_nop 0
	s_waitcnt vmcnt(14)
	v_lshlrev_b32_e32 v84, 16, v220
	v_mov_b32_dpp v76, v77 row_shr:2 row_mask:0xf bank_mask:0xf
	v_mul_f32_e32 v170, v77, v76
	v_mov_b32_e32 v76, 1.0
	v_mov_b32_dpp v78, v171 row_shr:2 row_mask:0xf bank_mask:0xf
	v_fmac_f32_e32 v171, v77, v78
	v_mov_b32_dpp v76, v79 row_shr:2 row_mask:0xf bank_mask:0xf
	v_mul_f32_e32 v173, v79, v76
	v_mov_b32_e32 v76, v145
	v_mov_b32_e32 v77, v145
	v_mul_f32_e32 v84, 0xbfb8aa3b, v84
	v_mov_b32_dpp v76, v168 row_shr:4 row_mask:0xf bank_mask:0xf
	v_fmac_f32_e32 v168, v147, v76
	v_mov_b32_e32 v76, v145
	v_mov_b32_dpp v77, v172 row_shr:2 row_mask:0xf bank_mask:0xf
	v_fmac_f32_e32 v172, v79, v77
	v_mov_b32_dpp v76, v144 row_shr:4 row_mask:0xf bank_mask:0xf
	v_fmac_f32_e32 v144, v169, v76
	v_mov_b32_e32 v76, v145
	v_mov_b32_e32 v77, 1.0
	v_exp_f32_e32 v153, v84
	v_mov_b32_dpp v76, v171 row_shr:4 row_mask:0xf bank_mask:0xf
	v_fmac_f32_e32 v171, v170, v76
	v_mov_b32_e32 v76, v145
	v_mov_b32_dpp v77, v147 row_shr:4 row_mask:0xf bank_mask:0xf
	v_mov_b32_e32 v152, v145
	v_mov_b32_dpp v76, v172 row_shr:4 row_mask:0xf bank_mask:0xf
	v_fmac_f32_e32 v172, v173, v76
	v_lshlrev_b32_e32 v76, 16, v218
	v_pk_mul_f32 v[84:85], v[146:147], v[76:77]
	v_mul_f32_e32 v77, 0x3d372713, v76
	v_mul_f32_e32 v77, v77, v76
	v_fmac_f32_e32 v76, v77, v76
	v_mul_f32_e32 v76, 0x3f4c422a, v76
	v_add_f32_e32 v76, v76, v76
	v_mul_f32_e32 v76, 0x3fb8aa3b, v76
	v_exp_f32_e32 v77, v76
	v_add_f32_e32 v76, 1.0, v153
	v_rcp_f32_e32 v76, v76
	v_mov_b32_dpp v152, v168 row_shr:8 row_mask:0xf bank_mask:0xf
	v_add_f32_e32 v77, 1.0, v77
	v_rcp_f32_e32 v77, v77
	v_mov_b32_e32 v153, 1.0
	v_fmac_f32_e32 v168, v85, v152
	v_mov_b32_e32 v79, 1.0
	v_fma_f32 v77, v77, -2.0, 1.0
	v_mov_b32_dpp v153, v85 row_shr:8 row_mask:0xf bank_mask:0xf
	v_add_f32_e32 v152, 1.0, v77
	v_pk_mul_f32 v[84:85], v[84:85], v[152:153]
	v_mov_b32_e32 v77, v162
	v_lshlrev_b32_e32 v80, 16, v219
	v_and_b32_e32 v82, 0xffff0000, v219
	v_and_b32_e32 v167, 0xffff0000, v220
	v_pk_mul_f32 v[76:77], v[76:77], v[84:85]
	v_mov_b32_dpp v79, v169 row_shr:4 row_mask:0xf bank_mask:0xf
	v_and_b32_e32 v78, 0xffff0000, v218
	v_add_f32_e32 v77, v77, v168
	v_mul_f32_e32 v84, 0xbfb8aa3b, v167
	v_mov_b32_e32 v147, v169
	ds_bpermute_b32 v164, v184, v85
	v_mul_f32_e32 v152, v76, v77
	v_mul_f32_e32 v77, v85, v86
	v_exp_f32_e32 v153, v84
	v_pk_mul_f32 v[84:85], v[146:147], v[78:79]
	v_mul_f32_e32 v79, 0x3d372713, v78
	v_mul_f32_e32 v79, v79, v78
	v_fmac_f32_e32 v78, v79, v78
	v_mul_f32_e32 v78, 0x3f4c422a, v78
	v_add_f32_e32 v78, v78, v78
	v_mul_f32_e32 v78, 0x3fb8aa3b, v78
	v_exp_f32_e32 v78, v78
	v_mul_f32_e32 v179, v76, v77
	v_add_f32_e32 v76, 1.0, v153
	v_rcp_f32_e32 v76, v76
	v_add_f32_e32 v77, 1.0, v78
	v_rcp_f32_e32 v77, v77
	v_mov_b32_e32 v79, 1.0
	v_mov_b32_e32 v174, v145
	v_mov_b32_e32 v81, 1.0
	v_fma_f32 v77, v77, -2.0, 1.0
	v_mov_b32_dpp v79, v85 row_shr:8 row_mask:0xf bank_mask:0xf
	v_add_f32_e32 v78, 1.0, v77
	v_mov_b32_dpp v174, v144 row_shr:8 row_mask:0xf bank_mask:0xf
	v_pk_mul_f32 v[78:79], v[84:85], v[78:79]
	v_mov_b32_e32 v77, v163
	v_lshlrev_b32_e32 v177, 16, v221
	v_fmac_f32_e32 v144, v85, v174
	v_pk_mul_f32 v[76:77], v[76:77], v[78:79]
	v_mov_b32_dpp v81, v170 row_shr:4 row_mask:0xf bank_mask:0xf
	v_add_f32_e32 v77, v77, v144
	v_mul_f32_e32 v78, 0xbfb8aa3b, v177
	v_mov_b32_e32 v147, v170
	v_and_b32_e32 v178, 0xffff0000, v221
	ds_bpermute_b32 v165, v184, v79
	v_mul_f32_e32 v84, v76, v77
	v_mul_f32_e32 v77, v79, v87
	v_exp_f32_e32 v85, v78
	v_pk_mul_f32 v[78:79], v[146:147], v[80:81]
	v_mul_f32_e32 v81, 0x3d372713, v80
	v_mul_f32_e32 v81, v81, v80
	v_fmac_f32_e32 v80, v81, v80
	v_mul_f32_e32 v80, 0x3f4c422a, v80
	v_add_f32_e32 v80, v80, v80
	v_mul_f32_e32 v80, 0x3fb8aa3b, v80
	v_exp_f32_e32 v80, v80
	ds_bpermute_b32 v167, v184, v144
	v_mul_f32_e32 v144, v76, v77
	v_add_f32_e32 v76, 1.0, v85
	v_add_f32_e32 v77, 1.0, v80
	v_rcp_f32_e32 v77, v77
	v_rcp_f32_e32 v76, v76
	v_mov_b32_e32 v175, v145
	v_mov_b32_e32 v81, 1.0
	v_fma_f32 v77, v77, -2.0, 1.0
	s_waitcnt lgkmcnt(3)
	v_pk_fma_f32 v[142:143], v[140:141], 0, v[142:143] op_sel_hi:[1,0,1]
	v_mov_b32_dpp v175, v171 row_shr:8 row_mask:0xf bank_mask:0xf
	v_mov_b32_dpp v81, v79 row_shr:8 row_mask:0xf bank_mask:0xf
	v_add_f32_e32 v80, 1.0, v77
	v_fmac_f32_e32 v171, v79, v175
	v_pk_mul_f32 v[78:79], v[78:79], v[80:81]
	v_mov_b32_e32 v77, v142
	v_mov_b32_e32 v83, 1.0
	v_pk_mul_f32 v[76:77], v[76:77], v[78:79]
	v_mul_f32_e32 v81, 0x3d372713, v82
	v_mov_b32_dpp v83, v173 row_shr:4 row_mask:0xf bank_mask:0xf
	v_add_f32_e32 v77, v77, v171
	v_mul_f32_e32 v78, 0xbfb8aa3b, v178
	v_mov_b32_e32 v147, v173
	v_mul_f32_e32 v81, v81, v82
	ds_bpermute_b32 v166, v184, v168
	ds_bpermute_b32 v168, v184, v79
	v_mul_f32_e32 v85, v76, v77
	v_mul_f32_e32 v77, v79, v140
	v_exp_f32_e32 v80, v78
	v_pk_mul_f32 v[78:79], v[146:147], v[82:83]
	v_fmac_f32_e32 v82, v81, v82
	v_mul_f32_e32 v81, 0x3f4c422a, v82
	v_add_f32_e32 v81, v81, v81
	v_mul_f32_e32 v81, 0x3fb8aa3b, v81
	v_exp_f32_e32 v81, v81
	v_mul_f32_e32 v82, v76, v77
	v_add_f32_e32 v76, 1.0, v80
	v_rcp_f32_e32 v76, v76
	v_add_f32_e32 v77, 1.0, v81
	v_rcp_f32_e32 v77, v77
	v_mov_b32_e32 v176, v145
	v_mov_b32_e32 v81, 1.0
	ds_bpermute_b32 v170, v184, v171
	v_fma_f32 v77, v77, -2.0, 1.0
	v_mov_b32_dpp v176, v172 row_shr:8 row_mask:0xf bank_mask:0xf
	v_mov_b32_dpp v81, v79 row_shr:8 row_mask:0xf bank_mask:0xf
	v_add_f32_e32 v80, 1.0, v77
	v_fmac_f32_e32 v172, v79, v176
	v_pk_mul_f32 v[78:79], v[78:79], v[80:81]
	v_mov_b32_e32 v77, v143
	v_pk_mul_f32 v[76:77], v[76:77], v[78:79]
	v_mul_f32_e32 v78, v79, v141
	v_add_f32_e32 v77, v77, v172
	v_mul_f32_e32 v77, v76, v77
	ds_bpermute_b32 v169, v184, v79
	ds_bpermute_b32 v171, v184, v172
	v_mul_f32_e32 v80, v76, v78
	v_cvt_pk_bf16_f32 v76, v152, v84
	v_cvt_pk_bf16_f32 v77, v85, v77
	v_lshl_add_u64 v[84:85], s[74:75], 0, v[132:133]
	s_mov_b32 s54, 0x25d49000
	v_add_co_u32_e32 v78, vcc, s54, v84
	s_mov_b32 s54, 0x27d49000
	s_nop 0
	v_addc_co_u32_e32 v79, vcc, 0, v85, vcc
	global_store_dwordx2 v[78:79], v[76:77], off
	v_add_co_u32_e32 v78, vcc, s54, v84
	v_cvt_pk_bf16_f32 v76, v179, v144
	v_cvt_pk_bf16_f32 v77, v82, v80
	s_nop 1
	v_addc_co_u32_e32 v79, vcc, 0, v85, vcc
	global_store_dwordx2 v[78:79], v[76:77], off
	s_mov_b32 s54, 0x13118000
	v_add_co_u32_e32 v80, vcc, s54, v138
	s_mov_b32 s54, 0x1311c000
	s_nop 0
	v_addc_co_u32_e32 v81, vcc, 0, v139, vcc
	s_nop 0
	v_add_co_u32_e32 v80, vcc, s54, v138
	s_mov_b32 s54, 0x13120000
	s_nop 0
	v_addc_co_u32_e32 v81, vcc, 0, v139, vcc
	s_nop 0
	v_add_co_u32_e32 v80, vcc, s54, v138
	s_mov_b32 s54, 0x13125000
	s_nop 0
	v_addc_co_u32_e32 v81, vcc, 0, v139, vcc
	v_add_co_u32_e32 v152, vcc, s54, v138
	s_nop 0
	s_nop 0
	v_addc_co_u32_e32 v153, vcc, 0, v139, vcc
	s_nop 0
	s_nop 0
	v_add_co_u32_e32 v152, vcc, 0x13128000, v138
	v_mfma_f32_16x16x32_bf16 v[80:83], v[72:75], v[8:11], 0
	s_nop 0
	v_addc_co_u32_e32 v153, vcc, 0, v139, vcc
	s_nop 0
	v_mfma_f32_16x16x32_bf16 v[80:83], v[60:63], v[24:27], v[80:83]
	v_mfma_f32_16x16x32_bf16 v[76:79], v[68:71], v[8:11], 0
	v_mfma_f32_16x16x32_bf16 v[76:79], v[64:67], v[24:27], v[76:79]
	s_nop 5
	v_add_f32_e32 v80, v56, v80
	v_mul_f32_e32 v80, 0xbfb8aa3b, v80
	v_exp_f32_e32 v80, v80
	s_nop 0
	v_add_f32_e32 v80, 1.0, v80
	v_rcp_f32_e32 v80, v80
	s_nop 0
	v_mul_f32_e32 v80, 0xc1000000, v80
	v_mul_f32_e32 v144, v185, v80
	v_add_f32_e32 v147, v144, v144
	v_cmp_nlt_f32_e32 vcc, s93, v147
	s_and_saveexec_b64 s[54:55], vcc
	s_xor_b64 s[54:55], exec, s[54:55]
	v_mul_f32_e32 v80, 0x3fb8aa3b, v147
	v_exp_f32_e32 v80, v80
	s_nop 0
	v_sub_f32_e32 v80, 1.0, v80
	s_andn2_saveexec_b64 s[54:55], s[54:55]
	v_fma_f32 v80, v147, s94, 0.5
	v_fma_f32 v80, v147, v80, 1.0
	v_mul_f32_e64 v80, v80, -v147
	s_or_b64 exec, exec, s[54:55]
	v_add_f32_e32 v81, v57, v81
	v_mul_f32_e32 v81, 0xbfb8aa3b, v81
	v_exp_f32_e32 v81, v81
	s_nop 0
	v_add_f32_e32 v81, 1.0, v81
	v_rcp_f32_e32 v81, v81
	s_nop 0
	v_mul_f32_e32 v81, 0xc1000000, v81
	v_mul_f32_e32 v81, v186, v81
	v_add_f32_e32 v189, v81, v81
	v_cmp_nlt_f32_e32 vcc, s93, v189
	s_and_saveexec_b64 s[54:55], vcc
	s_xor_b64 s[54:55], exec, s[54:55]
	v_mul_f32_e32 v147, 0x3fb8aa3b, v189
	v_exp_f32_e32 v147, v147
	s_nop 0
	v_sub_f32_e32 v147, 1.0, v147
	s_andn2_saveexec_b64 s[54:55], s[54:55]
	v_fma_f32 v147, v189, s94, 0.5
	v_fma_f32 v147, v189, v147, 1.0
	v_mul_f32_e64 v147, v147, -v189
	s_or_b64 exec, exec, s[54:55]
	v_add_f32_e32 v82, v58, v82
	v_mul_f32_e32 v82, 0xbfb8aa3b, v82
	v_exp_f32_e32 v82, v82
	s_nop 0
	v_add_f32_e32 v82, 1.0, v82
	v_rcp_f32_e32 v82, v82
	s_nop 0
	v_mul_f32_e32 v82, 0xc1000000, v82
	v_mul_f32_e32 v82, v187, v82
	v_add_f32_e32 v189, v82, v82
	v_cmp_nlt_f32_e32 vcc, s93, v189
	s_and_saveexec_b64 s[54:55], vcc
	s_xor_b64 s[54:55], exec, s[54:55]
	v_mul_f32_e32 v152, 0x3fb8aa3b, v189
	v_exp_f32_e32 v152, v152
	s_nop 0
	v_sub_f32_e32 v190, 1.0, v152
	s_andn2_saveexec_b64 s[54:55], s[54:55]
	v_fma_f32 v152, v189, s94, 0.5
	v_fma_f32 v152, v189, v152, 1.0
	v_mul_f32_e64 v190, v152, -v189
	s_or_b64 exec, exec, s[54:55]
	v_add_f32_e32 v83, v59, v83
	v_mul_f32_e32 v83, 0xbfb8aa3b, v83
	v_exp_f32_e32 v83, v83
	s_nop 0
	v_add_f32_e32 v83, 1.0, v83
	v_rcp_f32_e32 v83, v83
	s_nop 0
	v_mul_f32_e32 v83, 0xc1000000, v83
	v_mul_f32_e32 v83, v188, v83
	v_add_f32_e32 v191, v83, v83
	v_cmp_nlt_f32_e32 vcc, s93, v191
	s_and_saveexec_b64 s[54:55], vcc
	s_xor_b64 s[54:55], exec, s[54:55]
	v_mul_f32_e32 v152, 0x3fb8aa3b, v191
	v_exp_f32_e32 v152, v152
	s_nop 0
	v_sub_f32_e32 v189, 1.0, v152
	s_andn2_saveexec_b64 s[54:55], s[54:55]
	v_fma_f32 v152, v191, s94, 0.5
	v_fma_f32 v152, v191, v152, 1.0
	v_mul_f32_e64 v189, v152, -v191
	s_or_b64 exec, exec, s[54:55]
	v_add_f32_e32 v78, v34, v78
	v_mul_f32_e32 v78, 0xbfb8aa3b, v78
	s_nop 0
	s_waitcnt vmcnt(15)
	v_cndmask_b32_e64 v181, v223, 0, s[42:43]
	v_cndmask_b32_e64 v153, v222, 0, s[42:43]
	v_exp_f32_e32 v78, v78
	v_lshlrev_b32_e32 v152, 16, v153
	v_and_b32_e32 v153, 0xffff0000, v153
	v_lshlrev_b32_e32 v180, 16, v181
	v_and_b32_e32 v181, 0xffff0000, v181
	s_nop 0
	s_waitcnt vmcnt(14)
	v_cndmask_b32_e64 v191, v225, 0, s[44:45]
	v_cndmask_b32_e64 v177, v224, 0, s[44:45]
	v_pk_fma_f32 v[180:181], v[50:51], v[180:181], v[54:55]
	v_pk_fma_f32 v[152:153], v[48:49], v[152:153], v[52:53]
	v_lshlrev_b32_e32 v176, 16, v177
	v_and_b32_e32 v177, 0xffff0000, v177
	v_lshlrev_b32_e32 v192, 16, v191
	v_and_b32_e32 v193, 0xffff0000, v191
	v_pk_fma_f32 v[152:153], v[44:45], v[176:177], v[152:153]
	v_pk_fma_f32 v[176:177], v[46:47], v[192:193], v[180:181]
	s_nop 0
	s_waitcnt vmcnt(13)
	v_cndmask_b32_e64 v181, v227, 0, s[46:47]
	v_cndmask_b32_e64 v179, v226, 0, s[46:47]
	v_lshlrev_b32_e32 v178, 16, v179
	v_and_b32_e32 v179, 0xffff0000, v179
	v_add_f32_e32 v78, 1.0, v78
	v_add_f32_e32 v79, v35, v79
	v_add_f32_e32 v77, v33, v77
	v_pk_fma_f32 v[152:153], v[40:41], v[178:179], v[152:153]
	s_nop 0
	s_waitcnt vmcnt(12)
	v_cndmask_b32_e64 v179, v228, 0, s[64:65]
	v_rcp_f32_e32 v78, v78
	v_sqrt_f32_e32 v182, v190
	v_mul_f32_e32 v79, 0xbfb8aa3b, v79
	v_mul_f32_e32 v77, 0xbfb8aa3b, v77
	v_lshlrev_b32_e32 v180, 16, v181
	v_and_b32_e32 v181, 0xffff0000, v181
	v_exp_f32_e32 v79, v79
	v_exp_f32_e32 v77, v77
	v_pk_fma_f32 v[176:177], v[42:43], v[180:181], v[176:177]
	v_cndmask_b32_e64 v181, v229, 0, s[64:65]
	v_lshlrev_b32_e32 v180, 16, v181
	v_and_b32_e32 v181, 0xffff0000, v181
	v_add_f32_e32 v76, v32, v76
	v_pk_fma_f32 v[176:177], v[38:39], v[180:181], v[176:177]
	v_mul_f32_e32 v78, v78, v182
	v_mul_f32_e32 v76, 0xbfb8aa3b, v76
	v_lshlrev_b32_e32 v178, 16, v179
	v_and_b32_e32 v179, 0xffff0000, v179
	v_mul_f32_e32 v176, v176, v78
	v_add_f32_e32 v78, 1.0, v79
	v_add_f32_e32 v77, 1.0, v77
	v_exp_f32_e32 v76, v76
	v_pk_fma_f32 v[152:153], v[36:37], v[178:179], v[152:153]
	v_rcp_f32_e32 v178, v78
	v_rcp_f32_e32 v77, v77
	v_sqrt_f32_e32 v78, v147
	v_add_f32_e32 v76, 1.0, v76
	v_rcp_f32_e32 v76, v76
	v_mul_f32_e32 v79, 0x3fb8aa3b, v83
	v_mul_f32_e32 v77, v77, v78
	v_sqrt_f32_e32 v78, v80
	v_mul_f32_e32 v179, v153, v77
	v_mul_f32_e32 v77, 0x3fb8aa3b, v82
	s_waitcnt lgkmcnt(6)
	v_pk_mul_f32 v[82:83], v[86:87], v[164:165]
	v_sqrt_f32_e32 v86, v189
	v_mul_f32_e32 v87, 0x3fb8aa3b, v144
	v_mul_f32_e32 v76, v76, v78
	v_exp_f32_e32 v87, v87
	v_exp_f32_e32 v147, v79
	v_exp_f32_e32 v153, v77
	v_mul_f32_e32 v180, v152, v76
	v_mul_f32_e32 v76, 0x3fb8aa3b, v81
	v_exp_f32_e32 v152, v76
	v_mul_f32_e32 v86, v178, v86
	s_waitcnt lgkmcnt(1)
	v_pk_mul_f32 v[78:79], v[140:141], v[168:169]
	s_waitcnt lgkmcnt(0)
	v_pk_fma_f32 v[76:77], v[142:143], v[168:169], v[170:171]
	v_mul_f32_e32 v144, v177, v86
	v_mov_b32_e32 v86, 1.0
	v_mov_b32_e32 v140, v145
	v_mov_b32_e32 v141, v145
	v_mov_b32_e32 v142, v145
	v_mov_b32_dpp v86, v87 row_shr:1 row_mask:0xf bank_mask:0xf
	v_mov_b32_dpp v140, v180 row_shr:1 row_mask:0xf bank_mask:0xf
	v_mov_b32_dpp v141, v176 row_shr:1 row_mask:0xf bank_mask:0xf
	v_mov_b32_dpp v142, v144 row_shr:1 row_mask:0xf bank_mask:0xf
	v_fmac_f32_e32 v180, v87, v140
	v_mul_f32_e32 v86, v87, v86
	v_mov_b32_e32 v87, 1.0
	v_mov_b32_e32 v140, v145
	v_fmac_f32_e32 v176, v153, v141
	v_mov_b32_e32 v141, 1.0
	v_fmac_f32_e32 v144, v147, v142
	v_mov_b32_e32 v142, 1.0
	v_mov_b32_e32 v143, v145
	v_mov_b32_dpp v87, v152 row_shr:1 row_mask:0xf bank_mask:0xf
	v_mov_b32_dpp v140, v179 row_shr:1 row_mask:0xf bank_mask:0xf
	v_mov_b32_dpp v141, v147 row_shr:1 row_mask:0xf bank_mask:0xf
	v_mov_b32_dpp v142, v86 row_shr:2 row_mask:0xf bank_mask:0xf
	v_mov_b32_dpp v143, v180 row_shr:2 row_mask:0xf bank_mask:0xf
	v_fmac_f32_e32 v179, v152, v140
	v_mul_f32_e32 v87, v152, v87
	v_mov_b32_e32 v140, 1.0
	v_mul_f32_e32 v141, v147, v141
	v_fmac_f32_e32 v180, v86, v143
	v_mul_f32_e32 v147, v86, v142
	v_mov_b32_e32 v86, 1.0
	v_mov_b32_dpp v140, v153 row_shr:1 row_mask:0xf bank_mask:0xf
	v_mul_f32_e32 v140, v153, v140
	v_mov_b32_dpp v86, v87 row_shr:2 row_mask:0xf bank_mask:0xf
	v_mul_f32_e32 v168, v87, v86
	v_mov_b32_e32 v86, 1.0
	v_mov_b32_e32 v142, v145
	v_pk_fma_f32 v[80:81], v[162:163], v[164:165], v[166:167]
	v_mov_b32_dpp v86, v140 row_shr:2 row_mask:0xf bank_mask:0xf
	v_mul_f32_e32 v169, v140, v86
	v_mov_b32_e32 v86, 1.0
	v_mov_b32_dpp v142, v179 row_shr:2 row_mask:0xf bank_mask:0xf
	v_fmac_f32_e32 v179, v87, v142
	v_mov_b32_dpp v86, v141 row_shr:2 row_mask:0xf bank_mask:0xf
	v_mul_f32_e32 v170, v141, v86
	v_mov_b32_e32 v86, v145
	v_mov_b32_e32 v87, v145
	v_mov_b32_e32 v163, v145
	v_mov_b32_dpp v86, v180 row_shr:4 row_mask:0xf bank_mask:0xf
	v_fmac_f32_e32 v180, v147, v86
	v_mov_b32_e32 v86, v145
	v_mov_b32_dpp v87, v176 row_shr:2 row_mask:0xf bank_mask:0xf
	v_fmac_f32_e32 v176, v140, v87
	v_mov_b32_dpp v86, v179 row_shr:4 row_mask:0xf bank_mask:0xf
	v_mov_b32_e32 v87, v145
	v_fmac_f32_e32 v179, v168, v86
	v_mov_b32_e32 v86, v145
	v_mov_b32_dpp v87, v144 row_shr:2 row_mask:0xf bank_mask:0xf
	v_fmac_f32_e32 v144, v141, v87
	v_mov_b32_dpp v86, v176 row_shr:4 row_mask:0xf bank_mask:0xf
	v_fmac_f32_e32 v176, v169, v86
	v_mov_b32_e32 v86, v145
	v_mov_b32_e32 v87, 1.0
	s_nop 0
	s_waitcnt vmcnt(10)
	v_lshlrev_b32_e32 v140, 16, v232
	v_mov_b32_dpp v86, v144 row_shr:4 row_mask:0xf bank_mask:0xf
	v_mov_b32_dpp v87, v147 row_shr:4 row_mask:0xf bank_mask:0xf
	v_fmac_f32_e32 v144, v170, v86
	v_lshlrev_b32_e32 v86, 16, v230
	v_mul_f32_e32 v140, 0xbfb8aa3b, v140
	v_exp_f32_e32 v162, v140
	v_pk_mul_f32 v[140:141], v[146:147], v[86:87]
	v_mul_f32_e32 v87, 0x3d372713, v86
	v_mul_f32_e32 v87, v87, v86
	v_fmac_f32_e32 v86, v87, v86
	v_mul_f32_e32 v86, 0x3f4c422a, v86
	v_add_f32_e32 v86, v86, v86
	v_mul_f32_e32 v86, 0x3fb8aa3b, v86
	v_exp_f32_e32 v86, v86
	v_add_f32_e32 v87, 1.0, v162
	v_rcp_f32_e32 v162, v87
	v_mov_b32_e32 v87, 1.0
	v_add_f32_e32 v86, 1.0, v86
	v_rcp_f32_e32 v86, v86
	v_mov_b32_e32 v143, 1.0
	v_mov_b32_dpp v163, v180 row_shr:8 row_mask:0xf bank_mask:0xf
	v_mov_b32_dpp v87, v141 row_shr:8 row_mask:0xf bank_mask:0xf
	v_fma_f32 v86, v86, -2.0, 1.0
	v_add_f32_e32 v86, 1.0, v86
	v_mov_b32_dpp v143, v168 row_shr:4 row_mask:0xf bank_mask:0xf
	v_and_b32_e32 v142, 0xffff0000, v230
	v_fmac_f32_e32 v180, v141, v163
	v_pk_mul_f32 v[166:167], v[140:141], v[86:87]
	v_mov_b32_e32 v163, v80
	v_mov_b32_e32 v147, v168
	ds_bpermute_b32 v86, v184, v167
	v_mul_f32_e32 v87, v82, v167
	v_pk_mul_f32 v[162:163], v[162:163], v[166:167]
	v_pk_mul_f32 v[166:167], v[146:147], v[142:143]
	v_mul_f32_e32 v143, 0x3d372713, v142
	v_mul_f32_e32 v143, v143, v142
	v_fmac_f32_e32 v142, v143, v142
	v_and_b32_e32 v172, 0xffff0000, v232
	v_add_f32_e32 v141, v163, v180
	v_mul_f32_e32 v142, 0x3f4c422a, v142
	v_lshlrev_b32_e32 v152, 16, v231
	v_and_b32_e32 v164, 0xffff0000, v231
	v_mul_f32_e32 v175, v162, v141
	v_mul_f32_e32 v141, 0xbfb8aa3b, v172
	v_add_f32_e32 v142, v142, v142
	v_exp_f32_e32 v141, v141
	v_mul_f32_e32 v142, 0x3fb8aa3b, v142
	v_exp_f32_e32 v143, v142
	v_mul_f32_e32 v168, v162, v87
	v_add_f32_e32 v87, 1.0, v141
	v_rcp_f32_e32 v142, v87
	v_add_f32_e32 v87, 1.0, v143
	v_rcp_f32_e32 v87, v87
	v_mov_b32_e32 v163, 1.0
	v_mov_b32_e32 v153, 1.0
	v_mov_b32_e32 v143, v81
	v_fma_f32 v87, v87, -2.0, 1.0
	v_mov_b32_dpp v163, v167 row_shr:8 row_mask:0xf bank_mask:0xf
	v_add_f32_e32 v162, 1.0, v87
	v_mov_b32_dpp v153, v169 row_shr:4 row_mask:0xf bank_mask:0xf
	v_pk_mul_f32 v[162:163], v[166:167], v[162:163]
	v_mov_b32_e32 v147, v169
	v_mov_b32_e32 v171, v145
	ds_bpermute_b32 v87, v184, v163
	v_mul_f32_e32 v166, v83, v163
	v_pk_mul_f32 v[142:143], v[142:143], v[162:163]
	v_pk_mul_f32 v[162:163], v[146:147], v[152:153]
	v_mul_f32_e32 v147, 0x3d372713, v152
	v_mov_b32_dpp v171, v179 row_shr:8 row_mask:0xf bank_mask:0xf
	v_mul_f32_e32 v147, v147, v152
	v_fmac_f32_e32 v179, v167, v171
	v_fmac_f32_e32 v152, v147, v152
	v_lshlrev_b32_e32 v174, 16, v233
	v_add_f32_e32 v143, v143, v179
	v_mul_f32_e32 v147, 0x3f4c422a, v152
	v_mul_f32_e32 v171, v142, v143
	v_mul_f32_e32 v143, 0xbfb8aa3b, v174
	v_add_f32_e32 v147, v147, v147
	v_exp_f32_e32 v143, v143
	v_mul_f32_e32 v147, 0x3fb8aa3b, v147
	v_exp_f32_e32 v147, v147
	v_mul_f32_e32 v169, v142, v166
	v_add_f32_e32 v142, 1.0, v143
	v_rcp_f32_e32 v152, v142
	v_add_f32_e32 v142, 1.0, v147
	v_rcp_f32_e32 v142, v142
	v_mov_b32_e32 v143, 1.0
	v_mov_b32_e32 v177, v145
	v_mov_b32_e32 v153, v76
	v_fma_f32 v142, v142, -2.0, 1.0
	v_mov_b32_dpp v143, v163 row_shr:8 row_mask:0xf bank_mask:0xf
	v_add_f32_e32 v142, 1.0, v142
	v_mov_b32_dpp v177, v176 row_shr:8 row_mask:0xf bank_mask:0xf
	v_pk_mul_f32 v[166:167], v[162:163], v[142:143]
	v_fmac_f32_e32 v176, v163, v177
	v_pk_mul_f32 v[152:153], v[152:153], v[166:167]
	v_and_b32_e32 v173, 0xffff0000, v233
	v_add_f32_e32 v147, v153, v176
	v_mov_b32_e32 v165, 1.0
	v_mul_f32_e32 v172, v152, v147
	v_mul_f32_e32 v147, 0xbfb8aa3b, v173
	v_mov_b32_dpp v165, v170 row_shr:4 row_mask:0xf bank_mask:0xf
	v_exp_f32_e32 v153, v147
	v_mov_b32_e32 v147, v170
	ds_bpermute_b32 v142, v184, v167
	v_mul_f32_e32 v143, v78, v167
	v_pk_mul_f32 v[166:167], v[146:147], v[164:165]
	v_mul_f32_e32 v147, 0x3d372713, v164
	v_mul_f32_e32 v147, v147, v164
	v_fmac_f32_e32 v164, v147, v164
	v_mul_f32_e32 v147, 0x3f4c422a, v164
	v_add_f32_e32 v147, v147, v147
	v_mul_f32_e32 v147, 0x3fb8aa3b, v147
	v_exp_f32_e32 v147, v147
	v_mul_f32_e32 v170, v152, v143
	v_add_f32_e32 v143, 1.0, v153
	v_rcp_f32_e32 v152, v143
	v_add_f32_e32 v143, 1.0, v147
	v_rcp_f32_e32 v143, v143
	v_mov_b32_e32 v178, v145
	v_mov_b32_e32 v165, 1.0
	ds_bpermute_b32 v140, v184, v180
	v_fma_f32 v143, v143, -2.0, 1.0
	v_mov_b32_dpp v178, v144 row_shr:8 row_mask:0xf bank_mask:0xf
	v_mov_b32_dpp v165, v167 row_shr:8 row_mask:0xf bank_mask:0xf
	v_add_f32_e32 v164, 1.0, v143
	v_fmac_f32_e32 v144, v167, v178
	v_pk_mul_f32 v[164:165], v[166:167], v[164:165]
	ds_bpermute_b32 v141, v184, v179
	ds_bpermute_b32 v162, v184, v176
	ds_bpermute_b32 v143, v184, v165
	ds_bpermute_b32 v163, v184, v144
	v_mov_b32_e32 v153, v77
	s_mov_b32 s54, 0x25d51000
	v_pk_mul_f32 v[152:153], v[152:153], v[164:165]
	v_add_co_u32_e32 v164, vcc, s54, v84
	v_mul_f32_e32 v147, v79, v165
	v_add_f32_e32 v144, v153, v144
	v_addc_co_u32_e32 v165, vcc, 0, v85, vcc
	s_mov_b32 s54, 0x27d51000
	v_mul_f32_e32 v144, v152, v144
	v_mul_f32_e32 v147, v152, v147
	v_cvt_pk_bf16_f32 v152, v175, v171
	v_cvt_pk_bf16_f32 v153, v172, v144
	global_store_dwordx2 v[164:165], v[152:153], off
	v_add_co_u32_e32 v164, vcc, s54, v84
	v_cvt_pk_bf16_f32 v152, v168, v169
	v_cvt_pk_bf16_f32 v153, v170, v147
	s_nop 1
	v_addc_co_u32_e32 v165, vcc, 0, v85, vcc
	global_store_dwordx2 v[164:165], v[152:153], off
	s_mov_b32 s54, 0x1315a000
	v_add_co_u32_e32 v152, vcc, s54, v138
	s_mov_b32 s54, 0x1315e000
	s_nop 0
	v_addc_co_u32_e32 v153, vcc, 0, v139, vcc
	v_add_co_u32_e32 v164, vcc, s54, v138
	s_mov_b32 s54, 0x13162000
	s_nop 0
	v_addc_co_u32_e32 v165, vcc, 0, v139, vcc
	v_add_co_u32_e32 v166, vcc, s54, v138
	s_mov_b32 s54, 0x13167000
	s_nop 0
	v_addc_co_u32_e32 v167, vcc, 0, v139, vcc
	v_add_co_u32_e32 v174, vcc, s54, v138
	v_mfma_f32_16x16x32_bf16 v[72:75], v[72:75], v[12:15], 0
	s_nop 0
	v_addc_co_u32_e32 v175, vcc, 0, v139, vcc
	s_nop 0
	s_nop 0
	s_nop 0
	s_nop 0
	s_nop 0
	v_add_co_u32_e32 v138, vcc, 0x1316a000, v138
	v_mfma_f32_16x16x32_bf16 v[72:75], v[60:63], v[28:31], v[72:75]
	s_nop 0
	v_addc_co_u32_e32 v139, vcc, 0, v139, vcc
	s_nop 0
	s_nop 0
	s_nop 0
	s_nop 2
	v_add_f32_e32 v56, v56, v72
	v_mul_f32_e32 v56, 0xbfb8aa3b, v56
	v_exp_f32_e32 v56, v56
	v_mfma_f32_16x16x32_bf16 v[60:63], v[68:71], v[12:15], 0
	v_add_f32_e32 v56, 1.0, v56
	v_rcp_f32_e32 v56, v56
	v_mfma_f32_16x16x32_bf16 v[60:63], v[64:67], v[28:31], v[60:63]
	v_mul_f32_e32 v56, 0xc1000000, v56
	v_mul_f32_e32 v56, v185, v56
	v_add_f32_e32 v65, v56, v56
	v_cmp_nlt_f32_e32 vcc, s93, v65
	s_and_saveexec_b64 s[54:55], vcc
	s_xor_b64 s[54:55], exec, s[54:55]
	v_mul_f32_e32 v64, 0x3fb8aa3b, v65
	v_exp_f32_e32 v64, v64
	s_nop 0
	v_sub_f32_e32 v64, 1.0, v64
	s_andn2_saveexec_b64 s[54:55], s[54:55]
	v_fma_f32 v64, v65, s94, 0.5
	v_fma_f32 v64, v65, v64, 1.0
	v_mul_f32_e64 v64, v64, -v65
	s_or_b64 exec, exec, s[54:55]
	v_add_f32_e32 v57, v57, v73
	v_mul_f32_e32 v57, 0xbfb8aa3b, v57
	v_exp_f32_e32 v57, v57
	s_nop 0
	v_add_f32_e32 v57, 1.0, v57
	v_rcp_f32_e32 v57, v57
	s_nop 0
	v_mul_f32_e32 v57, 0xc1000000, v57
	v_mul_f32_e32 v57, v186, v57
	v_add_f32_e32 v66, v57, v57
	v_cmp_nlt_f32_e32 vcc, s93, v66
	s_and_saveexec_b64 s[54:55], vcc
	s_xor_b64 s[54:55], exec, s[54:55]
	v_mul_f32_e32 v65, 0x3fb8aa3b, v66
	v_exp_f32_e32 v65, v65
	s_nop 0
	v_sub_f32_e32 v65, 1.0, v65
	s_andn2_saveexec_b64 s[54:55], s[54:55]
	v_fma_f32 v65, v66, s94, 0.5
	v_fma_f32 v65, v66, v65, 1.0
	v_mul_f32_e64 v65, v65, -v66
	s_or_b64 exec, exec, s[54:55]
	v_add_f32_e32 v58, v58, v74
	v_mul_f32_e32 v58, 0xbfb8aa3b, v58
	v_exp_f32_e32 v58, v58
	s_nop 0
	v_add_f32_e32 v58, 1.0, v58
	v_rcp_f32_e32 v58, v58
	s_nop 0
	v_mul_f32_e32 v58, 0xc1000000, v58
	v_mul_f32_e32 v58, v187, v58
	v_add_f32_e32 v67, v58, v58
	v_cmp_nlt_f32_e32 vcc, s93, v67
	s_and_saveexec_b64 s[54:55], vcc
	s_xor_b64 s[54:55], exec, s[54:55]
	v_mul_f32_e32 v66, 0x3fb8aa3b, v67
	v_exp_f32_e32 v66, v66
	s_nop 0
	v_sub_f32_e32 v66, 1.0, v66
	s_andn2_saveexec_b64 s[54:55], s[54:55]
	v_fma_f32 v66, v67, s94, 0.5
	v_fma_f32 v66, v67, v66, 1.0
	v_mul_f32_e64 v66, v66, -v67
	s_or_b64 exec, exec, s[54:55]
	v_add_f32_e32 v59, v59, v75
	v_mul_f32_e32 v59, 0xbfb8aa3b, v59
	v_exp_f32_e32 v59, v59
	s_nop 0
	v_add_f32_e32 v59, 1.0, v59
	v_rcp_f32_e32 v59, v59
	s_nop 0
	v_mul_f32_e32 v59, 0xc1000000, v59
	v_mul_f32_e32 v67, v188, v59
	v_add_f32_e32 v68, v67, v67
	v_cmp_nlt_f32_e32 vcc, s93, v68
	s_and_saveexec_b64 s[54:55], vcc
	s_xor_b64 s[54:55], exec, s[54:55]
	v_mul_f32_e32 v59, 0x3fb8aa3b, v68
	v_exp_f32_e32 v59, v59
	s_nop 0
	v_sub_f32_e32 v59, 1.0, v59
	s_andn2_saveexec_b64 s[54:55], s[54:55]
	v_fma_f32 v59, v68, s94, 0.5
	v_fma_f32 v59, v68, v59, 1.0
	v_mul_f32_e64 v59, v59, -v68
	s_or_b64 exec, exec, s[54:55]
	v_add_f32_e32 v34, v34, v62
	s_nop 0
	s_waitcnt vmcnt(11)
	v_cndmask_b32_e64 v69, v234, 0, s[48:49]
	v_mul_f32_e32 v34, 0xbfb8aa3b, v34
	v_lshlrev_b32_e32 v68, 16, v69
	v_and_b32_e32 v69, 0xffff0000, v69
	v_exp_f32_e32 v34, v34
	v_cndmask_b32_e64 v71, v235, 0, s[48:49]
	v_pk_fma_f32 v[48:49], v[48:49], v[68:69], v[52:53]
	s_nop 0
	s_waitcnt vmcnt(10)
	v_cndmask_b32_e64 v53, v236, 0, s[50:51]
	v_lshlrev_b32_e32 v70, 16, v71
	v_and_b32_e32 v71, 0xffff0000, v71
	v_lshlrev_b32_e32 v52, 16, v53
	v_and_b32_e32 v53, 0xffff0000, v53
	v_pk_fma_f32 v[50:51], v[50:51], v[70:71], v[54:55]
	v_cndmask_b32_e64 v55, v237, 0, s[50:51]
	v_pk_fma_f32 v[44:45], v[44:45], v[52:53], v[48:49]
	s_nop 0
	s_waitcnt vmcnt(9)
	v_cndmask_b32_e64 v49, v238, 0, s[52:53]
	v_lshlrev_b32_e32 v54, 16, v55
	v_and_b32_e32 v55, 0xffff0000, v55
	v_lshlrev_b32_e32 v48, 16, v49
	v_and_b32_e32 v49, 0xffff0000, v49
	v_add_f32_e32 v34, 1.0, v34
	v_add_f32_e32 v35, v35, v63
	v_add_f32_e32 v33, v33, v61
	v_pk_fma_f32 v[46:47], v[46:47], v[54:55], v[50:51]
	v_cndmask_b32_e64 v51, v239, 0, s[52:53]
	v_pk_fma_f32 v[40:41], v[40:41], v[48:49], v[44:45]
	v_rcp_f32_e32 v34, v34
	v_sqrt_f32_e32 v48, v66
	v_mul_f32_e32 v35, 0xbfb8aa3b, v35
	v_mul_f32_e32 v33, 0xbfb8aa3b, v33
	v_lshlrev_b32_e32 v50, 16, v51
	v_and_b32_e32 v51, 0xffff0000, v51
	v_exp_f32_e32 v35, v35
	v_exp_f32_e32 v33, v33
	v_pk_fma_f32 v[42:43], v[42:43], v[50:51], v[46:47]
	s_nop 0
	s_waitcnt vmcnt(8)
	v_cndmask_b32_e64 v47, v243, 0, s[64:65]
	v_cndmask_b32_e64 v45, v242, 0, s[64:65]
	v_lshlrev_b32_e32 v44, 16, v45
	v_and_b32_e32 v45, 0xffff0000, v45
	v_lshlrev_b32_e32 v46, 16, v47
	v_and_b32_e32 v47, 0xffff0000, v47
	v_add_f32_e32 v32, v32, v60
	v_pk_fma_f32 v[36:37], v[36:37], v[44:45], v[40:41]
	v_pk_fma_f32 v[40:41], v[38:39], v[46:47], v[42:43]
	v_mul_f32_e32 v34, v34, v48
	v_mul_f32_e32 v32, 0xbfb8aa3b, v32
	v_mul_f32_e32 v54, v40, v34
	v_add_f32_e32 v34, 1.0, v35
	v_add_f32_e32 v33, 1.0, v33
	v_exp_f32_e32 v32, v32
	v_rcp_f32_e32 v40, v34
	v_rcp_f32_e32 v33, v33
	v_sqrt_f32_e32 v34, v65
	v_add_f32_e32 v32, 1.0, v32
	v_rcp_f32_e32 v32, v32
	v_sqrt_f32_e32 v45, v59
	v_mul_f32_e32 v33, v33, v34
	v_sqrt_f32_e32 v34, v64
	v_mul_f32_e32 v46, 0x3fb8aa3b, v56
	v_mul_f32_e32 v55, v37, v33
	v_mul_f32_e32 v33, 0x3fb8aa3b, v58
	v_mul_f32_e32 v32, v32, v34
	v_mul_f32_e32 v58, v36, v32
	v_mul_f32_e32 v32, 0x3fb8aa3b, v57
	v_exp_f32_e32 v46, v46
	v_exp_f32_e32 v44, v32
	v_mul_f32_e32 v40, v40, v45
	v_mul_f32_e32 v56, v41, v40
	v_mov_b32_e32 v41, v145
	v_exp_f32_e32 v43, v33
	v_mul_f32_e32 v35, 0x3fb8aa3b, v67
	v_mov_b32_dpp v41, v58 row_shr:1 row_mask:0xf bank_mask:0xf
	v_fmac_f32_e32 v58, v46, v41
	v_mov_b32_e32 v41, 1.0
	v_mov_b32_e32 v45, v145
	v_exp_f32_e32 v42, v35
	v_mov_b32_dpp v41, v44 row_shr:1 row_mask:0xf bank_mask:0xf
	v_mov_b32_dpp v45, v55 row_shr:1 row_mask:0xf bank_mask:0xf
	v_fmac_f32_e32 v55, v44, v45
	v_mul_f32_e32 v41, v44, v41
	v_mov_b32_e32 v44, 1.0
	v_mov_b32_e32 v45, v145
	v_mov_b32_e32 v40, 1.0
	v_mov_b32_dpp v44, v43 row_shr:1 row_mask:0xf bank_mask:0xf
	v_mov_b32_dpp v45, v54 row_shr:1 row_mask:0xf bank_mask:0xf
	v_fmac_f32_e32 v54, v43, v45
	v_mul_f32_e32 v43, v43, v44
	v_mov_b32_e32 v44, 1.0
	v_mov_b32_e32 v45, v145
	v_mov_b32_dpp v40, v46 row_shr:1 row_mask:0xf bank_mask:0xf
	v_mov_b32_dpp v44, v42 row_shr:1 row_mask:0xf bank_mask:0xf
	v_mov_b32_dpp v45, v56 row_shr:1 row_mask:0xf bank_mask:0xf
	v_mul_f32_e32 v40, v46, v40
	v_fmac_f32_e32 v56, v42, v45
	v_mul_f32_e32 v42, v42, v44
	v_mov_b32_e32 v44, 1.0
	v_mov_b32_e32 v45, v145
	v_mov_b32_e32 v51, v145
	v_mov_b32_dpp v44, v40 row_shr:2 row_mask:0xf bank_mask:0xf
	v_mov_b32_dpp v45, v58 row_shr:2 row_mask:0xf bank_mask:0xf
	v_fmac_f32_e32 v58, v40, v45
	v_mul_f32_e32 v147, v40, v44
	v_mov_b32_e32 v40, 1.0
	v_mov_b32_e32 v44, v145
	s_waitcnt lgkmcnt(3)
	v_pk_fma_f32 v[38:39], v[80:81], v[86:87], v[140:141]
	v_mov_b32_dpp v40, v41 row_shr:2 row_mask:0xf bank_mask:0xf
	v_mul_f32_e32 v57, v41, v40
	v_mov_b32_e32 v40, 1.0
	v_mov_b32_dpp v44, v55 row_shr:2 row_mask:0xf bank_mask:0xf
	v_fmac_f32_e32 v55, v41, v44
	v_mov_b32_dpp v40, v43 row_shr:2 row_mask:0xf bank_mask:0xf
	v_mul_f32_e32 v59, v43, v40
	v_mov_b32_e32 v40, 1.0
	v_mov_b32_e32 v41, v145
	v_mov_b32_e32 v45, 1.0
	v_mov_b32_dpp v40, v42 row_shr:2 row_mask:0xf bank_mask:0xf
	v_mul_f32_e32 v60, v42, v40
	v_mov_b32_e32 v40, v145
	v_mov_b32_dpp v41, v54 row_shr:2 row_mask:0xf bank_mask:0xf
	v_fmac_f32_e32 v54, v43, v41
	v_mov_b32_dpp v40, v58 row_shr:4 row_mask:0xf bank_mask:0xf
	v_fmac_f32_e32 v58, v147, v40
	v_mov_b32_e32 v40, v145
	v_mov_b32_e32 v41, v145
	v_mov_b32_dpp v51, v58 row_shr:8 row_mask:0xf bank_mask:0xf
	v_mov_b32_dpp v40, v55 row_shr:4 row_mask:0xf bank_mask:0xf
	v_fmac_f32_e32 v55, v57, v40
	v_mov_b32_e32 v40, v145
	v_mov_b32_dpp v41, v56 row_shr:2 row_mask:0xf bank_mask:0xf
	v_fmac_f32_e32 v56, v42, v41
	v_mov_b32_dpp v40, v54 row_shr:4 row_mask:0xf bank_mask:0xf
	v_fmac_f32_e32 v54, v59, v40
	v_mov_b32_e32 v40, v145
	v_mov_b32_e32 v41, 1.0
	s_nop 0
	s_waitcnt vmcnt(6)
	v_lshlrev_b32_e32 v42, 16, v246
	v_mov_b32_dpp v40, v56 row_shr:4 row_mask:0xf bank_mask:0xf
	v_mov_b32_dpp v41, v147 row_shr:4 row_mask:0xf bank_mask:0xf
	v_fmac_f32_e32 v56, v60, v40
	v_lshlrev_b32_e32 v40, 16, v244
	v_mul_f32_e32 v42, 0xbfb8aa3b, v42
	v_exp_f32_e32 v50, v42
	v_pk_mul_f32 v[42:43], v[146:147], v[40:41]
	v_mul_f32_e32 v41, 0x3d372713, v40
	v_mul_f32_e32 v41, v41, v40
	v_fmac_f32_e32 v40, v41, v40
	v_mul_f32_e32 v40, 0x3f4c422a, v40
	v_add_f32_e32 v40, v40, v40
	v_mul_f32_e32 v40, 0x3fb8aa3b, v40
	v_exp_f32_e32 v40, v40
	v_add_f32_e32 v41, 1.0, v50
	v_rcp_f32_e32 v50, v41
	v_mov_b32_e32 v41, 1.0
	v_add_f32_e32 v40, 1.0, v40
	v_rcp_f32_e32 v40, v40
	v_mov_b32_dpp v41, v43 row_shr:8 row_mask:0xf bank_mask:0xf
	v_pk_mul_f32 v[34:35], v[82:83], v[86:87]
	v_mov_b32_dpp v45, v57 row_shr:4 row_mask:0xf bank_mask:0xf
	v_fma_f32 v40, v40, -2.0, 1.0
	v_add_f32_e32 v40, 1.0, v40
	v_and_b32_e32 v44, 0xffff0000, v244
	v_fmac_f32_e32 v58, v43, v51
	v_pk_mul_f32 v[52:53], v[42:43], v[40:41]
	v_mov_b32_e32 v51, v38
	v_mov_b32_e32 v147, v57
	ds_bpermute_b32 v40, v184, v53
	v_mul_f32_e32 v41, v34, v53
	v_pk_mul_f32 v[50:51], v[50:51], v[52:53]
	v_pk_mul_f32 v[52:53], v[146:147], v[44:45]
	v_mul_f32_e32 v45, 0x3d372713, v44
	v_mul_f32_e32 v45, v45, v44
	v_fmac_f32_e32 v44, v45, v44
	v_and_b32_e32 v64, 0xffff0000, v246
	v_add_f32_e32 v43, v51, v58
	v_mul_f32_e32 v44, 0x3f4c422a, v44
	ds_bpermute_b32 v42, v184, v58
	v_mul_f32_e32 v58, v50, v43
	v_mul_f32_e32 v43, 0xbfb8aa3b, v64
	v_add_f32_e32 v44, v44, v44
	v_exp_f32_e32 v43, v43
	v_mul_f32_e32 v44, 0x3fb8aa3b, v44
	v_exp_f32_e32 v45, v44
	v_mul_f32_e32 v57, v50, v41
	v_add_f32_e32 v41, 1.0, v43
	v_rcp_f32_e32 v44, v41
	v_add_f32_e32 v41, 1.0, v45
	v_rcp_f32_e32 v41, v41
	v_mov_b32_e32 v51, 1.0
	v_mov_b32_e32 v47, 1.0
	v_lshlrev_b32_e32 v46, 16, v245
	v_fma_f32 v41, v41, -2.0, 1.0
	v_mov_b32_dpp v51, v53 row_shr:8 row_mask:0xf bank_mask:0xf
	v_add_f32_e32 v50, 1.0, v41
	v_mov_b32_dpp v47, v59 row_shr:4 row_mask:0xf bank_mask:0xf
	v_pk_mul_f32 v[50:51], v[52:53], v[50:51]
	v_mov_b32_e32 v45, v39
	v_mov_b32_e32 v147, v59
	v_mov_b32_e32 v61, v145
	ds_bpermute_b32 v41, v184, v51
	v_mul_f32_e32 v52, v35, v51
	v_pk_mul_f32 v[44:45], v[44:45], v[50:51]
	v_pk_mul_f32 v[50:51], v[146:147], v[46:47]
	v_mul_f32_e32 v47, 0x3d372713, v46
	v_mov_b32_dpp v61, v55 row_shr:8 row_mask:0xf bank_mask:0xf
	v_mul_f32_e32 v47, v47, v46
	v_fmac_f32_e32 v55, v53, v61
	v_fmac_f32_e32 v46, v47, v46
	v_lshlrev_b32_e32 v65, 16, v247
	v_add_f32_e32 v45, v45, v55
	v_mul_f32_e32 v46, 0x3f4c422a, v46
	ds_bpermute_b32 v43, v184, v55
	v_mul_f32_e32 v55, v44, v45
	v_mul_f32_e32 v45, 0xbfb8aa3b, v65
	v_add_f32_e32 v46, v46, v46
	v_exp_f32_e32 v45, v45
	v_mul_f32_e32 v46, 0x3fb8aa3b, v46
	v_exp_f32_e32 v46, v46
	v_mul_f32_e32 v59, v44, v52
	v_add_f32_e32 v44, 1.0, v45
	v_rcp_f32_e32 v52, v44
	v_add_f32_e32 v44, 1.0, v46
	v_rcp_f32_e32 v44, v44
	v_mov_b32_e32 v62, v145
	v_mov_b32_e32 v45, 1.0
	s_waitcnt lgkmcnt(4)
	v_pk_fma_f32 v[36:37], v[76:77], v[142:143], v[162:163]
	v_fma_f32 v44, v44, -2.0, 1.0
	v_mov_b32_e32 v49, 1.0
	v_mov_b32_dpp v62, v54 row_shr:8 row_mask:0xf bank_mask:0xf
	v_mov_b32_dpp v45, v51 row_shr:8 row_mask:0xf bank_mask:0xf
	v_add_f32_e32 v44, 1.0, v44
	v_pk_mul_f32 v[32:33], v[78:79], v[142:143]
	v_mov_b32_dpp v49, v60 row_shr:4 row_mask:0xf bank_mask:0xf
	v_and_b32_e32 v48, 0xffff0000, v245
	v_fmac_f32_e32 v54, v51, v62
	v_pk_mul_f32 v[50:51], v[50:51], v[44:45]
	v_mov_b32_e32 v53, v36
	v_mov_b32_e32 v147, v60
	ds_bpermute_b32 v44, v184, v51
	v_mul_f32_e32 v45, v32, v51
	v_pk_mul_f32 v[50:51], v[52:53], v[50:51]
	v_pk_mul_f32 v[52:53], v[146:147], v[48:49]
	v_mul_f32_e32 v49, 0x3d372713, v48
	v_mul_f32_e32 v49, v49, v48
	v_fmac_f32_e32 v48, v49, v48
	v_and_b32_e32 v66, 0xffff0000, v247
	v_add_f32_e32 v47, v51, v54
	v_mul_f32_e32 v48, 0x3f4c422a, v48
	ds_bpermute_b32 v46, v184, v54
	v_mul_f32_e32 v54, v50, v47
	v_mul_f32_e32 v47, 0xbfb8aa3b, v66
	v_add_f32_e32 v48, v48, v48
	v_exp_f32_e32 v47, v47
	v_mul_f32_e32 v48, 0x3fb8aa3b, v48
	v_exp_f32_e32 v49, v48
	v_mul_f32_e32 v60, v50, v45
	v_add_f32_e32 v45, 1.0, v47
	v_rcp_f32_e32 v48, v45
	v_add_f32_e32 v45, 1.0, v49
	v_rcp_f32_e32 v45, v45
	v_mov_b32_e32 v63, v145
	v_mov_b32_e32 v51, 1.0
	v_mov_b32_e32 v49, v37
	v_fma_f32 v45, v45, -2.0, 1.0
	v_mov_b32_dpp v63, v56 row_shr:8 row_mask:0xf bank_mask:0xf
	v_mov_b32_dpp v51, v53 row_shr:8 row_mask:0xf bank_mask:0xf
	v_add_f32_e32 v50, 1.0, v45
	v_fmac_f32_e32 v56, v53, v63
	v_pk_mul_f32 v[50:51], v[52:53], v[50:51]
	ds_bpermute_b32 v45, v184, v51
	ds_bpermute_b32 v47, v184, v56
	v_pk_mul_f32 v[48:49], v[48:49], v[50:51]
	s_mov_b32 s54, 0x25d59000
	v_add_f32_e32 v49, v49, v56
	v_add_co_u32_e32 v50, vcc, s54, v84
	v_mul_f32_e32 v52, v33, v51
	v_mul_f32_e32 v49, v48, v49
	v_addc_co_u32_e32 v51, vcc, 0, v85, vcc
	v_mul_f32_e32 v52, v48, v52
	v_cvt_pk_bf16_f32 v48, v58, v55
	v_cvt_pk_bf16_f32 v49, v54, v49
	global_store_dwordx2 v[50:51], v[48:49], off
	v_add_co_u32_e32 v50, vcc, 0x27d59000, v84
	v_cvt_pk_bf16_f32 v48, v57, v59
	v_cvt_pk_bf16_f32 v49, v60, v52
	s_nop 1
	v_addc_co_u32_e32 v51, vcc, 0, v85, vcc
	global_store_dwordx2 v[50:51], v[48:49], off
	s_and_saveexec_b64 s[54:55], s[6:7]
	s_cbranch_execz .LBB0_194
	s_waitcnt lgkmcnt(0)
	v_pk_fma_f32 v[48:49], v[36:37], v[44:45], v[46:47]
	v_pk_mul_f32 v[36:37], v[32:33], v[44:45]
	v_lshl_add_u64 v[32:33], s[74:75], 0, v[130:131]
	v_pk_fma_f32 v[46:47], v[38:39], v[40:41], v[42:43]
	v_add_co_u32_e32 v38, vcc, 0x2dd41000, v32
	v_pk_mul_f32 v[34:35], v[34:35], v[40:41]
	s_nop 0
	v_addc_co_u32_e32 v39, vcc, 0, v33, vcc
	v_add_co_u32_e32 v32, vcc, 0x2de41000, v32
	global_store_dwordx4 v[38:39], v[34:37], off
	s_nop 0
	v_addc_co_u32_e32 v33, vcc, 0, v33, vcc
	global_store_dwordx4 v[32:33], v[46:49], off
	s_branch .LBB0_194

.LBB0_422:
	v_and_b32_e32 v131, 64, v202
	v_xor_b32_e32 v130, 16, v202
	v_add_u32_e32 v131, 64, v131
	v_cmp_lt_i32_e32 vcc, v130, v131
	s_lshl_b32 s3, s12, 8
	s_add_i32 s3, s3, s27
	v_cndmask_b32_e32 v130, v202, v130, vcc
	v_lshlrev_b32_e32 v212, 2, v130
	v_xor_b32_e32 v130, 32, v202
	s_lshl_b32 s2, s34, 5
	v_or_b32_e32 v172, s3, v147
	s_lshl_b32 s3, s14, 8
	v_cmp_lt_i32_e32 vcc, v130, v131
	s_or_b32 s2, s3, s2
	v_ashrrev_i32_e32 v173, 31, v172
	v_cndmask_b32_e32 v130, v202, v130, vcc
	v_lshl_or_b32 v128, v138, 2, s2
	v_lshlrev_b32_e32 v144, 2, v130
	v_lshlrev_b64 v[130:131], 12, v[172:173]
	v_ashrrev_i32_e32 v129, 31, v128
	v_lshl_add_u64 v[130:131], s[66:67], 0, v[130:131]
	v_lshl_add_u64 v[182:183], v[128:129], 2, v[130:131]
	s_barrier
	s_nop 0
	v_mov_b32_e32 v238, v182
	v_mov_b32_e32 v239, v183
	global_load_dwordx4 v[226:229], v[238:239], off
	global_load_dwordx4 v[230:233], v[238:239], off offset:64
	global_load_dwordx4 v[234:237], v[238:239], off offset:512
	global_load_dwordx4 v[242:245], v[238:239], off offset:576
	s_mov_b64 s[100:101], 0x10000
	v_lshl_add_u64 v[238:239], v[238:239], 0, s[100:101]
	global_load_dwordx4 v[246:249], v[238:239], off
	s_nop 0
	v_cmp_eq_u32_e32 vcc, 0, v138
	s_lshl_b32 s2, s34, 3
	s_add_i32 s2, s2, 0
	v_lshl_add_u32 v213, v164, 5, s2
	s_nop 0
	s_waitcnt vmcnt(4)
	v_pk_mul_f32 v[228:229], v[228:229], s[52:53] op_sel_hi:[1,0]
	s_waitcnt vmcnt(3)
	v_pk_mul_f32 v[232:233], v[232:233], s[52:53] op_sel_hi:[1,0]
	v_pk_mul_f32 v[230:231], v[230:231], s[52:53] op_sel_hi:[1,0]
	v_pk_fma_f32 v[162:163], v[122:123], 0.5, v[232:233] op_sel_hi:[1,0,1]
	v_pk_fma_f32 v[142:143], v[120:121], 0.5, v[230:231] op_sel_hi:[1,0,1]
	v_mul_f32_e32 v120, v162, v162
	v_pk_fma_f32 v[152:153], v[162:163], v[162:163], v[120:121] op_sel_hi:[1,1,0]
	s_nop 0
	v_pk_mul_f32 v[226:227], v[226:227], s[52:53] op_sel_hi:[1,0]
	v_pk_fma_f32 v[186:187], v[126:127], 0.5, v[228:229] op_sel_hi:[1,0,1]
	v_pk_fma_f32 v[184:185], v[124:125], 0.5, v[226:227] op_sel_hi:[1,0,1]
	global_load_dwordx4 v[226:229], v[238:239], off offset:64
	global_load_dwordx4 v[230:233], v[238:239], off offset:512
	v_add_f32_e32 v126, v186, v187
	v_add_f32_e32 v124, v184, v185
	v_mul_f32_e32 v139, v184, v184
	v_mul_f32_e32 v141, v185, v185
	v_mul_f32_e32 v131, v186, v186
	v_mul_f32_e32 v133, v187, v187
	v_mul_f32_e32 v125, v142, v142
	v_mul_f32_e32 v127, v143, v143
	v_mov_b32_e32 v138, v142
	v_mov_b32_e32 v140, v143
	v_mov_b32_e32 v130, v162
	v_mov_b32_e32 v132, v163
	v_pk_add_f32 v[138:139], v[138:139], v[140:141]
	v_pk_add_f32 v[130:131], v[130:131], v[132:133]
	v_pk_add_f32 v[124:125], v[124:125], v[126:127]
	v_mov_b32_e32 v152, v145
	v_pk_add_f32 v[130:131], v[138:139], v[130:131]
	v_pk_add_f32 v[124:125], v[124:125], v[152:153]
	s_nop 0
	s_waitcnt vmcnt(4)
	v_pk_mul_f32 v[236:237], v[236:237], s[52:53] op_sel_hi:[1,0]
	v_pk_mul_f32 v[234:235], v[234:235], s[52:53] op_sel_hi:[1,0]
	v_pk_fma_f32 v[122:123], v[118:119], 0.5, v[236:237] op_sel_hi:[1,0,1]
	v_pk_fma_f32 v[120:121], v[116:117], 0.5, v[234:235] op_sel_hi:[1,0,1]
	global_load_dwordx4 v[234:237], v[238:239], off offset:576
	s_nop 0
	v_mul_f32_e32 v167, v120, v120
	v_mul_f32_e32 v169, v121, v121
	v_mul_f32_e32 v171, v122, v122
	v_mul_f32_e32 v175, v123, v123
	v_mov_b32_e32 v166, v120
	v_mov_b32_e32 v168, v121
	v_mov_b32_e32 v170, v122
	v_mov_b32_e32 v174, v123
	v_pk_add_f32 v[124:125], v[130:131], v[124:125]
	v_pk_add_f32 v[126:127], v[166:167], v[168:169]
	v_pk_add_f32 v[130:131], v[170:171], v[174:175]
	s_nop 0
	s_waitcnt vmcnt(4)
	v_pk_mul_f32 v[244:245], v[244:245], s[52:53] op_sel_hi:[1,0]
	v_pk_mul_f32 v[242:243], v[242:243], s[52:53] op_sel_hi:[1,0]
	v_pk_fma_f32 v[136:137], v[114:115], 0.5, v[244:245] op_sel_hi:[1,0,1]
	v_pk_fma_f32 v[134:135], v[112:113], 0.5, v[242:243] op_sel_hi:[1,0,1]
	s_mov_b64 s[100:101], 0x10000
	v_lshl_add_u64 v[238:239], v[238:239], 0, s[100:101]
	global_load_dwordx4 v[242:245], v[238:239], off
	v_mul_f32_e32 v117, v136, v136
	v_mul_f32_e32 v113, v134, v134
	v_mul_f32_e32 v115, v135, v135
	v_mul_f32_e32 v119, v137, v137
	v_mov_b32_e32 v112, v134
	v_mov_b32_e32 v114, v135
	v_mov_b32_e32 v116, v136
	v_mov_b32_e32 v118, v137
	v_pk_add_f32 v[126:127], v[126:127], v[130:131]
	v_pk_add_f32 v[112:113], v[112:113], v[114:115]
	v_pk_add_f32 v[114:115], v[116:117], v[118:119]
	v_pk_add_f32 v[124:125], v[124:125], v[126:127]
	v_pk_add_f32 v[112:113], v[112:113], v[114:115]
	s_nop 0
	v_pk_add_f32 v[112:113], v[124:125], v[112:113]
	ds_bpermute_b32 v114, v212, v112
	ds_bpermute_b32 v115, v212, v113
	s_waitcnt lgkmcnt(0)
	v_pk_add_f32 v[112:113], v[112:113], v[114:115]
	ds_bpermute_b32 v114, v144, v112
	ds_bpermute_b32 v115, v144, v113
	s_and_saveexec_b64 s[2:3], vcc
	v_readlane_b32 s22, v253, 34
	s_mov_b64 s[40:41], s[60:61]
	s_cbranch_execz .LBB0_424
	s_waitcnt lgkmcnt(0)
	v_pk_add_f32 v[112:113], v[112:113], v[114:115]
	ds_write_b64 v213, v[112:113]
.LBB0_424:
	s_or_b64 exec, exec, s[2:3]
	v_or_b32_e32 v180, 16, v172
	v_ashrrev_i32_e32 v181, 31, v180
	v_lshlrev_b64 v[112:113], 12, v[180:181]
	v_lshl_add_u64 v[112:113], s[66:67], 0, v[112:113]
	v_lshl_add_u64 v[174:175], v[128:129], 2, v[112:113]
	s_waitcnt lgkmcnt(0)
	s_nop 0
	s_nop 0
	s_waitcnt vmcnt(4)
	v_pk_mul_f32 v[248:249], v[248:249], s[52:53] op_sel_hi:[1,0]
	v_pk_mul_f32 v[246:247], v[246:247], s[52:53] op_sel_hi:[1,0]
	v_pk_fma_f32 v[178:179], v[110:111], 0.5, v[248:249] op_sel_hi:[1,0,1]
	v_pk_fma_f32 v[176:177], v[108:109], 0.5, v[246:247] op_sel_hi:[1,0,1]
	global_load_dwordx4 v[246:249], v[238:239], off offset:64
	s_nop 0
	v_add_f32_e32 v112, v176, v177
	v_add_f32_e32 v114, v178, v179
	v_mul_f32_e32 v131, v176, v176
	v_mul_f32_e32 v133, v177, v177
	v_mul_f32_e32 v125, v178, v178
	v_mul_f32_e32 v127, v179, v179
	s_nop 0
	s_waitcnt vmcnt(4)
	v_pk_mul_f32 v[228:229], v[228:229], s[52:53] op_sel_hi:[1,0]
	v_pk_mul_f32 v[226:227], v[226:227], s[52:53] op_sel_hi:[1,0]
	v_pk_fma_f32 v[140:141], v[106:107], 0.5, v[228:229] op_sel_hi:[1,0,1]
	v_pk_fma_f32 v[138:139], v[104:105], 0.5, v[226:227] op_sel_hi:[1,0,1]
	global_load_dwordx4 v[226:229], v[238:239], off offset:512
	v_mul_f32_e32 v104, v140, v140
	v_pk_fma_f32 v[152:153], v[140:141], v[140:141], v[104:105] op_sel_hi:[1,1,0]
	s_nop 0
	v_mul_f32_e32 v113, v138, v138
	v_mul_f32_e32 v115, v139, v139
	v_mov_b32_e32 v130, v138
	v_mov_b32_e32 v132, v139
	v_mov_b32_e32 v124, v140
	v_mov_b32_e32 v126, v141
	v_pk_add_f32 v[130:131], v[130:131], v[132:133]
	v_pk_add_f32 v[124:125], v[124:125], v[126:127]
	v_pk_add_f32 v[112:113], v[112:113], v[114:115]
	v_mov_b32_e32 v152, v145
	v_pk_add_f32 v[124:125], v[130:131], v[124:125]
	v_pk_add_f32 v[112:113], v[112:113], v[152:153]
	s_nop 0
	s_waitcnt vmcnt(4)
	v_pk_mul_f32 v[232:233], v[232:233], s[52:53] op_sel_hi:[1,0]
	v_pk_mul_f32 v[230:231], v[230:231], s[52:53] op_sel_hi:[1,0]
	v_pk_fma_f32 v[110:111], v[102:103], 0.5, v[232:233] op_sel_hi:[1,0,1]
	v_pk_fma_f32 v[108:109], v[100:101], 0.5, v[230:231] op_sel_hi:[1,0,1]
	global_load_dwordx4 v[230:233], v[238:239], off offset:576
	s_nop 0
	v_mul_f32_e32 v105, v108, v108
	v_mul_f32_e32 v107, v109, v109
	v_mul_f32_e32 v165, v110, v110
	v_mul_f32_e32 v167, v111, v111
	v_mov_b32_e32 v104, v108
	v_mov_b32_e32 v106, v109
	v_mov_b32_e32 v164, v110
	v_mov_b32_e32 v166, v111
	v_pk_add_f32 v[104:105], v[104:105], v[106:107]
	v_pk_add_f32 v[106:107], v[164:165], v[166:167]
	v_pk_add_f32 v[112:113], v[124:125], v[112:113]
	v_pk_add_f32 v[104:105], v[104:105], v[106:107]
	s_nop 0
	s_waitcnt vmcnt(4)
	v_pk_mul_f32 v[236:237], v[236:237], s[52:53] op_sel_hi:[1,0]
	v_pk_mul_f32 v[234:235], v[234:235], s[52:53] op_sel_hi:[1,0]
	v_pk_fma_f32 v[118:119], v[98:99], 0.5, v[236:237] op_sel_hi:[1,0,1]
	v_pk_fma_f32 v[116:117], v[96:97], 0.5, v[234:235] op_sel_hi:[1,0,1]
	s_mov_b64 s[100:101], 0x10000
	v_lshl_add_u64 v[238:239], v[238:239], 0, s[100:101]
	global_load_dwordx4 v[234:237], v[238:239], off
	v_mul_f32_e32 v101, v118, v118
	v_mul_f32_e32 v97, v116, v116
	v_mul_f32_e32 v99, v117, v117
	v_mul_f32_e32 v103, v119, v119
	v_mov_b32_e32 v96, v116
	v_mov_b32_e32 v98, v117
	v_mov_b32_e32 v100, v118
	v_mov_b32_e32 v102, v119
	v_pk_add_f32 v[96:97], v[96:97], v[98:99]
	v_pk_add_f32 v[98:99], v[100:101], v[102:103]
	v_pk_add_f32 v[104:105], v[112:113], v[104:105]
	v_pk_add_f32 v[96:97], v[96:97], v[98:99]
	s_nop 0
	v_pk_add_f32 v[96:97], v[104:105], v[96:97]
	ds_bpermute_b32 v98, v212, v96
	ds_bpermute_b32 v99, v212, v97
	s_waitcnt lgkmcnt(0)
	v_pk_add_f32 v[96:97], v[96:97], v[98:99]
	ds_bpermute_b32 v98, v144, v96
	ds_bpermute_b32 v99, v144, v97
	s_and_saveexec_b64 s[2:3], vcc
	s_mov_b64 s[60:61], s[58:59]
	s_cbranch_execz .LBB0_426
	s_waitcnt lgkmcnt(0)
	v_pk_add_f32 v[96:97], v[96:97], v[98:99]
	ds_write_b64 v213, v[96:97] offset:512
.LBB0_426:
	s_or_b64 exec, exec, s[2:3]
	v_or_b32_e32 v170, 32, v172
	v_ashrrev_i32_e32 v171, 31, v170
	v_lshlrev_b64 v[96:97], 12, v[170:171]
	v_lshl_add_u64 v[96:97], s[66:67], 0, v[96:97]
	v_lshl_add_u64 v[164:165], v[128:129], 2, v[96:97]
	s_waitcnt lgkmcnt(0)
	s_nop 0
	s_nop 0
	s_waitcnt vmcnt(4)
	v_pk_mul_f32 v[244:245], v[244:245], s[52:53] op_sel_hi:[1,0]
	v_pk_mul_f32 v[242:243], v[242:243], s[52:53] op_sel_hi:[1,0]
	v_pk_fma_f32 v[168:169], v[94:95], 0.5, v[244:245] op_sel_hi:[1,0,1]
	v_pk_fma_f32 v[166:167], v[92:93], 0.5, v[242:243] op_sel_hi:[1,0,1]
	global_load_dwordx4 v[242:245], v[238:239], off offset:64
	s_nop 0
	v_add_f32_e32 v96, v166, v167
	v_add_f32_e32 v98, v168, v169
	v_mul_f32_e32 v105, v166, v166
	v_mul_f32_e32 v107, v167, v167
	v_mul_f32_e32 v101, v168, v168
	v_mul_f32_e32 v103, v169, v169
	s_nop 0
	s_waitcnt vmcnt(4)
	v_pk_mul_f32 v[248:249], v[248:249], s[52:53] op_sel_hi:[1,0]
	v_pk_mul_f32 v[246:247], v[246:247], s[52:53] op_sel_hi:[1,0]
	v_pk_fma_f32 v[114:115], v[90:91], 0.5, v[248:249] op_sel_hi:[1,0,1]
	v_pk_fma_f32 v[112:113], v[88:89], 0.5, v[246:247] op_sel_hi:[1,0,1]
	global_load_dwordx4 v[246:249], v[238:239], off offset:512
	v_mul_f32_e32 v88, v114, v114
	v_pk_fma_f32 v[124:125], v[114:115], v[114:115], v[88:89] op_sel_hi:[1,1,0]
	s_nop 0
	v_mul_f32_e32 v97, v112, v112
	v_mul_f32_e32 v99, v113, v113
	v_mov_b32_e32 v104, v112
	v_mov_b32_e32 v106, v113
	v_mov_b32_e32 v100, v114
	v_mov_b32_e32 v102, v115
	v_pk_add_f32 v[104:105], v[104:105], v[106:107]
	v_pk_add_f32 v[100:101], v[100:101], v[102:103]
	v_pk_add_f32 v[96:97], v[96:97], v[98:99]
	v_mov_b32_e32 v124, v145
	v_pk_add_f32 v[100:101], v[104:105], v[100:101]
	v_pk_add_f32 v[96:97], v[96:97], v[124:125]
	s_nop 0
	s_waitcnt vmcnt(4)
	v_pk_mul_f32 v[228:229], v[228:229], s[52:53] op_sel_hi:[1,0]
	v_pk_mul_f32 v[226:227], v[226:227], s[52:53] op_sel_hi:[1,0]
	v_pk_fma_f32 v[86:87], v[86:87], 0.5, v[228:229] op_sel_hi:[1,0,1]
	v_pk_fma_f32 v[84:85], v[84:85], 0.5, v[226:227] op_sel_hi:[1,0,1]
	global_load_dwordx4 v[226:229], v[238:239], off offset:576
	s_nop 0
	v_mul_f32_e32 v127, v84, v84
	v_mul_f32_e32 v131, v85, v85
	v_mul_f32_e32 v133, v86, v86
	v_mul_f32_e32 v153, v87, v87
	v_mov_b32_e32 v126, v84
	v_mov_b32_e32 v130, v85
	v_mov_b32_e32 v132, v86
	v_mov_b32_e32 v152, v87
	v_pk_add_f32 v[96:97], v[100:101], v[96:97]
	v_pk_add_f32 v[98:99], v[126:127], v[130:131]
	v_pk_add_f32 v[100:101], v[132:133], v[152:153]
	s_nop 0
	s_waitcnt vmcnt(4)
	v_pk_mul_f32 v[232:233], v[232:233], s[52:53] op_sel_hi:[1,0]
	v_pk_mul_f32 v[230:231], v[230:231], s[52:53] op_sel_hi:[1,0]
	v_pk_fma_f32 v[94:95], v[82:83], 0.5, v[232:233] op_sel_hi:[1,0,1]
	v_pk_fma_f32 v[92:93], v[80:81], 0.5, v[230:231] op_sel_hi:[1,0,1]
	s_mov_b64 s[100:101], 0x50000
	v_lshl_add_u64 v[238:239], v[238:239], 0, s[100:101]
	global_load_dwordx4 v[230:233], v[238:239], off
	v_mul_f32_e32 v89, v94, v94
	v_mul_f32_e32 v81, v92, v92
	v_mul_f32_e32 v83, v93, v93
	v_mul_f32_e32 v91, v95, v95
	v_mov_b32_e32 v80, v92
	v_mov_b32_e32 v82, v93
	v_mov_b32_e32 v88, v94
	v_mov_b32_e32 v90, v95
	v_pk_add_f32 v[98:99], v[98:99], v[100:101]
	v_pk_add_f32 v[80:81], v[80:81], v[82:83]
	v_pk_add_f32 v[82:83], v[88:89], v[90:91]
	v_pk_add_f32 v[96:97], v[96:97], v[98:99]
	v_pk_add_f32 v[80:81], v[80:81], v[82:83]
	s_nop 0
	v_pk_add_f32 v[80:81], v[96:97], v[80:81]
	ds_bpermute_b32 v82, v212, v80
	ds_bpermute_b32 v83, v212, v81
	s_waitcnt lgkmcnt(0)
	v_pk_add_f32 v[80:81], v[80:81], v[82:83]
	ds_bpermute_b32 v82, v144, v80
	ds_bpermute_b32 v83, v144, v81
	s_and_saveexec_b64 s[2:3], vcc
	s_cbranch_execz .LBB0_428
	s_waitcnt lgkmcnt(0)
	v_pk_add_f32 v[80:81], v[80:81], v[82:83]
	ds_write_b64 v213, v[80:81] offset:1024
.LBB0_428:
	s_or_b64 exec, exec, s[2:3]
	v_or_b32_e32 v132, 48, v172
	v_ashrrev_i32_e32 v133, 31, v132
	v_lshlrev_b64 v[80:81], 12, v[132:133]
	v_lshl_add_u64 v[80:81], s[66:67], 0, v[80:81]
	v_lshl_add_u64 v[124:125], v[128:129], 2, v[80:81]
	s_waitcnt lgkmcnt(0)
	s_nop 0
	s_nop 0
	s_waitcnt vmcnt(1)
	s_waitcnt vmcnt(4)
	v_pk_mul_f32 v[236:237], v[236:237], s[52:53] op_sel_hi:[1,0]
	s_nop 0
	s_waitcnt vmcnt(3)
	v_pk_mul_f32 v[244:245], v[244:245], s[52:53] op_sel_hi:[1,0]
	v_pk_mul_f32 v[242:243], v[242:243], s[52:53] op_sel_hi:[1,0]
	v_pk_fma_f32 v[90:91], v[74:75], 0.5, v[244:245] op_sel_hi:[1,0,1]
	v_pk_fma_f32 v[88:89], v[72:73], 0.5, v[242:243] op_sel_hi:[1,0,1]
	v_mul_f32_e32 v72, v90, v90
	v_pk_fma_f32 v[100:101], v[90:91], v[90:91], v[72:73] op_sel_hi:[1,1,0]
	s_nop 0
	v_pk_mul_f32 v[234:235], v[234:235], s[52:53] op_sel_hi:[1,0]
	v_pk_fma_f32 v[130:131], v[78:79], 0.5, v[236:237] op_sel_hi:[1,0,1]
	v_pk_fma_f32 v[126:127], v[76:77], 0.5, v[234:235] op_sel_hi:[1,0,1]
	global_load_dwordx4 v[234:237], v[238:239], off offset:64
	global_load_dwordx4 v[242:245], v[238:239], off offset:512
	v_add_f32_e32 v78, v130, v131
	v_add_f32_e32 v76, v126, v127
	v_mul_f32_e32 v97, v126, v126
	v_mul_f32_e32 v99, v127, v127
	v_mul_f32_e32 v81, v130, v130
	v_mul_f32_e32 v83, v131, v131
	v_mul_f32_e32 v77, v88, v88
	v_mul_f32_e32 v79, v89, v89
	v_mov_b32_e32 v96, v88
	v_mov_b32_e32 v98, v89
	v_mov_b32_e32 v80, v90
	v_mov_b32_e32 v82, v91
	v_pk_add_f32 v[96:97], v[96:97], v[98:99]
	v_pk_add_f32 v[80:81], v[80:81], v[82:83]
	v_pk_add_f32 v[76:77], v[76:77], v[78:79]
	v_mov_b32_e32 v100, v145
	v_pk_add_f32 v[80:81], v[96:97], v[80:81]
	v_pk_add_f32 v[76:77], v[76:77], v[100:101]
	s_nop 0
	s_waitcnt vmcnt(4)
	v_pk_mul_f32 v[248:249], v[248:249], s[52:53] op_sel_hi:[1,0]
	v_pk_mul_f32 v[246:247], v[246:247], s[52:53] op_sel_hi:[1,0]
	v_pk_fma_f32 v[70:71], v[70:71], 0.5, v[248:249] op_sel_hi:[1,0,1]
	v_pk_fma_f32 v[68:69], v[68:69], 0.5, v[246:247] op_sel_hi:[1,0,1]
	global_load_dwordx4 v[246:249], v[238:239], off offset:576
	s_nop 0
	v_mul_f32_e32 v103, v68, v68
	v_mul_f32_e32 v105, v69, v69
	v_mul_f32_e32 v107, v70, v70
	v_mul_f32_e32 v153, v71, v71
	v_mov_b32_e32 v102, v68
	v_mov_b32_e32 v104, v69
	v_mov_b32_e32 v106, v70
	v_mov_b32_e32 v152, v71
	v_pk_add_f32 v[76:77], v[80:81], v[76:77]
	v_pk_add_f32 v[78:79], v[102:103], v[104:105]
	v_pk_add_f32 v[80:81], v[106:107], v[152:153]
	s_nop 0
	s_waitcnt vmcnt(4)
	v_pk_mul_f32 v[228:229], v[228:229], s[52:53] op_sel_hi:[1,0]
	v_pk_mul_f32 v[226:227], v[226:227], s[52:53] op_sel_hi:[1,0]
	v_pk_fma_f32 v[74:75], v[66:67], 0.5, v[228:229] op_sel_hi:[1,0,1]
	v_pk_fma_f32 v[72:73], v[64:65], 0.5, v[226:227] op_sel_hi:[1,0,1]
	s_mov_b64 s[100:101], 0x10000
	v_lshl_add_u64 v[238:239], v[238:239], 0, s[100:101]
	global_load_dwordx4 v[226:229], v[238:239], off
	v_mul_f32_e32 v189, v74, v74
	v_mul_f32_e32 v65, v72, v72
	v_mul_f32_e32 v67, v73, v73
	v_mul_f32_e32 v191, v75, v75
	v_mov_b32_e32 v64, v72
	v_mov_b32_e32 v66, v73
	v_mov_b32_e32 v188, v74
	v_mov_b32_e32 v190, v75
	v_pk_add_f32 v[78:79], v[78:79], v[80:81]
	v_pk_add_f32 v[64:65], v[64:65], v[66:67]
	v_pk_add_f32 v[66:67], v[188:189], v[190:191]
	v_pk_add_f32 v[76:77], v[76:77], v[78:79]
	v_pk_add_f32 v[64:65], v[64:65], v[66:67]
	s_nop 0
	v_pk_add_f32 v[64:65], v[76:77], v[64:65]
	ds_bpermute_b32 v66, v212, v64
	ds_bpermute_b32 v67, v212, v65
	s_waitcnt lgkmcnt(0)
	v_pk_add_f32 v[64:65], v[64:65], v[66:67]
	ds_bpermute_b32 v66, v144, v64
	ds_bpermute_b32 v67, v144, v65
	s_and_saveexec_b64 s[2:3], vcc
	s_cbranch_execz .LBB0_430
	s_waitcnt lgkmcnt(0)
	v_pk_add_f32 v[64:65], v[64:65], v[66:67]
	ds_write_b64 v213, v[64:65] offset:1536
.LBB0_430:
	s_or_b64 exec, exec, s[2:3]
	v_add_u32_e32 v102, 0x80, v172
	v_ashrrev_i32_e32 v103, 31, v102
	v_lshlrev_b64 v[64:65], 12, v[102:103]
	v_lshl_add_u64 v[64:65], s[66:67], 0, v[64:65]
	v_lshl_add_u64 v[96:97], v[128:129], 2, v[64:65]
	s_waitcnt lgkmcnt(0)
	s_nop 0
	s_nop 0
	s_waitcnt vmcnt(4)
	v_pk_mul_f32 v[232:233], v[232:233], s[52:53] op_sel_hi:[1,0]
	v_pk_mul_f32 v[230:231], v[230:231], s[52:53] op_sel_hi:[1,0]
	v_pk_fma_f32 v[100:101], v[62:63], 0.5, v[232:233] op_sel_hi:[1,0,1]
	v_pk_fma_f32 v[98:99], v[60:61], 0.5, v[230:231] op_sel_hi:[1,0,1]
	global_load_dwordx4 v[230:233], v[238:239], off offset:64
	s_nop 0
	v_add_f32_e32 v60, v98, v99
	v_add_f32_e32 v62, v100, v101
	v_mul_f32_e32 v81, v98, v98
	v_mul_f32_e32 v83, v99, v99
	v_mul_f32_e32 v77, v100, v100
	v_mul_f32_e32 v79, v101, v101
	s_nop 0
	s_waitcnt vmcnt(4)
	v_pk_mul_f32 v[236:237], v[236:237], s[52:53] op_sel_hi:[1,0]
	v_pk_mul_f32 v[234:235], v[234:235], s[52:53] op_sel_hi:[1,0]
	v_pk_fma_f32 v[66:67], v[58:59], 0.5, v[236:237] op_sel_hi:[1,0,1]
	v_pk_fma_f32 v[64:65], v[56:57], 0.5, v[234:235] op_sel_hi:[1,0,1]
	global_load_dwordx4 v[234:237], v[238:239], off offset:512
	v_mul_f32_e32 v56, v66, v66
	v_pk_fma_f32 v[104:105], v[66:67], v[66:67], v[56:57] op_sel_hi:[1,1,0]
	s_nop 0
	v_mul_f32_e32 v61, v64, v64
	v_mul_f32_e32 v63, v65, v65
	v_mov_b32_e32 v80, v64
	v_mov_b32_e32 v82, v65
	v_mov_b32_e32 v76, v66
	v_mov_b32_e32 v78, v67
	v_pk_add_f32 v[80:81], v[80:81], v[82:83]
	v_pk_add_f32 v[76:77], v[76:77], v[78:79]
	v_pk_add_f32 v[60:61], v[60:61], v[62:63]
	v_mov_b32_e32 v104, v145
	v_pk_add_f32 v[76:77], v[80:81], v[76:77]
	v_pk_add_f32 v[60:61], v[60:61], v[104:105]
	s_nop 0
	s_waitcnt vmcnt(4)
	v_pk_mul_f32 v[244:245], v[244:245], s[52:53] op_sel_hi:[1,0]
	v_pk_mul_f32 v[242:243], v[242:243], s[52:53] op_sel_hi:[1,0]
	v_pk_fma_f32 v[54:55], v[54:55], 0.5, v[244:245] op_sel_hi:[1,0,1]
	v_pk_fma_f32 v[52:53], v[52:53], 0.5, v[242:243] op_sel_hi:[1,0,1]
	global_load_dwordx4 v[242:245], v[238:239], off offset:576
	s_nop 0
	v_mul_f32_e32 v107, v52, v52
	v_mul_f32_e32 v153, v53, v53
	v_mul_f32_e32 v189, v54, v54
	v_mul_f32_e32 v191, v55, v55
	v_mov_b32_e32 v106, v52
	v_mov_b32_e32 v152, v53
	v_mov_b32_e32 v188, v54
	v_mov_b32_e32 v190, v55
	v_pk_add_f32 v[60:61], v[76:77], v[60:61]
	v_pk_add_f32 v[62:63], v[106:107], v[152:153]
	v_pk_add_f32 v[76:77], v[188:189], v[190:191]
	s_nop 0
	s_waitcnt vmcnt(4)
	v_pk_mul_f32 v[248:249], v[248:249], s[52:53] op_sel_hi:[1,0]
	v_pk_mul_f32 v[246:247], v[246:247], s[52:53] op_sel_hi:[1,0]
	v_pk_fma_f32 v[50:51], v[50:51], 0.5, v[248:249] op_sel_hi:[1,0,1]
	v_pk_fma_f32 v[48:49], v[48:49], 0.5, v[246:247] op_sel_hi:[1,0,1]
	s_mov_b64 s[100:101], 0x10000
	v_lshl_add_u64 v[238:239], v[238:239], 0, s[100:101]
	global_load_dwordx4 v[246:249], v[238:239], off
	v_mul_f32_e32 v193, v50, v50
	v_mul_f32_e32 v57, v48, v48
	v_mul_f32_e32 v59, v49, v49
	v_mul_f32_e32 v195, v51, v51
	v_mov_b32_e32 v56, v48
	v_mov_b32_e32 v58, v49
	v_mov_b32_e32 v192, v50
	v_mov_b32_e32 v194, v51
	v_pk_add_f32 v[62:63], v[62:63], v[76:77]
	v_pk_add_f32 v[56:57], v[56:57], v[58:59]
	v_pk_add_f32 v[58:59], v[192:193], v[194:195]
	v_pk_add_f32 v[60:61], v[60:61], v[62:63]
	v_pk_add_f32 v[56:57], v[56:57], v[58:59]
	s_nop 0
	v_pk_add_f32 v[56:57], v[60:61], v[56:57]
	ds_bpermute_b32 v58, v212, v56
	ds_bpermute_b32 v59, v212, v57
	s_waitcnt lgkmcnt(0)
	v_pk_add_f32 v[56:57], v[56:57], v[58:59]
	ds_bpermute_b32 v58, v144, v56
	ds_bpermute_b32 v59, v144, v57
	s_and_saveexec_b64 s[2:3], vcc
	s_cbranch_execz .LBB0_432
	s_waitcnt lgkmcnt(0)
	v_pk_add_f32 v[56:57], v[56:57], v[58:59]
	ds_write_b64 v213, v[56:57] offset:4096
.LBB0_432:
	s_or_b64 exec, exec, s[2:3]
	v_add_u32_e32 v82, 0x90, v172
	v_ashrrev_i32_e32 v83, 31, v82
	v_lshlrev_b64 v[56:57], 12, v[82:83]
	v_lshl_add_u64 v[56:57], s[66:67], 0, v[56:57]
	v_lshl_add_u64 v[76:77], v[128:129], 2, v[56:57]
	s_waitcnt lgkmcnt(0)
	s_nop 0
	s_nop 0
	s_waitcnt vmcnt(4)
	v_pk_mul_f32 v[228:229], v[228:229], s[52:53] op_sel_hi:[1,0]
	v_pk_mul_f32 v[226:227], v[226:227], s[52:53] op_sel_hi:[1,0]
	v_pk_fma_f32 v[80:81], v[46:47], 0.5, v[228:229] op_sel_hi:[1,0,1]
	v_pk_fma_f32 v[78:79], v[44:45], 0.5, v[226:227] op_sel_hi:[1,0,1]
	global_load_dwordx4 v[226:229], v[238:239], off offset:64
	s_nop 0
	v_add_f32_e32 v56, v78, v79
	v_add_f32_e32 v58, v80, v81
	v_mul_f32_e32 v105, v78, v78
	v_mul_f32_e32 v107, v79, v79
	v_mul_f32_e32 v61, v80, v80
	v_mul_f32_e32 v63, v81, v81
	s_nop 0
	s_waitcnt vmcnt(4)
	v_pk_mul_f32 v[232:233], v[232:233], s[52:53] op_sel_hi:[1,0]
	v_pk_mul_f32 v[230:231], v[230:231], s[52:53] op_sel_hi:[1,0]
	v_pk_fma_f32 v[46:47], v[42:43], 0.5, v[232:233] op_sel_hi:[1,0,1]
	v_pk_fma_f32 v[44:45], v[40:41], 0.5, v[230:231] op_sel_hi:[1,0,1]
	global_load_dwordx4 v[230:233], v[238:239], off offset:512
	v_mul_f32_e32 v40, v46, v46
	v_pk_fma_f32 v[152:153], v[46:47], v[46:47], v[40:41] op_sel_hi:[1,1,0]
	s_nop 0
	v_mul_f32_e32 v57, v44, v44
	v_mul_f32_e32 v59, v45, v45
	v_mov_b32_e32 v104, v44
	v_mov_b32_e32 v106, v45
	v_mov_b32_e32 v60, v46
	v_mov_b32_e32 v62, v47
	v_pk_add_f32 v[104:105], v[104:105], v[106:107]
	v_pk_add_f32 v[60:61], v[60:61], v[62:63]
	v_pk_add_f32 v[56:57], v[56:57], v[58:59]
	v_mov_b32_e32 v152, v145
	v_pk_add_f32 v[60:61], v[104:105], v[60:61]
	v_pk_add_f32 v[56:57], v[56:57], v[152:153]
	s_nop 0
	s_waitcnt vmcnt(4)
	v_pk_mul_f32 v[236:237], v[236:237], s[52:53] op_sel_hi:[1,0]
	v_pk_mul_f32 v[234:235], v[234:235], s[52:53] op_sel_hi:[1,0]
	v_pk_fma_f32 v[38:39], v[38:39], 0.5, v[236:237] op_sel_hi:[1,0,1]
	v_pk_fma_f32 v[36:37], v[36:37], 0.5, v[234:235] op_sel_hi:[1,0,1]
	global_load_dwordx4 v[234:237], v[238:239], off offset:576
	s_nop 0
	v_mul_f32_e32 v189, v36, v36
	v_mul_f32_e32 v191, v37, v37
	v_mul_f32_e32 v193, v38, v38
	v_mul_f32_e32 v195, v39, v39
	v_mov_b32_e32 v188, v36
	v_mov_b32_e32 v190, v37
	v_mov_b32_e32 v192, v38
	v_mov_b32_e32 v194, v39
	v_pk_add_f32 v[56:57], v[60:61], v[56:57]
	v_pk_add_f32 v[58:59], v[188:189], v[190:191]
	v_pk_add_f32 v[60:61], v[192:193], v[194:195]
	s_nop 0
	s_waitcnt vmcnt(4)
	v_pk_mul_f32 v[244:245], v[244:245], s[52:53] op_sel_hi:[1,0]
	v_pk_mul_f32 v[242:243], v[242:243], s[52:53] op_sel_hi:[1,0]
	v_pk_fma_f32 v[34:35], v[34:35], 0.5, v[244:245] op_sel_hi:[1,0,1]
	v_pk_fma_f32 v[32:33], v[32:33], 0.5, v[242:243] op_sel_hi:[1,0,1]
	s_mov_b64 s[100:101], 0x10000
	v_lshl_add_u64 v[238:239], v[238:239], 0, s[100:101]
	global_load_dwordx4 v[242:245], v[238:239], off
	v_mul_f32_e32 v215, v34, v34
	v_mul_f32_e32 v41, v32, v32
	v_mul_f32_e32 v43, v33, v33
	v_mul_f32_e32 v217, v35, v35
	v_mov_b32_e32 v40, v32
	v_mov_b32_e32 v42, v33
	v_mov_b32_e32 v214, v34
	v_mov_b32_e32 v216, v35
	v_pk_add_f32 v[58:59], v[58:59], v[60:61]
	v_pk_add_f32 v[40:41], v[40:41], v[42:43]
	v_pk_add_f32 v[42:43], v[214:215], v[216:217]
	v_pk_add_f32 v[56:57], v[56:57], v[58:59]
	v_pk_add_f32 v[40:41], v[40:41], v[42:43]
	s_nop 0
	v_pk_add_f32 v[40:41], v[56:57], v[40:41]
	ds_bpermute_b32 v42, v212, v40
	ds_bpermute_b32 v43, v212, v41
	s_waitcnt lgkmcnt(0)
	v_pk_add_f32 v[40:41], v[40:41], v[42:43]
	ds_bpermute_b32 v42, v144, v40
	ds_bpermute_b32 v43, v144, v41
	s_and_saveexec_b64 s[2:3], vcc
	s_cbranch_execz .LBB0_434
	s_waitcnt lgkmcnt(0)
	v_pk_add_f32 v[40:41], v[40:41], v[42:43]
	ds_write_b64 v213, v[40:41] offset:4608
.LBB0_434:
	s_or_b64 exec, exec, s[2:3]
	v_add_u32_e32 v62, 0xa0, v172
	v_ashrrev_i32_e32 v63, 31, v62
	v_lshlrev_b64 v[40:41], 12, v[62:63]
	v_lshl_add_u64 v[40:41], s[66:67], 0, v[40:41]
	v_lshl_add_u64 v[56:57], v[128:129], 2, v[40:41]
	s_waitcnt lgkmcnt(0)
	s_nop 0
	s_nop 0
	s_waitcnt vmcnt(1)
	s_waitcnt vmcnt(4)
	v_pk_mul_f32 v[248:249], v[248:249], s[52:53] op_sel_hi:[1,0]
	s_nop 0
	s_waitcnt vmcnt(3)
	v_pk_mul_f32 v[226:227], v[226:227], s[52:53] op_sel_hi:[1,0]
	v_pk_mul_f32 v[152:153], v[228:229], s[52:53] op_sel_hi:[1,0]
	v_pk_fma_f32 v[24:25], v[24:25], 0.5, v[226:227] op_sel_hi:[1,0,1]
	s_nop 0
	v_pk_mul_f32 v[246:247], v[246:247], s[52:53] op_sel_hi:[1,0]
	v_pk_fma_f32 v[60:61], v[30:31], 0.5, v[248:249] op_sel_hi:[1,0,1]
	v_pk_fma_f32 v[26:27], v[26:27], 0.5, v[152:153] op_sel_hi:[1,0,1]
	v_pk_fma_f32 v[58:59], v[28:29], 0.5, v[246:247] op_sel_hi:[1,0,1]
	global_load_dwordx4 v[246:249], v[238:239], off offset:64
	global_load_dwordx4 v[226:229], v[238:239], off offset:512
	v_mul_f32_e32 v41, v60, v60
	v_mul_f32_e32 v40, v26, v26
	v_add_f32_e32 v28, v58, v59
	v_add_f32_e32 v30, v60, v61
	v_mul_f32_e32 v105, v58, v58
	v_mul_f32_e32 v107, v59, v59
	v_mul_f32_e32 v43, v61, v61
	v_mul_f32_e32 v29, v24, v24
	v_mul_f32_e32 v31, v25, v25
	v_pk_fma_f32 v[152:153], v[26:27], v[26:27], v[40:41] op_sel_hi:[1,1,0]
	v_mov_b32_e32 v104, v24
	v_mov_b32_e32 v106, v25
	v_mov_b32_e32 v40, v26
	v_mov_b32_e32 v42, v27
	v_pk_add_f32 v[104:105], v[104:105], v[106:107]
	v_pk_add_f32 v[40:41], v[40:41], v[42:43]
	v_pk_add_f32 v[28:29], v[28:29], v[30:31]
	v_mov_b32_e32 v152, v145
	v_pk_add_f32 v[40:41], v[104:105], v[40:41]
	v_pk_add_f32 v[28:29], v[28:29], v[152:153]
	s_nop 0
	s_waitcnt vmcnt(4)
	v_pk_mul_f32 v[232:233], v[232:233], s[52:53] op_sel_hi:[1,0]
	v_pk_mul_f32 v[230:231], v[230:231], s[52:53] op_sel_hi:[1,0]
	v_pk_fma_f32 v[22:23], v[22:23], 0.5, v[232:233] op_sel_hi:[1,0,1]
	v_pk_fma_f32 v[20:21], v[20:21], 0.5, v[230:231] op_sel_hi:[1,0,1]
	global_load_dwordx4 v[230:233], v[238:239], off offset:576
	s_nop 0
	v_mul_f32_e32 v193, v20, v20
	v_mul_f32_e32 v195, v21, v21
	v_mul_f32_e32 v215, v22, v22
	v_mul_f32_e32 v217, v23, v23
	v_mov_b32_e32 v192, v20
	v_mov_b32_e32 v194, v21
	v_mov_b32_e32 v214, v22
	v_mov_b32_e32 v216, v23
	v_pk_add_f32 v[28:29], v[40:41], v[28:29]
	v_pk_add_f32 v[30:31], v[192:193], v[194:195]
	v_pk_add_f32 v[40:41], v[214:215], v[216:217]
	s_nop 0
	s_waitcnt vmcnt(4)
	v_pk_mul_f32 v[236:237], v[236:237], s[52:53] op_sel_hi:[1,0]
	v_pk_mul_f32 v[234:235], v[234:235], s[52:53] op_sel_hi:[1,0]
	v_pk_fma_f32 v[18:19], v[18:19], 0.5, v[236:237] op_sel_hi:[1,0,1]
	v_pk_fma_f32 v[16:17], v[16:17], 0.5, v[234:235] op_sel_hi:[1,0,1]
	v_mul_f32_e32 v219, v18, v18
	v_mul_f32_e32 v189, v16, v16
	v_mul_f32_e32 v191, v17, v17
	v_mul_f32_e32 v221, v19, v19
	v_pk_add_f32 v[30:31], v[30:31], v[40:41]
	v_mov_b32_e32 v188, v16
	v_mov_b32_e32 v190, v17
	v_mov_b32_e32 v218, v18
	v_mov_b32_e32 v220, v19
	v_pk_add_f32 v[28:29], v[28:29], v[30:31]
	v_pk_add_f32 v[30:31], v[188:189], v[190:191]
	v_pk_add_f32 v[40:41], v[218:219], v[220:221]
	s_nop 0
	v_pk_add_f32 v[30:31], v[30:31], v[40:41]
	s_nop 0
	v_pk_add_f32 v[28:29], v[28:29], v[30:31]
	ds_bpermute_b32 v30, v212, v28
	ds_bpermute_b32 v31, v212, v29
	s_waitcnt lgkmcnt(0)
	v_pk_add_f32 v[28:29], v[28:29], v[30:31]
	ds_bpermute_b32 v30, v144, v28
	ds_bpermute_b32 v31, v144, v29
	s_and_saveexec_b64 s[2:3], vcc
	s_cbranch_execz .LBB0_436
	s_waitcnt lgkmcnt(0)
	v_pk_add_f32 v[28:29], v[28:29], v[30:31]
	ds_write_b64 v213, v[28:29] offset:5120
.LBB0_436:
	s_or_b64 exec, exec, s[2:3]
	v_add_u32_e32 v42, 0xb0, v172
	v_ashrrev_i32_e32 v43, 31, v42
	v_lshlrev_b64 v[28:29], 12, v[42:43]
	v_lshl_add_u64 v[28:29], s[66:67], 0, v[28:29]
	v_lshl_add_u64 v[28:29], v[128:129], 2, v[28:29]
	s_nop 0
	s_waitcnt vmcnt(0) lgkmcnt(0)
	s_waitcnt vmcnt(3)
	v_pk_mul_f32 v[30:31], v[244:245], s[52:53] op_sel_hi:[1,0]
	v_pk_mul_f32 v[242:243], v[242:243], s[52:53] op_sel_hi:[1,0]
	v_pk_fma_f32 v[40:41], v[14:15], 0.5, v[30:31] op_sel_hi:[1,0,1]
	v_pk_fma_f32 v[30:31], v[12:13], 0.5, v[242:243] op_sel_hi:[1,0,1]
	s_nop 0
	v_add_f32_e32 v104, v30, v31
	v_add_f32_e32 v106, v40, v41
	v_mul_f32_e32 v193, v30, v30
	v_mul_f32_e32 v195, v31, v31
	v_mul_f32_e32 v189, v40, v40
	v_mul_f32_e32 v191, v41, v41
	s_nop 0
	s_waitcnt vmcnt(2)
	v_pk_mul_f32 v[248:249], v[248:249], s[52:53] op_sel_hi:[1,0]
	v_pk_mul_f32 v[246:247], v[246:247], s[52:53] op_sel_hi:[1,0]
	v_pk_fma_f32 v[14:15], v[10:11], 0.5, v[248:249] op_sel_hi:[1,0,1]
	v_pk_fma_f32 v[12:13], v[8:9], 0.5, v[246:247] op_sel_hi:[1,0,1]
	v_mul_f32_e32 v8, v14, v14
	v_pk_fma_f32 v[152:153], v[14:15], v[14:15], v[8:9] op_sel_hi:[1,1,0]
	s_nop 0
	v_mul_f32_e32 v105, v12, v12
	v_mul_f32_e32 v107, v13, v13
	v_mov_b32_e32 v192, v12
	v_mov_b32_e32 v194, v13
	v_mov_b32_e32 v188, v14
	v_mov_b32_e32 v190, v15
	v_pk_add_f32 v[192:193], v[192:193], v[194:195]
	v_pk_add_f32 v[188:189], v[188:189], v[190:191]
	v_pk_add_f32 v[104:105], v[104:105], v[106:107]
	v_mov_b32_e32 v152, v145
	v_pk_add_f32 v[188:189], v[192:193], v[188:189]
	v_pk_add_f32 v[104:105], v[104:105], v[152:153]
	s_nop 0
	s_waitcnt vmcnt(1)
	v_pk_mul_f32 v[228:229], v[228:229], s[52:53] op_sel_hi:[1,0]
	v_pk_mul_f32 v[226:227], v[226:227], s[52:53] op_sel_hi:[1,0]
	v_pk_fma_f32 v[6:7], v[6:7], 0.5, v[228:229] op_sel_hi:[1,0,1]
	v_pk_fma_f32 v[4:5], v[4:5], 0.5, v[226:227] op_sel_hi:[1,0,1]
	s_nop 0
	v_mul_f32_e32 v215, v4, v4
	v_mul_f32_e32 v217, v5, v5
	v_mul_f32_e32 v219, v6, v6
	v_mul_f32_e32 v221, v7, v7
	v_mov_b32_e32 v214, v4
	v_mov_b32_e32 v216, v5
	v_mov_b32_e32 v218, v6
	v_mov_b32_e32 v220, v7
	v_pk_add_f32 v[106:107], v[214:215], v[216:217]
	v_pk_add_f32 v[152:153], v[218:219], v[220:221]
	v_pk_add_f32 v[104:105], v[188:189], v[104:105]
	v_pk_add_f32 v[106:107], v[106:107], v[152:153]
	s_nop 0
	s_waitcnt vmcnt(0)
	v_pk_mul_f32 v[232:233], v[232:233], s[52:53] op_sel_hi:[1,0]
	v_pk_mul_f32 v[230:231], v[230:231], s[52:53] op_sel_hi:[1,0]
	v_pk_fma_f32 v[10:11], v[2:3], 0.5, v[232:233] op_sel_hi:[1,0,1]
	v_pk_fma_f32 v[8:9], v[0:1], 0.5, v[230:231] op_sel_hi:[1,0,1]
	v_mul_f32_e32 v223, v10, v10
	v_mul_f32_e32 v1, v8, v8
	v_mul_f32_e32 v3, v9, v9
	v_mul_f32_e32 v225, v11, v11
	v_mov_b32_e32 v0, v8
	v_mov_b32_e32 v2, v9
	v_mov_b32_e32 v222, v10
	v_mov_b32_e32 v224, v11
	v_pk_add_f32 v[0:1], v[0:1], v[2:3]
	v_pk_add_f32 v[2:3], v[222:223], v[224:225]
	v_pk_add_f32 v[104:105], v[104:105], v[106:107]
	v_pk_add_f32 v[0:1], v[0:1], v[2:3]
	s_nop 0
	v_pk_add_f32 v[0:1], v[104:105], v[0:1]
	ds_bpermute_b32 v2, v212, v0
	ds_bpermute_b32 v3, v212, v1
	s_waitcnt lgkmcnt(0)
	v_pk_add_f32 v[0:1], v[0:1], v[2:3]
	ds_bpermute_b32 v2, v144, v0
	ds_bpermute_b32 v3, v144, v1
	s_and_saveexec_b64 s[2:3], vcc
	s_cbranch_execz .LBB0_438
	s_waitcnt lgkmcnt(0)
	v_pk_add_f32 v[0:1], v[0:1], v[2:3]
	ds_write_b64 v213, v[0:1] offset:5632

.LBB0_447:
	s_or_b64 exec, exec, s[4:5]
	v_readlane_b32 s2, v253, 0
	v_readlane_b32 s3, v253, 1
	s_lshl_b64 s[2:3], s[2:3], 2
	s_add_u32 s4, s8, s2
	s_addc_u32 s5, s9, s3
	s_add_u32 s2, s10, s2
	s_addc_u32 s3, s11, s3
	v_lshlrev_b64 v[106:107], 2, v[128:129]
	v_lshlrev_b64 v[0:1], 10, v[172:173]
	v_lshl_add_u64 v[104:105], s[4:5], 0, v[106:107]
	v_lshl_add_u64 v[106:107], s[2:3], 0, v[106:107]
	s_waitcnt lgkmcnt(0)
	s_barrier
	v_lshl_add_u64 v[172:173], v[0:1], 0, v[128:129]
	s_nop 0
	s_nop 0
	s_lshl_b32 s6, s27, 3
	s_add_i32 s6, s6, 0
	v_lshl_add_u32 v144, v147, 3, s6
	ds_read_b64 v[188:189], v144 offset:8192
	v_cndmask_b32_e64 v147, 0, 1, s[20:21]
	v_cmp_ne_u32_e64 s[2:3], 1, v147
	s_andn2_b64 vcc, exec, s[20:21]
	s_waitcnt lgkmcnt(0)
	v_sub_f32_e32 v153, v187, v188
	v_sub_f32_e32 v152, v186, v188
	v_sub_f32_e32 v185, v185, v188
	v_sub_f32_e32 v184, v184, v188
	v_pk_mul_f32 v[184:185], v[188:189], v[184:185] op_sel:[1,0]
	v_pk_mul_f32 v[152:153], v[188:189], v[152:153] op_sel:[1,0]
	s_waitcnt vmcnt(0)
	v_pk_fma_f32 v[0:1], v[212:213], v[184:185], v[228:229]
	v_pk_fma_f32 v[2:3], v[214:215], v[152:153], v[230:231]
	global_store_dwordx4 v[182:183], v[0:3], off
	v_lshl_add_u64 v[182:183], v[172:173], 1, s[64:65]
	v_cvt_pk_bf16_f32 v152, v0, v1
	v_cvt_pk_bf16_f32 v153, v2, v3
	global_store_dwordx2 v[182:183], v[152:153], off
	v_lshl_add_u64 v[182:183], v[172:173], 2, s[72:73]
	s_cbranch_vccnz .LBB0_449
	global_store_dwordx4 v[182:183], v[0:3], off
.LBB0_449:
	s_nop 0
	s_nop 0
	v_mov_b32_e32 v184, v189
	v_mov_b32_e32 v185, v189
	v_sub_f32_e32 v143, v143, v188
	v_sub_f32_e32 v142, v142, v188
	v_sub_f32_e32 v153, v163, v188
	v_sub_f32_e32 v152, v162, v188
	v_pk_mul_f32 v[162:163], v[184:185], v[142:143]
	v_mov_b32_e32 v142, v189
	v_mov_b32_e32 v143, v189
	v_pk_mul_f32 v[152:153], v[142:143], v[152:153]
	s_and_b64 vcc, exec, s[2:3]
	s_nop 0
	v_pk_fma_f32 v[2:3], v[152:153], v[218:219], v[234:235]
	v_or_b32_e32 v152, 16, v172
	v_mov_b32_e32 v153, v173
	v_pk_fma_f32 v[0:1], v[162:163], v[216:217], v[232:233]
	v_lshl_add_u64 v[162:163], v[152:153], 2, s[66:67]
	v_lshl_add_u64 v[152:153], v[152:153], 1, s[64:65]
	global_store_dwordx4 v[162:163], v[0:3], off
	v_cvt_pk_bf16_f32 v162, v0, v1
	v_cvt_pk_bf16_f32 v163, v2, v3
	global_store_dwordx2 v[152:153], v[162:163], off
	s_cbranch_vccnz .LBB0_451
	global_store_dwordx4 v[182:183], v[0:3], off offset:64
.LBB0_451:
	s_nop 0
	s_nop 0
	v_sub_f32_e32 v123, v123, v188
	v_sub_f32_e32 v122, v122, v188
	v_sub_f32_e32 v121, v121, v188
	v_sub_f32_e32 v120, v120, v188
	v_or_b32_e32 v152, 0x80, v172
	v_mov_b32_e32 v153, v173
	v_pk_mul_f32 v[120:121], v[184:185], v[120:121]
	v_pk_mul_f32 v[122:123], v[142:143], v[122:123]
	s_and_b64 vcc, exec, s[2:3]
	s_nop 0
	v_pk_fma_f32 v[2:3], v[122:123], v[222:223], v[244:245]
	v_pk_fma_f32 v[0:1], v[120:121], v[220:221], v[242:243]
	v_lshl_add_u64 v[120:121], v[152:153], 2, s[66:67]
	v_lshl_add_u64 v[122:123], v[152:153], 1, s[64:65]
	global_store_dwordx4 v[120:121], v[0:3], off
	v_cvt_pk_bf16_f32 v120, v0, v1
	v_cvt_pk_bf16_f32 v121, v2, v3
	global_store_dwordx2 v[122:123], v[120:121], off
	s_cbranch_vccnz .LBB0_453
	global_store_dwordx4 v[182:183], v[0:3], off offset:512
.LBB0_453:
	s_nop 0
	s_nop 0
	v_sub_f32_e32 v137, v137, v188
	v_sub_f32_e32 v136, v136, v188
	v_sub_f32_e32 v135, v135, v188
	v_sub_f32_e32 v134, v134, v188
	v_mov_b32_e32 v188, v189
	v_pk_mul_f32 v[134:135], v[184:185], v[134:135]
	v_pk_mul_f32 v[136:137], v[188:189], v[136:137]
	v_or_b32_e32 v172, 0x90, v172
	s_and_b64 vcc, exec, s[2:3]
	s_nop 0
	v_pk_fma_f32 v[2:3], v[136:137], v[226:227], v[248:249]
	v_pk_fma_f32 v[0:1], v[134:135], v[224:225], v[246:247]
	v_lshl_add_u64 v[120:121], v[172:173], 2, s[66:67]
	v_lshl_add_u64 v[122:123], v[172:173], 1, s[64:65]
	global_store_dwordx4 v[120:121], v[0:3], off
	v_cvt_pk_bf16_f32 v120, v0, v1
	v_cvt_pk_bf16_f32 v121, v2, v3
	global_store_dwordx2 v[122:123], v[120:121], off
	s_cbranch_vccnz .LBB0_455
	global_store_dwordx4 v[182:183], v[0:3], off offset:576
	s_nop 1
.LBB0_455:
	s_nop 1
	v_lshlrev_b64 v[0:1], 10, v[180:181]
	ds_read_b64 v[122:123], v144 offset:8320
	v_lshl_add_u64 v[120:121], v[0:1], 0, v[128:129]
	s_nop 0
	s_nop 0
	s_and_b64 vcc, exec, s[2:3]
	s_waitcnt lgkmcnt(0)
	v_sub_f32_e32 v143, v179, v122
	v_sub_f32_e32 v142, v178, v122
	v_sub_f32_e32 v153, v177, v122
	v_sub_f32_e32 v152, v176, v122
	v_pk_mul_f32 v[152:153], v[122:123], v[152:153] op_sel:[1,0]
	v_pk_mul_f32 v[142:143], v[122:123], v[142:143] op_sel:[1,0]
	s_nop 0
	v_pk_fma_f32 v[0:1], v[212:213], v[152:153], v[228:229]
	v_pk_fma_f32 v[2:3], v[214:215], v[142:143], v[230:231]
	global_store_dwordx4 v[174:175], v[0:3], off
	v_cvt_pk_bf16_f32 v134, v0, v1
	v_cvt_pk_bf16_f32 v135, v2, v3
	v_lshl_add_u64 v[136:137], v[120:121], 1, s[64:65]
	global_store_dwordx2 v[136:137], v[134:135], off
	v_lshl_add_u64 v[134:135], v[120:121], 2, s[72:73]
	s_cbranch_vccnz .LBB0_457
	global_store_dwordx4 v[134:135], v[0:3], off
.LBB0_457:
	s_nop 0
	s_nop 0
	v_mov_b32_e32 v136, v123
	v_mov_b32_e32 v137, v123
	v_sub_f32_e32 v139, v139, v122
	v_sub_f32_e32 v138, v138, v122
	v_sub_f32_e32 v141, v141, v122
	v_sub_f32_e32 v140, v140, v122
	v_pk_mul_f32 v[142:143], v[136:137], v[138:139]
	v_mov_b32_e32 v138, v123
	v_mov_b32_e32 v139, v123
	v_pk_mul_f32 v[140:141], v[138:139], v[140:141]
	s_and_b64 vcc, exec, s[2:3]
	s_nop 0
	v_pk_fma_f32 v[2:3], v[140:141], v[218:219], v[234:235]
	v_or_b32_e32 v140, 16, v120
	v_mov_b32_e32 v141, v121
	v_pk_fma_f32 v[0:1], v[142:143], v[216:217], v[232:233]
	v_lshl_add_u64 v[142:143], v[140:141], 2, s[66:67]
	v_lshl_add_u64 v[140:141], v[140:141], 1, s[64:65]
	global_store_dwordx4 v[142:143], v[0:3], off
	v_cvt_pk_bf16_f32 v142, v0, v1
	v_cvt_pk_bf16_f32 v143, v2, v3
	global_store_dwordx2 v[140:141], v[142:143], off
	s_cbranch_vccnz .LBB0_459
	global_store_dwordx4 v[134:135], v[0:3], off offset:64
.LBB0_459:
	s_nop 0
	s_nop 0
	v_sub_f32_e32 v111, v111, v122
	v_sub_f32_e32 v110, v110, v122
	v_sub_f32_e32 v109, v109, v122
	v_sub_f32_e32 v108, v108, v122
	v_or_b32_e32 v152, 0x80, v120
	v_mov_b32_e32 v153, v121
	v_pk_mul_f32 v[108:109], v[136:137], v[108:109]
	v_pk_mul_f32 v[110:111], v[138:139], v[110:111]
	s_and_b64 vcc, exec, s[2:3]
	s_nop 0
	v_pk_fma_f32 v[2:3], v[110:111], v[222:223], v[244:245]
	v_pk_fma_f32 v[0:1], v[108:109], v[220:221], v[242:243]
	v_lshl_add_u64 v[108:109], v[152:153], 2, s[66:67]
	v_lshl_add_u64 v[110:111], v[152:153], 1, s[64:65]
	global_store_dwordx4 v[108:109], v[0:3], off
	v_cvt_pk_bf16_f32 v108, v0, v1
	v_cvt_pk_bf16_f32 v109, v2, v3
	global_store_dwordx2 v[110:111], v[108:109], off
	s_cbranch_vccnz .LBB0_461
	global_store_dwordx4 v[134:135], v[0:3], off offset:512
.LBB0_461:
	s_nop 0
	s_nop 0
	v_sub_f32_e32 v119, v119, v122
	v_sub_f32_e32 v118, v118, v122
	v_sub_f32_e32 v117, v117, v122
	v_sub_f32_e32 v116, v116, v122
	v_mov_b32_e32 v122, v123
	v_pk_mul_f32 v[116:117], v[136:137], v[116:117]
	v_pk_mul_f32 v[118:119], v[122:123], v[118:119]
	v_or_b32_e32 v120, 0x90, v120
	s_and_b64 vcc, exec, s[2:3]
	s_nop 0
	v_pk_fma_f32 v[2:3], v[118:119], v[226:227], v[248:249]
	v_pk_fma_f32 v[0:1], v[116:117], v[224:225], v[246:247]
	v_lshl_add_u64 v[108:109], v[120:121], 2, s[66:67]
	v_lshl_add_u64 v[110:111], v[120:121], 1, s[64:65]
	global_store_dwordx4 v[108:109], v[0:3], off
	v_cvt_pk_bf16_f32 v108, v0, v1
	v_cvt_pk_bf16_f32 v109, v2, v3
	global_store_dwordx2 v[110:111], v[108:109], off
	s_cbranch_vccnz .LBB0_463
	global_store_dwordx4 v[134:135], v[0:3], off offset:576
	s_nop 1
.LBB0_463:
	s_nop 1
	v_lshlrev_b64 v[0:1], 10, v[170:171]
	ds_read_b64 v[110:111], v144 offset:8448
	v_lshl_add_u64 v[108:109], v[0:1], 0, v[128:129]
	s_nop 0
	s_nop 0
	s_and_b64 vcc, exec, s[2:3]
	s_waitcnt lgkmcnt(0)
	v_sub_f32_e32 v121, v169, v110
	v_sub_f32_e32 v120, v168, v110
	v_sub_f32_e32 v123, v167, v110
	v_sub_f32_e32 v122, v166, v110
	v_pk_mul_f32 v[122:123], v[110:111], v[122:123] op_sel:[1,0]
	v_pk_mul_f32 v[120:121], v[110:111], v[120:121] op_sel:[1,0]
	s_nop 0
	v_pk_fma_f32 v[0:1], v[212:213], v[122:123], v[228:229]
	v_pk_fma_f32 v[2:3], v[214:215], v[120:121], v[230:231]
	global_store_dwordx4 v[164:165], v[0:3], off
	v_cvt_pk_bf16_f32 v116, v0, v1
	v_cvt_pk_bf16_f32 v117, v2, v3
	v_lshl_add_u64 v[118:119], v[108:109], 1, s[64:65]
	global_store_dwordx2 v[118:119], v[116:117], off
	v_lshl_add_u64 v[116:117], v[108:109], 2, s[72:73]
	s_cbranch_vccnz .LBB0_465
	global_store_dwordx4 v[116:117], v[0:3], off
.LBB0_465:
	s_nop 0
	s_nop 0
	v_mov_b32_e32 v118, v111
	v_mov_b32_e32 v119, v111
	v_sub_f32_e32 v113, v113, v110
	v_sub_f32_e32 v112, v112, v110
	v_sub_f32_e32 v115, v115, v110
	v_sub_f32_e32 v114, v114, v110
	v_pk_mul_f32 v[134:135], v[118:119], v[112:113]
	v_mov_b32_e32 v112, v111
	v_mov_b32_e32 v113, v111
	v_pk_mul_f32 v[114:115], v[112:113], v[114:115]
	s_and_b64 vcc, exec, s[2:3]
	s_nop 0
	v_pk_fma_f32 v[2:3], v[114:115], v[218:219], v[234:235]
	v_or_b32_e32 v114, 16, v108
	v_mov_b32_e32 v115, v109
	v_pk_fma_f32 v[0:1], v[134:135], v[216:217], v[232:233]
	v_lshl_add_u64 v[120:121], v[114:115], 2, s[66:67]
	v_lshl_add_u64 v[114:115], v[114:115], 1, s[64:65]
	global_store_dwordx4 v[120:121], v[0:3], off
	v_cvt_pk_bf16_f32 v120, v0, v1
	v_cvt_pk_bf16_f32 v121, v2, v3
	global_store_dwordx2 v[114:115], v[120:121], off
	s_cbranch_vccnz .LBB0_467
	global_store_dwordx4 v[116:117], v[0:3], off offset:64
.LBB0_467:
	s_nop 0
	s_nop 0
	v_sub_f32_e32 v87, v87, v110
	v_sub_f32_e32 v86, v86, v110
	v_sub_f32_e32 v85, v85, v110
	v_sub_f32_e32 v84, v84, v110
	v_or_b32_e32 v114, 0x80, v108
	v_mov_b32_e32 v115, v109
	v_pk_mul_f32 v[84:85], v[118:119], v[84:85]
	v_pk_mul_f32 v[86:87], v[112:113], v[86:87]
	s_and_b64 vcc, exec, s[2:3]
	s_nop 0
	v_pk_fma_f32 v[2:3], v[86:87], v[222:223], v[244:245]
	v_pk_fma_f32 v[0:1], v[84:85], v[220:221], v[242:243]
	v_lshl_add_u64 v[84:85], v[114:115], 2, s[66:67]
	v_lshl_add_u64 v[86:87], v[114:115], 1, s[64:65]
	global_store_dwordx4 v[84:85], v[0:3], off
	v_cvt_pk_bf16_f32 v84, v0, v1
	v_cvt_pk_bf16_f32 v85, v2, v3
	global_store_dwordx2 v[86:87], v[84:85], off
	s_cbranch_vccnz .LBB0_469
	global_store_dwordx4 v[116:117], v[0:3], off offset:512
.LBB0_469:
	s_nop 0
	s_nop 0
	v_sub_f32_e32 v95, v95, v110
	v_sub_f32_e32 v94, v94, v110
	v_sub_f32_e32 v93, v93, v110
	v_sub_f32_e32 v92, v92, v110
	v_mov_b32_e32 v110, v111
	v_pk_mul_f32 v[92:93], v[118:119], v[92:93]
	v_pk_mul_f32 v[94:95], v[110:111], v[94:95]
	v_or_b32_e32 v108, 0x90, v108
	s_and_b64 vcc, exec, s[2:3]
	s_nop 0
	v_pk_fma_f32 v[2:3], v[94:95], v[226:227], v[248:249]
	v_pk_fma_f32 v[0:1], v[92:93], v[224:225], v[246:247]
	v_lshl_add_u64 v[84:85], v[108:109], 2, s[66:67]
	v_lshl_add_u64 v[86:87], v[108:109], 1, s[64:65]
	global_store_dwordx4 v[84:85], v[0:3], off
	v_cvt_pk_bf16_f32 v84, v0, v1
	v_cvt_pk_bf16_f32 v85, v2, v3
	global_store_dwordx2 v[86:87], v[84:85], off
	s_cbranch_vccnz .LBB0_471
	global_store_dwordx4 v[116:117], v[0:3], off offset:576
	s_nop 1
.LBB0_471:
	s_nop 1
	v_lshlrev_b64 v[0:1], 10, v[132:133]
	ds_read_b64 v[86:87], v144 offset:8576
	v_lshl_add_u64 v[84:85], v[0:1], 0, v[128:129]
	s_nop 0
	s_nop 0
	s_and_b64 vcc, exec, s[2:3]
	s_waitcnt lgkmcnt(0)
	v_sub_f32_e32 v109, v131, v86
	v_sub_f32_e32 v108, v130, v86
	v_sub_f32_e32 v111, v127, v86
	v_sub_f32_e32 v110, v126, v86
	v_pk_mul_f32 v[110:111], v[86:87], v[110:111] op_sel:[1,0]
	v_pk_mul_f32 v[108:109], v[86:87], v[108:109] op_sel:[1,0]
	s_nop 0
	v_pk_fma_f32 v[0:1], v[212:213], v[110:111], v[228:229]
	v_pk_fma_f32 v[2:3], v[214:215], v[108:109], v[230:231]
	global_store_dwordx4 v[124:125], v[0:3], off
	v_cvt_pk_bf16_f32 v92, v0, v1
	v_cvt_pk_bf16_f32 v93, v2, v3
	v_lshl_add_u64 v[94:95], v[84:85], 1, s[64:65]
	global_store_dwordx2 v[94:95], v[92:93], off
	v_lshl_add_u64 v[92:93], v[84:85], 2, s[72:73]
	s_cbranch_vccnz .LBB0_473
	global_store_dwordx4 v[92:93], v[0:3], off
.LBB0_473:
	s_nop 0
	s_nop 0
	v_mov_b32_e32 v94, v87
	v_mov_b32_e32 v95, v87
	v_sub_f32_e32 v89, v89, v86
	v_sub_f32_e32 v88, v88, v86
	v_sub_f32_e32 v91, v91, v86
	v_sub_f32_e32 v90, v90, v86
	v_pk_mul_f32 v[112:113], v[94:95], v[88:89]
	v_mov_b32_e32 v88, v87
	v_mov_b32_e32 v89, v87
	v_pk_mul_f32 v[90:91], v[88:89], v[90:91]
	s_and_b64 vcc, exec, s[2:3]
	s_nop 0
	v_pk_fma_f32 v[2:3], v[90:91], v[218:219], v[234:235]
	v_or_b32_e32 v90, 16, v84
	v_mov_b32_e32 v91, v85
	v_pk_fma_f32 v[0:1], v[112:113], v[216:217], v[232:233]
	v_lshl_add_u64 v[108:109], v[90:91], 2, s[66:67]
	v_lshl_add_u64 v[90:91], v[90:91], 1, s[64:65]
	global_store_dwordx4 v[108:109], v[0:3], off
	v_cvt_pk_bf16_f32 v108, v0, v1
	v_cvt_pk_bf16_f32 v109, v2, v3
	global_store_dwordx2 v[90:91], v[108:109], off
	s_cbranch_vccnz .LBB0_475
	global_store_dwordx4 v[92:93], v[0:3], off offset:64
.LBB0_475:
	s_nop 0
	s_nop 0
	v_sub_f32_e32 v71, v71, v86
	v_sub_f32_e32 v70, v70, v86
	v_sub_f32_e32 v69, v69, v86
	v_sub_f32_e32 v68, v68, v86
	v_or_b32_e32 v90, 0x80, v84
	v_mov_b32_e32 v91, v85
	v_pk_mul_f32 v[68:69], v[94:95], v[68:69]
	v_pk_mul_f32 v[70:71], v[88:89], v[70:71]
	s_and_b64 vcc, exec, s[2:3]
	s_nop 0
	v_pk_fma_f32 v[2:3], v[70:71], v[222:223], v[244:245]
	v_pk_fma_f32 v[0:1], v[68:69], v[220:221], v[242:243]
	v_lshl_add_u64 v[68:69], v[90:91], 2, s[66:67]
	v_lshl_add_u64 v[70:71], v[90:91], 1, s[64:65]
	global_store_dwordx4 v[68:69], v[0:3], off
	v_cvt_pk_bf16_f32 v68, v0, v1
	v_cvt_pk_bf16_f32 v69, v2, v3
	global_store_dwordx2 v[70:71], v[68:69], off
	s_cbranch_vccnz .LBB0_477
	global_store_dwordx4 v[92:93], v[0:3], off offset:512
.LBB0_477:
	s_nop 0
	s_nop 0
	v_sub_f32_e32 v75, v75, v86
	v_sub_f32_e32 v74, v74, v86
	v_sub_f32_e32 v73, v73, v86
	v_sub_f32_e32 v72, v72, v86
	v_mov_b32_e32 v86, v87
	v_pk_mul_f32 v[72:73], v[94:95], v[72:73]
	v_pk_mul_f32 v[74:75], v[86:87], v[74:75]
	v_or_b32_e32 v84, 0x90, v84
	s_and_b64 vcc, exec, s[2:3]
	s_nop 0
	v_pk_fma_f32 v[2:3], v[74:75], v[226:227], v[248:249]
	v_pk_fma_f32 v[0:1], v[72:73], v[224:225], v[246:247]
	v_lshl_add_u64 v[68:69], v[84:85], 2, s[66:67]
	v_lshl_add_u64 v[70:71], v[84:85], 1, s[64:65]
	global_store_dwordx4 v[68:69], v[0:3], off
	v_cvt_pk_bf16_f32 v68, v0, v1
	v_cvt_pk_bf16_f32 v69, v2, v3
	global_store_dwordx2 v[70:71], v[68:69], off
	s_cbranch_vccnz .LBB0_479
	global_store_dwordx4 v[92:93], v[0:3], off offset:576
	s_nop 1
.LBB0_479:
	s_nop 1
	v_lshlrev_b64 v[0:1], 10, v[102:103]
	ds_read_b64 v[70:71], v144 offset:9216
	v_lshl_add_u64 v[68:69], v[0:1], 0, v[128:129]
	s_nop 0
	s_nop 0
	s_and_b64 vcc, exec, s[2:3]
	s_waitcnt lgkmcnt(0)
	v_sub_f32_e32 v85, v101, v70
	v_sub_f32_e32 v84, v100, v70
	v_sub_f32_e32 v87, v99, v70
	v_sub_f32_e32 v86, v98, v70
	v_pk_mul_f32 v[86:87], v[70:71], v[86:87] op_sel:[1,0]
	v_pk_mul_f32 v[84:85], v[70:71], v[84:85] op_sel:[1,0]
	s_nop 0
	v_pk_fma_f32 v[0:1], v[212:213], v[86:87], v[228:229]
	v_pk_fma_f32 v[2:3], v[214:215], v[84:85], v[230:231]
	global_store_dwordx4 v[96:97], v[0:3], off
	v_cvt_pk_bf16_f32 v72, v0, v1
	v_cvt_pk_bf16_f32 v73, v2, v3
	v_lshl_add_u64 v[74:75], v[68:69], 1, s[64:65]
	global_store_dwordx2 v[74:75], v[72:73], off
	v_lshl_add_u64 v[72:73], v[68:69], 2, s[72:73]
	s_cbranch_vccnz .LBB0_481
	global_store_dwordx4 v[72:73], v[0:3], off
.LBB0_481:
	s_nop 0
	s_nop 0
	v_mov_b32_e32 v74, v71
	v_mov_b32_e32 v75, v71
	v_sub_f32_e32 v65, v65, v70
	v_sub_f32_e32 v64, v64, v70
	v_sub_f32_e32 v67, v67, v70
	v_sub_f32_e32 v66, v66, v70
	v_pk_mul_f32 v[88:89], v[74:75], v[64:65]
	v_mov_b32_e32 v64, v71
	v_mov_b32_e32 v65, v71
	v_pk_mul_f32 v[66:67], v[64:65], v[66:67]
	s_and_b64 vcc, exec, s[2:3]
	s_nop 0
	v_pk_fma_f32 v[2:3], v[66:67], v[218:219], v[234:235]
	v_or_b32_e32 v66, 16, v68
	v_mov_b32_e32 v67, v69
	v_pk_fma_f32 v[0:1], v[88:89], v[216:217], v[232:233]
	v_lshl_add_u64 v[84:85], v[66:67], 2, s[66:67]
	v_lshl_add_u64 v[66:67], v[66:67], 1, s[64:65]
	global_store_dwordx4 v[84:85], v[0:3], off
	v_cvt_pk_bf16_f32 v84, v0, v1
	v_cvt_pk_bf16_f32 v85, v2, v3
	global_store_dwordx2 v[66:67], v[84:85], off
	s_cbranch_vccnz .LBB0_483
	global_store_dwordx4 v[72:73], v[0:3], off offset:64
.LBB0_483:
	s_nop 0
	s_nop 0
	v_sub_f32_e32 v55, v55, v70
	v_sub_f32_e32 v54, v54, v70
	v_sub_f32_e32 v53, v53, v70
	v_sub_f32_e32 v52, v52, v70
	v_or_b32_e32 v66, 0x80, v68
	v_mov_b32_e32 v67, v69
	v_pk_mul_f32 v[52:53], v[74:75], v[52:53]
	v_pk_mul_f32 v[54:55], v[64:65], v[54:55]
	s_and_b64 vcc, exec, s[2:3]
	s_nop 0
	v_pk_fma_f32 v[2:3], v[54:55], v[222:223], v[244:245]
	v_pk_fma_f32 v[0:1], v[52:53], v[220:221], v[242:243]
	v_lshl_add_u64 v[52:53], v[66:67], 2, s[66:67]
	v_lshl_add_u64 v[54:55], v[66:67], 1, s[64:65]
	global_store_dwordx4 v[52:53], v[0:3], off
	v_cvt_pk_bf16_f32 v52, v0, v1
	v_cvt_pk_bf16_f32 v53, v2, v3
	global_store_dwordx2 v[54:55], v[52:53], off
	s_cbranch_vccnz .LBB0_485
	global_store_dwordx4 v[72:73], v[0:3], off offset:512
.LBB0_485:
	s_nop 0
	s_nop 0
	v_sub_f32_e32 v51, v51, v70
	v_sub_f32_e32 v50, v50, v70
	v_sub_f32_e32 v49, v49, v70
	v_sub_f32_e32 v48, v48, v70
	v_mov_b32_e32 v70, v71
	v_pk_mul_f32 v[48:49], v[74:75], v[48:49]
	v_pk_mul_f32 v[50:51], v[70:71], v[50:51]
	v_or_b32_e32 v68, 0x90, v68
	s_and_b64 vcc, exec, s[2:3]
	s_nop 0
	v_pk_fma_f32 v[2:3], v[50:51], v[226:227], v[248:249]
	v_pk_fma_f32 v[0:1], v[48:49], v[224:225], v[246:247]
	v_lshl_add_u64 v[48:49], v[68:69], 2, s[66:67]
	v_lshl_add_u64 v[50:51], v[68:69], 1, s[64:65]
	global_store_dwordx4 v[48:49], v[0:3], off
	v_cvt_pk_bf16_f32 v48, v0, v1
	v_cvt_pk_bf16_f32 v49, v2, v3
	global_store_dwordx2 v[50:51], v[48:49], off
	s_cbranch_vccnz .LBB0_487
	global_store_dwordx4 v[72:73], v[0:3], off offset:576
	s_nop 1
.LBB0_487:
	s_nop 1
	v_lshlrev_b64 v[0:1], 10, v[82:83]
	ds_read_b64 v[50:51], v144 offset:9344
	v_lshl_add_u64 v[48:49], v[0:1], 0, v[128:129]
	s_nop 0
	s_nop 0
	s_and_b64 vcc, exec, s[2:3]
	s_waitcnt lgkmcnt(0)
	v_sub_f32_e32 v65, v81, v50
	v_sub_f32_e32 v64, v80, v50
	v_sub_f32_e32 v67, v79, v50
	v_sub_f32_e32 v66, v78, v50
	v_pk_mul_f32 v[66:67], v[50:51], v[66:67] op_sel:[1,0]
	v_pk_mul_f32 v[64:65], v[50:51], v[64:65] op_sel:[1,0]
	s_nop 0
	v_pk_fma_f32 v[0:1], v[212:213], v[66:67], v[228:229]
	v_pk_fma_f32 v[2:3], v[214:215], v[64:65], v[230:231]
	global_store_dwordx4 v[76:77], v[0:3], off
	v_cvt_pk_bf16_f32 v52, v0, v1
	v_cvt_pk_bf16_f32 v53, v2, v3
	v_lshl_add_u64 v[54:55], v[48:49], 1, s[64:65]
	global_store_dwordx2 v[54:55], v[52:53], off
	v_lshl_add_u64 v[52:53], v[48:49], 2, s[72:73]
	s_cbranch_vccnz .LBB0_489
	global_store_dwordx4 v[52:53], v[0:3], off
.LBB0_489:
	s_nop 0
	s_nop 0
	v_mov_b32_e32 v54, v51
	v_mov_b32_e32 v55, v51
	v_sub_f32_e32 v45, v45, v50
	v_sub_f32_e32 v44, v44, v50
	v_sub_f32_e32 v47, v47, v50
	v_sub_f32_e32 v46, v46, v50
	v_pk_mul_f32 v[68:69], v[54:55], v[44:45]
	v_mov_b32_e32 v44, v51
	v_mov_b32_e32 v45, v51
	v_pk_mul_f32 v[46:47], v[44:45], v[46:47]
	s_and_b64 vcc, exec, s[2:3]
	s_nop 0
	v_pk_fma_f32 v[2:3], v[46:47], v[218:219], v[234:235]
	v_or_b32_e32 v46, 16, v48
	v_mov_b32_e32 v47, v49
	v_pk_fma_f32 v[0:1], v[68:69], v[216:217], v[232:233]
	v_lshl_add_u64 v[64:65], v[46:47], 2, s[66:67]
	v_lshl_add_u64 v[46:47], v[46:47], 1, s[64:65]
	global_store_dwordx4 v[64:65], v[0:3], off
	v_cvt_pk_bf16_f32 v64, v0, v1
	v_cvt_pk_bf16_f32 v65, v2, v3
	global_store_dwordx2 v[46:47], v[64:65], off
	s_cbranch_vccnz .LBB0_491
	global_store_dwordx4 v[52:53], v[0:3], off offset:64
.LBB0_491:
	s_nop 0
	s_nop 0
	v_sub_f32_e32 v39, v39, v50
	v_sub_f32_e32 v38, v38, v50
	v_sub_f32_e32 v37, v37, v50
	v_sub_f32_e32 v36, v36, v50
	v_or_b32_e32 v46, 0x80, v48
	v_mov_b32_e32 v47, v49
	v_pk_mul_f32 v[36:37], v[54:55], v[36:37]
	v_pk_mul_f32 v[38:39], v[44:45], v[38:39]
	s_and_b64 vcc, exec, s[2:3]
	s_nop 0
	v_pk_fma_f32 v[2:3], v[38:39], v[222:223], v[244:245]
	v_pk_fma_f32 v[0:1], v[36:37], v[220:221], v[242:243]
	v_lshl_add_u64 v[36:37], v[46:47], 2, s[66:67]
	v_lshl_add_u64 v[38:39], v[46:47], 1, s[64:65]
	global_store_dwordx4 v[36:37], v[0:3], off
	v_cvt_pk_bf16_f32 v36, v0, v1
	v_cvt_pk_bf16_f32 v37, v2, v3
	global_store_dwordx2 v[38:39], v[36:37], off
	s_cbranch_vccnz .LBB0_493
	global_store_dwordx4 v[52:53], v[0:3], off offset:512
.LBB0_493:
	s_nop 0
	s_nop 0
	v_sub_f32_e32 v35, v35, v50
	v_sub_f32_e32 v34, v34, v50
	v_sub_f32_e32 v33, v33, v50
	v_sub_f32_e32 v32, v32, v50
	v_mov_b32_e32 v50, v51
	v_pk_mul_f32 v[32:33], v[54:55], v[32:33]
	v_pk_mul_f32 v[34:35], v[50:51], v[34:35]
	v_or_b32_e32 v48, 0x90, v48
	s_and_b64 vcc, exec, s[2:3]
	s_nop 0
	v_pk_fma_f32 v[2:3], v[34:35], v[226:227], v[248:249]
	v_pk_fma_f32 v[0:1], v[32:33], v[224:225], v[246:247]
	v_lshl_add_u64 v[32:33], v[48:49], 2, s[66:67]
	v_lshl_add_u64 v[34:35], v[48:49], 1, s[64:65]
	global_store_dwordx4 v[32:33], v[0:3], off
	v_cvt_pk_bf16_f32 v32, v0, v1
	v_cvt_pk_bf16_f32 v33, v2, v3
	global_store_dwordx2 v[34:35], v[32:33], off
	s_cbranch_vccnz .LBB0_495
	global_store_dwordx4 v[52:53], v[0:3], off offset:576
	s_nop 1
.LBB0_495:
	s_nop 1
	v_lshlrev_b64 v[0:1], 10, v[62:63]
	ds_read_b64 v[34:35], v144 offset:9472
	v_lshl_add_u64 v[32:33], v[0:1], 0, v[128:129]
	s_nop 0
	s_nop 0
	s_and_b64 vcc, exec, s[2:3]
	s_waitcnt lgkmcnt(0)
	v_sub_f32_e32 v45, v61, v34
	v_sub_f32_e32 v44, v60, v34
	v_sub_f32_e32 v47, v59, v34
	v_sub_f32_e32 v46, v58, v34
	v_pk_mul_f32 v[46:47], v[34:35], v[46:47] op_sel:[1,0]
	v_pk_mul_f32 v[44:45], v[34:35], v[44:45] op_sel:[1,0]
	s_nop 0
	v_pk_fma_f32 v[0:1], v[212:213], v[46:47], v[228:229]
	v_pk_fma_f32 v[2:3], v[214:215], v[44:45], v[230:231]
	global_store_dwordx4 v[56:57], v[0:3], off
	v_cvt_pk_bf16_f32 v36, v0, v1
	v_cvt_pk_bf16_f32 v37, v2, v3
	v_lshl_add_u64 v[38:39], v[32:33], 1, s[64:65]
	global_store_dwordx2 v[38:39], v[36:37], off
	v_lshl_add_u64 v[36:37], v[32:33], 2, s[72:73]
	s_cbranch_vccnz .LBB0_497
	global_store_dwordx4 v[36:37], v[0:3], off
.LBB0_497:
	s_nop 0
	s_nop 0
	v_mov_b32_e32 v38, v35
	v_mov_b32_e32 v39, v35
	v_sub_f32_e32 v25, v25, v34
	v_sub_f32_e32 v24, v24, v34
	v_sub_f32_e32 v27, v27, v34
	v_sub_f32_e32 v26, v26, v34
	v_pk_mul_f32 v[48:49], v[38:39], v[24:25]
	v_mov_b32_e32 v24, v35
	v_mov_b32_e32 v25, v35
	v_pk_mul_f32 v[26:27], v[24:25], v[26:27]
	s_and_b64 vcc, exec, s[2:3]
	s_nop 0
	v_pk_fma_f32 v[2:3], v[26:27], v[218:219], v[234:235]
	v_or_b32_e32 v26, 16, v32
	v_mov_b32_e32 v27, v33
	v_pk_fma_f32 v[0:1], v[48:49], v[216:217], v[232:233]
	v_lshl_add_u64 v[44:45], v[26:27], 2, s[66:67]
	v_lshl_add_u64 v[26:27], v[26:27], 1, s[64:65]
	global_store_dwordx4 v[44:45], v[0:3], off
	v_cvt_pk_bf16_f32 v44, v0, v1
	v_cvt_pk_bf16_f32 v45, v2, v3
	global_store_dwordx2 v[26:27], v[44:45], off
	s_cbranch_vccnz .LBB0_499
	global_store_dwordx4 v[36:37], v[0:3], off offset:64
.LBB0_499:
	s_nop 0
	s_nop 0
	v_sub_f32_e32 v23, v23, v34
	v_sub_f32_e32 v22, v22, v34
	v_sub_f32_e32 v21, v21, v34
	v_sub_f32_e32 v20, v20, v34
	v_or_b32_e32 v26, 0x80, v32
	v_mov_b32_e32 v27, v33
	v_pk_mul_f32 v[20:21], v[38:39], v[20:21]
	v_pk_mul_f32 v[22:23], v[24:25], v[22:23]
	s_and_b64 vcc, exec, s[2:3]
	s_nop 0
	v_pk_fma_f32 v[2:3], v[22:23], v[222:223], v[244:245]
	v_pk_fma_f32 v[0:1], v[20:21], v[220:221], v[242:243]
	v_lshl_add_u64 v[20:21], v[26:27], 2, s[66:67]
	v_lshl_add_u64 v[22:23], v[26:27], 1, s[64:65]
	global_store_dwordx4 v[20:21], v[0:3], off
	v_cvt_pk_bf16_f32 v20, v0, v1
	v_cvt_pk_bf16_f32 v21, v2, v3
	global_store_dwordx2 v[22:23], v[20:21], off
	s_cbranch_vccnz .LBB0_501
	global_store_dwordx4 v[36:37], v[0:3], off offset:512
.LBB0_501:
	s_nop 0
	s_nop 0
	v_sub_f32_e32 v19, v19, v34
	v_sub_f32_e32 v18, v18, v34
	v_sub_f32_e32 v17, v17, v34
	v_sub_f32_e32 v16, v16, v34
	v_mov_b32_e32 v34, v35
	v_pk_mul_f32 v[16:17], v[38:39], v[16:17]
	v_pk_mul_f32 v[18:19], v[34:35], v[18:19]
	v_or_b32_e32 v32, 0x90, v32
	s_and_b64 vcc, exec, s[2:3]
	s_nop 0
	v_pk_fma_f32 v[2:3], v[18:19], v[226:227], v[248:249]
	v_pk_fma_f32 v[0:1], v[16:17], v[224:225], v[246:247]
	v_lshl_add_u64 v[16:17], v[32:33], 2, s[66:67]
	v_lshl_add_u64 v[18:19], v[32:33], 1, s[64:65]
	global_store_dwordx4 v[16:17], v[0:3], off
	v_cvt_pk_bf16_f32 v16, v0, v1
	v_cvt_pk_bf16_f32 v17, v2, v3
	global_store_dwordx2 v[18:19], v[16:17], off
	s_cbranch_vccnz .LBB0_503
	global_store_dwordx4 v[36:37], v[0:3], off offset:576
	s_nop 1
.LBB0_503:
	s_nop 1
	v_lshlrev_b64 v[0:1], 10, v[42:43]
	ds_read_b64 v[18:19], v144 offset:9600
	v_lshl_add_u64 v[16:17], v[0:1], 0, v[128:129]
	s_nop 0
	s_nop 0
	s_and_b64 vcc, exec, s[2:3]
	s_waitcnt lgkmcnt(0)
	v_sub_f32_e32 v25, v41, v18
	v_sub_f32_e32 v24, v40, v18
	v_sub_f32_e32 v27, v31, v18
	v_sub_f32_e32 v26, v30, v18
	v_pk_mul_f32 v[26:27], v[18:19], v[26:27] op_sel:[1,0]
	v_pk_mul_f32 v[24:25], v[18:19], v[24:25] op_sel:[1,0]
	s_nop 0
	v_pk_fma_f32 v[0:1], v[212:213], v[26:27], v[228:229]
	v_pk_fma_f32 v[2:3], v[214:215], v[24:25], v[230:231]
	global_store_dwordx4 v[28:29], v[0:3], off
	v_cvt_pk_bf16_f32 v20, v0, v1
	v_cvt_pk_bf16_f32 v21, v2, v3
	v_lshl_add_u64 v[22:23], v[16:17], 1, s[64:65]
	global_store_dwordx2 v[22:23], v[20:21], off
	v_lshl_add_u64 v[20:21], v[16:17], 2, s[72:73]
	s_cbranch_vccnz .LBB0_505
	global_store_dwordx4 v[20:21], v[0:3], off
.LBB0_505:
	s_nop 0
	s_nop 0
	v_mov_b32_e32 v22, v19
	v_mov_b32_e32 v23, v19
	v_sub_f32_e32 v13, v13, v18
	v_sub_f32_e32 v12, v12, v18
	v_sub_f32_e32 v15, v15, v18
	v_sub_f32_e32 v14, v14, v18
	v_pk_mul_f32 v[28:29], v[22:23], v[12:13]
	v_mov_b32_e32 v12, v19
	v_mov_b32_e32 v13, v19
	v_pk_mul_f32 v[14:15], v[12:13], v[14:15]
	s_and_b64 vcc, exec, s[2:3]
	s_nop 0
	v_pk_fma_f32 v[2:3], v[14:15], v[218:219], v[234:235]
	v_or_b32_e32 v14, 16, v16
	v_mov_b32_e32 v15, v17
	v_pk_fma_f32 v[0:1], v[28:29], v[216:217], v[232:233]
	v_lshl_add_u64 v[24:25], v[14:15], 2, s[66:67]
	v_lshl_add_u64 v[14:15], v[14:15], 1, s[64:65]
	global_store_dwordx4 v[24:25], v[0:3], off
	v_cvt_pk_bf16_f32 v24, v0, v1
	v_cvt_pk_bf16_f32 v25, v2, v3
	global_store_dwordx2 v[14:15], v[24:25], off
	s_cbranch_vccnz .LBB0_507
	global_store_dwordx4 v[20:21], v[0:3], off offset:64
.LBB0_507:
	s_nop 0
	s_nop 0
	v_sub_f32_e32 v7, v7, v18
	v_sub_f32_e32 v6, v6, v18
	v_sub_f32_e32 v5, v5, v18
	v_sub_f32_e32 v4, v4, v18
	v_or_b32_e32 v14, 0x80, v16
	v_mov_b32_e32 v15, v17
	v_pk_mul_f32 v[4:5], v[22:23], v[4:5]
	v_pk_mul_f32 v[6:7], v[12:13], v[6:7]
	s_and_b64 vcc, exec, s[2:3]
	s_nop 0
	v_pk_fma_f32 v[2:3], v[6:7], v[222:223], v[244:245]
	v_pk_fma_f32 v[0:1], v[4:5], v[220:221], v[242:243]
	v_lshl_add_u64 v[4:5], v[14:15], 2, s[66:67]
	v_lshl_add_u64 v[6:7], v[14:15], 1, s[64:65]
	global_store_dwordx4 v[4:5], v[0:3], off
	v_cvt_pk_bf16_f32 v4, v0, v1
	v_cvt_pk_bf16_f32 v5, v2, v3
	global_store_dwordx2 v[6:7], v[4:5], off
	s_cbranch_vccnz .LBB0_509
	global_store_dwordx4 v[20:21], v[0:3], off offset:512
.LBB0_509:
	s_nop 0
	s_nop 0
	v_sub_f32_e32 v11, v11, v18
	v_sub_f32_e32 v10, v10, v18
	v_sub_f32_e32 v9, v9, v18
	v_sub_f32_e32 v8, v8, v18
	v_mov_b32_e32 v18, v19
	v_or_b32_e32 v16, 0x90, v16
	v_pk_mul_f32 v[8:9], v[22:23], v[8:9]
	v_pk_mul_f32 v[10:11], v[18:19], v[10:11]
	v_lshl_add_u64 v[12:13], v[16:17], 2, s[66:67]
	v_lshl_add_u64 v[14:15], v[16:17], 1, s[64:65]
	s_and_b64 vcc, exec, s[2:3]
	s_nop 0
	v_pk_fma_f32 v[2:3], v[10:11], v[226:227], v[248:249]
	v_pk_fma_f32 v[0:1], v[8:9], v[224:225], v[246:247]
	global_store_dwordx4 v[12:13], v[0:3], off
	v_cvt_pk_bf16_f32 v4, v0, v1
	v_cvt_pk_bf16_f32 v5, v2, v3
	global_store_dwordx2 v[14:15], v[4:5], off
	s_cbranch_vccnz .LBB0_511
	global_store_dwordx4 v[20:21], v[0:3], off offset:576
